# attention tile loop: loads for tile i+2 issued right after tile i+1 is staged inside the tile compute (prefetch distance 1.5 tiles, no load-issue code between barrier and first MFMA)
# speedup vs baseline: 1.0029x; 1.0029x over previous
; #define LAS __attribute__((address_space(3)))
; __device__ __forceinline__ void phase4_attn(const Args& a, LAS unsigned char* lds) {
;     ...
;                 const int kt_lo = t >= 8 ? t - 8 : 0, wlo = kt_lo >> 1, n_sel = (t >> 1) + 1, n_all = n_sel + ((t >> 1) - wlo + 1);
;                 const bf16_t* Ks = ksl + (size_t)bh * 2048 * 64; const bf16_t* Vs = vslT + (size_t)bh * 64 * 2048;
;                 const bf16_t* Kw = kwn + (size_t)bh * 2048 * 64; const bf16_t* Vw = vwnT + (size_t)bh * 64 * 2048;
;     ...
;                 u32x4 kR0, kR1, vR0, vR1;
;                 A_ISSUE(0);
;                 A_STAGE(0);
;                 __syncthreads();
;                 f32x16 oacc[2]; oacc[0] = zero16(); oacc[1] = zero16();
;                 float l_run = 0.f;
; #pragma unroll 1
;                 for (int i = 0; i < n_all; ++i) {
;                     const int bufo = i & 1;
;                     if (i + 1 < n_all) A_ISSUE(i + 1);
;                     const LAS unsigned char* Kb = lds + A_KBUF + bufo * A_KT; const LAS unsigned char* Vb = lds + A_VBUF + bufo * A_VT;
;                     const bool issel = i < n_sel;
;                     const int st = issel ? i : wlo + (i - n_sel);
;                     const int dlt = 64 * t + ql - 128 * st - 4 * h;
.LBB0_727:
	v_add_u32_e32 v244, v118, v153
	v_add_u32_e32 v245, v156, v157
	v_add_u32_e32 v245, 0x9000, v245
	v_ashrrev_i32_e32 v239, 3, v152
	v_lshlrev_b32_e32 v240, 4, v152
	v_and_b32_e32 v240, 0x70, v240
	v_mul_u32_u24_e32 v246, 0x90, v239
	v_add_u32_e32 v246, v246, v240
	v_mul_u32_u24_e32 v247, 0x108, v239
	v_add_u32_e32 v247, v247, v240
	v_add_u32_e32 v247, 0x9000, v247
	v_lshlrev_b32_e32 v248, 4, v152
	v_add_u32_e32 v249, 0x2000, v248
	v_and_b32_e32 v250, 31, v152
	v_sub_u32_e32 v250, v250, v155
	v_readfirstlane_b32 s50, v152
	s_bfe_u32 s50, s50, 0x10006
	s_lshl_b32 s0, s38, 1
	s_add_i32 s50, s50, s0
	s_add_i32 s6, s44, 1
	s_add_i32 s7, s91, s44
	s_add_i32 s0, s44, 0
	s_cmp_lt_i32 s0, s90
	s_cbranch_scc0 .Lt1_pre_noissue
	s_cmp_lt_u32 s0, s89
	s_cselect_b32 s0, s71, s75
	s_cselect_b32 s1, s72, s76
	s_cselect_b32 s4, s73, s77
	s_cselect_b32 s5, s74, s78
	s_cselect_b32 s6, s6, s7
	s_ashr_i32 s7, s6, 31
	s_lshl_b64 s[6:7], s[6:7], 14
	s_add_u32 s6, s6, s58
	s_addc_u32 s7, s7, s59
	s_add_u32 s0, s0, s6
	s_addc_u32 s1, s1, s7
	s_add_u32 s4, s4, s6
	s_addc_u32 s5, s5, s7
	global_load_dwordx4 v[96:99], v248, s[0:1]
	global_load_dwordx4 v[100:103], v249, s[0:1]
	global_load_dwordx4 v[104:107], v248, s[4:5]
	global_load_dwordx4 v[108:111], v249, s[4:5]
.Lt1_pre_noissue:
.Lt1_head:
	s_cmp_lt_i32 s44, s90
	s_cselect_b32 s45, 1, 0
	s_branch .Lt1_noissue
	s_add_i32 s6, s44, 1
	s_add_i32 s7, s91, s44
	s_cmp_lt_i32 s44, s90
	s_cselect_b32 s45, 1, 0
	s_cbranch_scc0 .Lt1_noissue
	s_cmp_lt_u32 s44, s89
	s_cselect_b32 s0, s71, s75
	s_cselect_b32 s1, s72, s76
	s_cselect_b32 s4, s73, s77
	s_cselect_b32 s5, s74, s78
	s_cselect_b32 s6, s6, s7
	s_ashr_i32 s7, s6, 31
	s_lshl_b64 s[6:7], s[6:7], 14
	s_add_u32 s6, s6, s58
	s_addc_u32 s7, s7, s59
	s_add_u32 s0, s0, s6
	s_addc_u32 s1, s1, s7
	s_add_u32 s4, s4, s6
	s_addc_u32 s5, s5, s7
	global_load_dwordx4 v[96:99], v248, s[0:1]
	global_load_dwordx4 v[100:103], v249, s[0:1]
	global_load_dwordx4 v[104:107], v248, s[4:5]
	global_load_dwordx4 v[108:111], v249, s[4:5]

; #define LAS __attribute__((address_space(3)))
; #define MFMA32(a, b, c) __builtin_amdgcn_mfma_f32_32x32x16_bf16((a), (b), (c), 0, 0, 0)
; __device__ __forceinline__ float ex2(float x) { return __builtin_amdgcn_exp2f(x); }
; template <int MODE>
; __device__ __forceinline__ void attn_tile(const LAS unsigned char* Kb, const LAS unsigned char* Vb, const bf16x8_t (&qf)[4], f32x16 (&oacc)[2], float& l_run,
;                                           int r, int h, int dlt0, int dlt1, bool hiw) {
;     ...
; #pragma unroll
;     for (int mt = 0; mt < 4; ++mt) {
;         if (mt == 0) { if (hiw) __builtin_amdgcn_s_setprio(1); else __builtin_amdgcn_s_setprio(0); }
;         if (mt == 2) { if (hiw) __builtin_amdgcn_s_setprio(0); else __builtin_amdgcn_s_setprio(1); }
;         const int dl = mt < 2 ? dlt0 : dlt1;
;         f32x16 sacc = zero16();
; #pragma unroll
;         for (int ks = 0; ks < 4; ++ks) { const bf16x8_t ka = *(const LAS bf16x8_t*)(Kb + (32 * mt + r) * A_KSTR + 32 * ks + 16 * h); sacc = MFMA32(ka, qf[ks], sacc); }
; #pragma unroll
;         for (int i = 0; i < 16; ++i) {
;             float p;
;             if (MODE == 2) p = ex2(sacc[i]);
;             else if (MODE == 3) p = ex2(sacc[i] + __int_as_float(dl));
;             else { const int ci = 32 * mt + (i & 3) + 8 * (i >> 2); p = ((unsigned)(dl - ci) < ulim) ? ex2(sacc[i]) : 0.f; }
;             sacc[i] = p; ls += p;
;         }
; #pragma unroll
;         for (int s = 0; s < 2; ++s) {
;             const bf16x8_t pf = pack8(sacc, 8 * s);
; #pragma unroll
;             for (int dt = 0; dt < 2; ++dt) {
;                 const LAS unsigned char* vp = Vb + (32 * dt + r) * A_CVSTR + (32 * mt + 16 * s + 4 * h) * 2;
;                 const s16x4_t lo = *(const LAS s16x4_t*)vp, hi = *(const LAS s16x4_t*)(vp + 16);
;                 oacc[dt] = MFMA32(__builtin_shufflevector(lo, hi, 0, 1, 2, 3, 4, 5, 6, 7), pf, oacc[dt]);
;             }
;         }
;     }
;     l_run += ls;
.Lt1_full:
	ds_read_b128 v[200:203], v72 offset:0
	ds_read_b128 v[204:207], v72 offset:32
	ds_read_b128 v[208:211], v72 offset:64
	ds_read_b128 v[212:215], v72 offset:96
	ds_read2_b64 v[216:219], v73 offset0:0 offset1:2
	ds_read2_b64 v[220:223], v74 offset0:32 offset1:34
	ds_read2_b64 v[224:227], v73 offset0:4 offset1:6
	ds_read2_b64 v[228:231], v74 offset0:36 offset1:38
	s_waitcnt lgkmcnt(7)
	v_mfma_f32_32x32x16_bf16 v[32:47], v[200:203], v[80:83], 0
	ds_read_b128 v[200:203], v72 offset:4608
	s_waitcnt lgkmcnt(7)
	v_mfma_f32_32x32x16_bf16 v[32:47], v[204:207], v[84:87], v[32:47]
	ds_read_b128 v[204:207], v72 offset:4640
	s_waitcnt lgkmcnt(7)
	v_mfma_f32_32x32x16_bf16 v[32:47], v[208:211], v[88:91], v[32:47]
	ds_read_b128 v[208:211], v72 offset:4672
	s_waitcnt lgkmcnt(7)
	v_mfma_f32_32x32x16_bf16 v[32:47], v[212:215], v[92:95], v[32:47]
	ds_read_b128 v[212:215], v72 offset:4704
	s_nop 7
	s_nop 3
	s_waitcnt lgkmcnt(3)
	v_mfma_f32_32x32x16_bf16 v[48:63], v[200:203], v[80:83], 0
	ds_read_b128 v[200:203], v72 offset:9216
	v_exp_f32_e32 v32, v32
	v_exp_f32_e32 v33, v33
	s_waitcnt lgkmcnt(3)
	v_mfma_f32_32x32x16_bf16 v[48:63], v[204:207], v[84:87], v[48:63]
	ds_read_b128 v[204:207], v72 offset:9248
	v_exp_f32_e32 v34, v34
	v_exp_f32_e32 v35, v35
	v_mov_b32_e32 v232, v32
	v_mov_b32_e32 v233, v33
	v_cvt_pk_bf16_f32 v64, v32, v33
	v_exp_f32_e32 v36, v36
	v_exp_f32_e32 v37, v37
	v_add_f32_e32 v232, v232, v34
	v_add_f32_e32 v233, v233, v35
	v_cvt_pk_bf16_f32 v65, v34, v35
	v_exp_f32_e32 v38, v38
	v_exp_f32_e32 v39, v39
	v_add_f32_e32 v232, v232, v36
	v_add_f32_e32 v233, v233, v37
	v_cvt_pk_bf16_f32 v66, v36, v37
	v_add_f32_e32 v232, v232, v38
	v_add_f32_e32 v233, v233, v39
	v_cvt_pk_bf16_f32 v67, v38, v39
	s_waitcnt lgkmcnt(3)
	v_mfma_f32_32x32x16_bf16 v[48:63], v[208:211], v[88:91], v[48:63]
	ds_read_b128 v[208:211], v72 offset:9280
	v_exp_f32_e32 v40, v40
	v_exp_f32_e32 v41, v41
	s_waitcnt lgkmcnt(3)
	v_mfma_f32_32x32x16_bf16 v[48:63], v[212:215], v[92:95], v[48:63]
	ds_read_b128 v[212:215], v72 offset:9312
	v_exp_f32_e32 v42, v42
	v_exp_f32_e32 v43, v43
	v_add_f32_e32 v232, v232, v40
	v_add_f32_e32 v233, v233, v41
	v_cvt_pk_bf16_f32 v68, v40, v41
	v_mfma_f32_32x32x16_bf16 v[0:15], v[216:219], v[64:67], v[0:15]
	ds_read2_b64 v[216:219], v73 offset0:8 offset1:10
	v_exp_f32_e32 v44, v44
	v_exp_f32_e32 v45, v45
	v_add_f32_e32 v232, v232, v42
	v_add_f32_e32 v233, v233, v43
	v_cvt_pk_bf16_f32 v69, v42, v43
	v_mfma_f32_32x32x16_bf16 v[16:31], v[220:223], v[64:67], v[16:31]
	ds_read2_b64 v[220:223], v74 offset0:40 offset1:42
	v_exp_f32_e32 v46, v46
	v_exp_f32_e32 v47, v47
	v_add_f32_e32 v232, v232, v44
	v_add_f32_e32 v233, v233, v45
	v_cvt_pk_bf16_f32 v70, v44, v45
	v_add_f32_e32 v232, v232, v46
	v_add_f32_e32 v233, v233, v47
	v_cvt_pk_bf16_f32 v71, v46, v47
	s_waitcnt lgkmcnt(5)
	v_mfma_f32_32x32x16_bf16 v[32:47], v[200:203], v[80:83], 0
	ds_read_b128 v[200:203], v72 offset:13824
	v_exp_f32_e32 v48, v48
	v_exp_f32_e32 v49, v49
	s_waitcnt lgkmcnt(5)
	v_mfma_f32_32x32x16_bf16 v[32:47], v[204:207], v[84:87], v[32:47]
	ds_read_b128 v[204:207], v72 offset:13856
	v_exp_f32_e32 v50, v50
	v_exp_f32_e32 v51, v51
	v_add_f32_e32 v232, v232, v48
	v_add_f32_e32 v233, v233, v49
	v_cvt_pk_bf16_f32 v64, v48, v49
	v_mfma_f32_32x32x16_bf16 v[0:15], v[224:227], v[68:71], v[0:15]
	ds_read2_b64 v[224:227], v73 offset0:12 offset1:14
	v_exp_f32_e32 v52, v52
	v_exp_f32_e32 v53, v53
	v_add_f32_e32 v232, v232, v50
	v_add_f32_e32 v233, v233, v51
	v_cvt_pk_bf16_f32 v65, v50, v51
	v_mfma_f32_32x32x16_bf16 v[16:31], v[228:231], v[68:71], v[16:31]
	ds_read2_b64 v[228:231], v74 offset0:44 offset1:46
	v_exp_f32_e32 v54, v54
	v_exp_f32_e32 v55, v55
	v_add_f32_e32 v232, v232, v52
	v_add_f32_e32 v233, v233, v53
	v_cvt_pk_bf16_f32 v66, v52, v53
	v_add_f32_e32 v232, v232, v54
	v_add_f32_e32 v233, v233, v55
	v_cvt_pk_bf16_f32 v67, v54, v55
	s_waitcnt lgkmcnt(7)
	v_mfma_f32_32x32x16_bf16 v[32:47], v[208:211], v[88:91], v[32:47]
	ds_read_b128 v[208:211], v72 offset:13888
	v_exp_f32_e32 v56, v56
	v_exp_f32_e32 v57, v57
	s_waitcnt lgkmcnt(7)
	v_mfma_f32_32x32x16_bf16 v[32:47], v[212:215], v[92:95], v[32:47]
	ds_read_b128 v[212:215], v72 offset:13920
	v_exp_f32_e32 v58, v58
	v_exp_f32_e32 v59, v59
	v_add_f32_e32 v232, v232, v56
	v_add_f32_e32 v233, v233, v57
	v_cvt_pk_bf16_f32 v68, v56, v57
	s_waitcnt lgkmcnt(7)
	v_mfma_f32_32x32x16_bf16 v[0:15], v[216:219], v[64:67], v[0:15]
	ds_read2_b64 v[216:219], v73 offset0:16 offset1:18
	v_exp_f32_e32 v60, v60
	v_exp_f32_e32 v61, v61
	v_add_f32_e32 v232, v232, v58
	v_add_f32_e32 v233, v233, v59
	v_cvt_pk_bf16_f32 v69, v58, v59
	s_waitcnt lgkmcnt(7)
	v_mfma_f32_32x32x16_bf16 v[16:31], v[220:223], v[64:67], v[16:31]
	ds_read2_b64 v[220:223], v74 offset0:48 offset1:50
	v_exp_f32_e32 v62, v62
	v_exp_f32_e32 v63, v63
	v_add_f32_e32 v232, v232, v60
	v_add_f32_e32 v233, v233, v61
	v_cvt_pk_bf16_f32 v70, v60, v61
	v_add_f32_e32 v232, v232, v62
	v_add_f32_e32 v233, v233, v63
	v_cvt_pk_bf16_f32 v71, v62, v63
	s_waitcnt lgkmcnt(7)
	v_mfma_f32_32x32x16_bf16 v[48:63], v[200:203], v[80:83], 0
	v_exp_f32_e32 v32, v32
	v_exp_f32_e32 v33, v33
	s_waitcnt lgkmcnt(6)
	v_mfma_f32_32x32x16_bf16 v[48:63], v[204:207], v[84:87], v[48:63]
	v_exp_f32_e32 v34, v34
	v_exp_f32_e32 v35, v35
	v_add_f32_e32 v232, v232, v32
	v_add_f32_e32 v233, v233, v33
	v_cvt_pk_bf16_f32 v64, v32, v33
	s_waitcnt lgkmcnt(5)
	v_mfma_f32_32x32x16_bf16 v[0:15], v[224:227], v[68:71], v[0:15]
	ds_read2_b64 v[224:227], v73 offset0:20 offset1:22
	v_exp_f32_e32 v36, v36
	v_exp_f32_e32 v37, v37
	v_add_f32_e32 v232, v232, v34
	v_add_f32_e32 v233, v233, v35
	v_cvt_pk_bf16_f32 v65, v34, v35
	s_waitcnt lgkmcnt(5)
	v_mfma_f32_32x32x16_bf16 v[16:31], v[228:231], v[68:71], v[16:31]
	ds_read2_b64 v[228:231], v74 offset0:52 offset1:54
	v_exp_f32_e32 v38, v38
	v_exp_f32_e32 v39, v39
	v_add_f32_e32 v232, v232, v36
	v_add_f32_e32 v233, v233, v37
	v_cvt_pk_bf16_f32 v66, v36, v37
	v_add_f32_e32 v232, v232, v38
	v_add_f32_e32 v233, v233, v39
	v_cvt_pk_bf16_f32 v67, v38, v39
	s_cmp_eq_u32 s45, 0
	s_cbranch_scc1 .Lt1_full_nostage
	s_waitcnt vmcnt(3)
	ds_write_b128 v251, v[96:99]
	s_waitcnt vmcnt(2)
	ds_write_b128 v251, v[100:103] offset:9216
	s_waitcnt vmcnt(1)
	ds_write2_b64 v252, v[104:105], v[106:107] offset1:1
	s_waitcnt vmcnt(0)
	ds_write2_b64 v252, v[108:109], v[110:111] offset0:16 offset1:17
	s_mov_b32 s47, 1
	s_add_i32 s6, s44, 2
	s_add_i32 s7, s91, s44
	s_add_i32 s7, s7, 1
	s_add_i32 s0, s44, 1
	s_cmp_lt_i32 s0, s90
	s_cbranch_scc0 .Lt1_full_nostage
	s_cmp_lt_u32 s0, s89
	s_cselect_b32 s0, s71, s75
	s_cselect_b32 s1, s72, s76
	s_cselect_b32 s4, s73, s77
	s_cselect_b32 s5, s74, s78
	s_cselect_b32 s6, s6, s7
	s_ashr_i32 s7, s6, 31
	s_lshl_b64 s[6:7], s[6:7], 14
	s_add_u32 s6, s6, s58
	s_addc_u32 s7, s7, s59
	s_add_u32 s0, s0, s6
	s_addc_u32 s1, s1, s7
	s_add_u32 s4, s4, s6
	s_addc_u32 s5, s5, s7
	global_load_dwordx4 v[96:99], v248, s[0:1]
	global_load_dwordx4 v[100:103], v249, s[0:1]
	global_load_dwordx4 v[104:107], v248, s[4:5]
	global_load_dwordx4 v[108:111], v249, s[4:5]
; #define LAS __attribute__((address_space(3)))
; #define MFMA32(a, b, c) __builtin_amdgcn_mfma_f32_32x32x16_bf16((a), (b), (c), 0, 0, 0)
; __device__ __forceinline__ float ex2(float x) { return __builtin_amdgcn_exp2f(x); }
; template <int MODE>
; __device__ __forceinline__ void attn_tile(const LAS unsigned char* Kb, const LAS unsigned char* Vb, const bf16x8_t (&qf)[4], f32x16 (&oacc)[2], float& l_run,
;                                           int r, int h, int dlt0, int dlt1, bool hiw) {
;     ...
; #pragma unroll
;     for (int mt = 0; mt < 4; ++mt) {
;         if (mt == 0) { if (hiw) __builtin_amdgcn_s_setprio(1); else __builtin_amdgcn_s_setprio(0); }
;         if (mt == 2) { if (hiw) __builtin_amdgcn_s_setprio(0); else __builtin_amdgcn_s_setprio(1); }
;         const int dl = mt < 2 ? dlt0 : dlt1;
;         f32x16 sacc = zero16();
; #pragma unroll
;         for (int ks = 0; ks < 4; ++ks) { const bf16x8_t ka = *(const LAS bf16x8_t*)(Kb + (32 * mt + r) * A_KSTR + 32 * ks + 16 * h); sacc = MFMA32(ka, qf[ks], sacc); }
; #pragma unroll
;         for (int i = 0; i < 16; ++i) {
;             float p;
;             if (MODE == 2) p = ex2(sacc[i]);
;             else if (MODE == 3) p = ex2(sacc[i] + __int_as_float(dl));
;             else { const int ci = 32 * mt + (i & 3) + 8 * (i >> 2); p = ((unsigned)(dl - ci) < ulim) ? ex2(sacc[i]) : 0.f; }
;             sacc[i] = p; ls += p;
;         }
; #pragma unroll
;         for (int s = 0; s < 2; ++s) {
;             const bf16x8_t pf = pack8(sacc, 8 * s);
; #pragma unroll
;             for (int dt = 0; dt < 2; ++dt) {
;                 const LAS unsigned char* vp = Vb + (32 * dt + r) * A_CVSTR + (32 * mt + 16 * s + 4 * h) * 2;
;                 const s16x4_t lo = *(const LAS s16x4_t*)vp, hi = *(const LAS s16x4_t*)(vp + 16);
;                 oacc[dt] = MFMA32(__builtin_shufflevector(lo, hi, 0, 1, 2, 3, 4, 5, 6, 7), pf, oacc[dt]);
;             }
;         }
;     }
;     l_run += ls;
.Lt1_full_nostage:
	s_waitcnt lgkmcnt(5)
	v_mfma_f32_32x32x16_bf16 v[48:63], v[208:211], v[88:91], v[48:63]
	v_exp_f32_e32 v40, v40
	v_exp_f32_e32 v41, v41
	s_waitcnt lgkmcnt(4)
	v_mfma_f32_32x32x16_bf16 v[48:63], v[212:215], v[92:95], v[48:63]
	v_exp_f32_e32 v42, v42
	v_exp_f32_e32 v43, v43
	v_add_f32_e32 v232, v232, v40
	v_add_f32_e32 v233, v233, v41
	v_cvt_pk_bf16_f32 v68, v40, v41
	s_waitcnt lgkmcnt(3)
	v_mfma_f32_32x32x16_bf16 v[0:15], v[216:219], v[64:67], v[0:15]
	ds_read2_b64 v[216:219], v73 offset0:24 offset1:26
	v_exp_f32_e32 v44, v44
	v_exp_f32_e32 v45, v45
	v_add_f32_e32 v232, v232, v42
	v_add_f32_e32 v233, v233, v43
	v_cvt_pk_bf16_f32 v69, v42, v43
	s_waitcnt lgkmcnt(3)
	v_mfma_f32_32x32x16_bf16 v[16:31], v[220:223], v[64:67], v[16:31]
	ds_read2_b64 v[220:223], v74 offset0:56 offset1:58
	v_exp_f32_e32 v46, v46
	v_exp_f32_e32 v47, v47
	v_add_f32_e32 v232, v232, v44
	v_add_f32_e32 v233, v233, v45
	v_cvt_pk_bf16_f32 v70, v44, v45
	v_add_f32_e32 v232, v232, v46
	v_add_f32_e32 v233, v233, v47
	v_cvt_pk_bf16_f32 v71, v46, v47
	v_exp_f32_e32 v48, v48
	v_exp_f32_e32 v49, v49
	v_exp_f32_e32 v50, v50
	v_exp_f32_e32 v51, v51
	v_add_f32_e32 v232, v232, v48
	v_add_f32_e32 v233, v233, v49
	v_cvt_pk_bf16_f32 v64, v48, v49
	s_waitcnt lgkmcnt(3)
	v_mfma_f32_32x32x16_bf16 v[0:15], v[224:227], v[68:71], v[0:15]
	ds_read2_b64 v[224:227], v73 offset0:28 offset1:30
	v_exp_f32_e32 v52, v52
	v_exp_f32_e32 v53, v53
	v_add_f32_e32 v232, v232, v50
	v_add_f32_e32 v233, v233, v51
	v_cvt_pk_bf16_f32 v65, v50, v51
	s_waitcnt lgkmcnt(3)
	v_mfma_f32_32x32x16_bf16 v[16:31], v[228:231], v[68:71], v[16:31]
	ds_read2_b64 v[228:231], v74 offset0:60 offset1:62
	v_exp_f32_e32 v54, v54
	v_exp_f32_e32 v55, v55
	v_add_f32_e32 v232, v232, v52
	v_add_f32_e32 v233, v233, v53
	v_cvt_pk_bf16_f32 v66, v52, v53
	v_add_f32_e32 v232, v232, v54
	v_add_f32_e32 v233, v233, v55
	v_cvt_pk_bf16_f32 v67, v54, v55
	v_exp_f32_e32 v56, v56
	v_exp_f32_e32 v57, v57
	v_exp_f32_e32 v58, v58
	v_exp_f32_e32 v59, v59
	v_add_f32_e32 v232, v232, v56
	v_add_f32_e32 v233, v233, v57
	v_cvt_pk_bf16_f32 v68, v56, v57
	s_waitcnt lgkmcnt(3)
	v_mfma_f32_32x32x16_bf16 v[0:15], v[216:219], v[64:67], v[0:15]
	v_exp_f32_e32 v60, v60
	v_exp_f32_e32 v61, v61
	v_add_f32_e32 v232, v232, v58
	v_add_f32_e32 v233, v233, v59
	v_cvt_pk_bf16_f32 v69, v58, v59
	s_waitcnt lgkmcnt(2)
	v_mfma_f32_32x32x16_bf16 v[16:31], v[220:223], v[64:67], v[16:31]
	v_exp_f32_e32 v62, v62
	v_exp_f32_e32 v63, v63
	v_add_f32_e32 v232, v232, v60
	v_add_f32_e32 v233, v233, v61
	v_cvt_pk_bf16_f32 v70, v60, v61
	v_add_f32_e32 v232, v232, v62
	v_add_f32_e32 v233, v233, v63
	v_cvt_pk_bf16_f32 v71, v62, v63
	s_nop 1
	s_waitcnt lgkmcnt(1)
	v_mfma_f32_32x32x16_bf16 v[0:15], v[224:227], v[68:71], v[0:15]
	s_waitcnt lgkmcnt(0)
	v_mfma_f32_32x32x16_bf16 v[16:31], v[228:231], v[68:71], v[16:31]
	v_add_f32_e32 v232, v232, v233
	v_add_f32_e32 v112, v112, v232
	s_branch .Lt1_join
.Lt1_bias:
	ds_read_b128 v[200:203], v72 offset:0
	ds_read_b128 v[204:207], v72 offset:32
	ds_read_b128 v[208:211], v72 offset:64
	ds_read_b128 v[212:215], v72 offset:96
	ds_read2_b64 v[216:219], v73 offset0:0 offset1:2
	ds_read2_b64 v[220:223], v74 offset0:32 offset1:34
	ds_read2_b64 v[224:227], v73 offset0:4 offset1:6
	ds_read2_b64 v[228:231], v74 offset0:36 offset1:38
	v_bfe_i32 v236, v158, s49, 1
	s_add_i32 s49, s49, 1
	v_bfe_i32 v237, v158, s49, 1
	s_waitcnt lgkmcnt(7)
	v_mfma_f32_32x32x16_bf16 v[32:47], v[200:203], v[80:83], 0
	ds_read_b128 v[200:203], v72 offset:4608
	s_waitcnt lgkmcnt(7)
	v_mfma_f32_32x32x16_bf16 v[32:47], v[204:207], v[84:87], v[32:47]
	ds_read_b128 v[204:207], v72 offset:4640
	s_waitcnt lgkmcnt(7)
	v_mfma_f32_32x32x16_bf16 v[32:47], v[208:211], v[88:91], v[32:47]
	ds_read_b128 v[208:211], v72 offset:4672
	s_waitcnt lgkmcnt(7)
	v_mfma_f32_32x32x16_bf16 v[32:47], v[212:215], v[92:95], v[32:47]
	ds_read_b128 v[212:215], v72 offset:4704
	s_nop 7
	s_nop 3
	s_waitcnt lgkmcnt(3)
	v_mfma_f32_32x32x16_bf16 v[48:63], v[200:203], v[80:83], 0
	ds_read_b128 v[200:203], v72 offset:9216
	v_exp_f32_e32 v32, v32
	v_exp_f32_e32 v33, v33
	s_waitcnt lgkmcnt(3)
	v_mfma_f32_32x32x16_bf16 v[48:63], v[204:207], v[84:87], v[48:63]
	ds_read_b128 v[204:207], v72 offset:9248
	v_exp_f32_e32 v34, v34
	v_exp_f32_e32 v35, v35
	v_mov_b32_e32 v232, v32
	v_mov_b32_e32 v233, v33
	v_cvt_pk_bf16_f32 v64, v32, v33
	v_and_b32_e32 v64, v236, v64
	v_exp_f32_e32 v36, v36
	v_exp_f32_e32 v37, v37
	v_add_f32_e32 v232, v232, v34
	v_add_f32_e32 v233, v233, v35
	v_cvt_pk_bf16_f32 v65, v34, v35
	v_and_b32_e32 v65, v236, v65
	v_exp_f32_e32 v38, v38
	v_exp_f32_e32 v39, v39
	v_add_f32_e32 v232, v232, v36
	v_add_f32_e32 v233, v233, v37
	v_cvt_pk_bf16_f32 v66, v36, v37
	v_and_b32_e32 v66, v236, v66
	v_add_f32_e32 v232, v232, v38
	v_add_f32_e32 v233, v233, v39
	v_cvt_pk_bf16_f32 v67, v38, v39
	v_and_b32_e32 v67, v236, v67
	s_waitcnt lgkmcnt(3)
	v_mfma_f32_32x32x16_bf16 v[48:63], v[208:211], v[88:91], v[48:63]
	ds_read_b128 v[208:211], v72 offset:9280
	v_exp_f32_e32 v40, v40
	v_exp_f32_e32 v41, v41
	s_waitcnt lgkmcnt(3)
	v_mfma_f32_32x32x16_bf16 v[48:63], v[212:215], v[92:95], v[48:63]
	ds_read_b128 v[212:215], v72 offset:9312
	v_exp_f32_e32 v42, v42
	v_exp_f32_e32 v43, v43
	v_add_f32_e32 v232, v232, v40
	v_add_f32_e32 v233, v233, v41
	v_cvt_pk_bf16_f32 v68, v40, v41
	v_and_b32_e32 v68, v236, v68
	v_mfma_f32_32x32x16_bf16 v[0:15], v[216:219], v[64:67], v[0:15]
	ds_read2_b64 v[216:219], v73 offset0:8 offset1:10
	v_exp_f32_e32 v44, v44
	v_exp_f32_e32 v45, v45
	v_add_f32_e32 v232, v232, v42
	v_add_f32_e32 v233, v233, v43
	v_cvt_pk_bf16_f32 v69, v42, v43
	v_and_b32_e32 v69, v236, v69
	v_mfma_f32_32x32x16_bf16 v[16:31], v[220:223], v[64:67], v[16:31]
	ds_read2_b64 v[220:223], v74 offset0:40 offset1:42
	v_exp_f32_e32 v46, v46
	v_exp_f32_e32 v47, v47
	v_add_f32_e32 v232, v232, v44
	v_add_f32_e32 v233, v233, v45
	v_cvt_pk_bf16_f32 v70, v44, v45
	v_and_b32_e32 v70, v236, v70
	v_add_f32_e32 v232, v232, v46
	v_add_f32_e32 v233, v233, v47
	v_cvt_pk_bf16_f32 v71, v46, v47
	v_and_b32_e32 v71, v236, v71
	s_waitcnt lgkmcnt(5)
; #define LAS __attribute__((address_space(3)))
; #define MFMA32(a, b, c) __builtin_amdgcn_mfma_f32_32x32x16_bf16((a), (b), (c), 0, 0, 0)
; __device__ __forceinline__ float ex2(float x) { return __builtin_amdgcn_exp2f(x); }
; template <int MODE>
; __device__ __forceinline__ void attn_tile(const LAS unsigned char* Kb, const LAS unsigned char* Vb, const bf16x8_t (&qf)[4], f32x16 (&oacc)[2], float& l_run,
;                                           int r, int h, int dlt0, int dlt1, bool hiw) {
;     ...
; #pragma unroll
;     for (int mt = 0; mt < 4; ++mt) {
;         if (mt == 0) { if (hiw) __builtin_amdgcn_s_setprio(1); else __builtin_amdgcn_s_setprio(0); }
;         if (mt == 2) { if (hiw) __builtin_amdgcn_s_setprio(0); else __builtin_amdgcn_s_setprio(1); }
;         const int dl = mt < 2 ? dlt0 : dlt1;
;         f32x16 sacc = zero16();
; #pragma unroll
;         for (int ks = 0; ks < 4; ++ks) { const bf16x8_t ka = *(const LAS bf16x8_t*)(Kb + (32 * mt + r) * A_KSTR + 32 * ks + 16 * h); sacc = MFMA32(ka, qf[ks], sacc); }
; #pragma unroll
;         for (int i = 0; i < 16; ++i) {
;             float p;
;             if (MODE == 2) p = ex2(sacc[i]);
;             else if (MODE == 3) p = ex2(sacc[i] + __int_as_float(dl));
;             else { const int ci = 32 * mt + (i & 3) + 8 * (i >> 2); p = ((unsigned)(dl - ci) < ulim) ? ex2(sacc[i]) : 0.f; }
;             sacc[i] = p; ls += p;
;         }
; #pragma unroll
;         for (int s = 0; s < 2; ++s) {
;             const bf16x8_t pf = pack8(sacc, 8 * s);
; #pragma unroll
;             for (int dt = 0; dt < 2; ++dt) {
;                 const LAS unsigned char* vp = Vb + (32 * dt + r) * A_CVSTR + (32 * mt + 16 * s + 4 * h) * 2;
;                 const s16x4_t lo = *(const LAS s16x4_t*)vp, hi = *(const LAS s16x4_t*)(vp + 16);
;                 oacc[dt] = MFMA32(__builtin_shufflevector(lo, hi, 0, 1, 2, 3, 4, 5, 6, 7), pf, oacc[dt]);
;             }
;         }
;     }
;     l_run += ls;
	v_mfma_f32_32x32x16_bf16 v[32:47], v[200:203], v[80:83], 0
	ds_read_b128 v[200:203], v72 offset:13824
	v_exp_f32_e32 v48, v48
	v_exp_f32_e32 v49, v49
	s_waitcnt lgkmcnt(5)
	v_mfma_f32_32x32x16_bf16 v[32:47], v[204:207], v[84:87], v[32:47]
	ds_read_b128 v[204:207], v72 offset:13856
	v_exp_f32_e32 v50, v50
	v_exp_f32_e32 v51, v51
	v_add_f32_e32 v232, v232, v48
	v_add_f32_e32 v233, v233, v49
	v_cvt_pk_bf16_f32 v64, v48, v49
	v_and_b32_e32 v64, v236, v64
	v_mfma_f32_32x32x16_bf16 v[0:15], v[224:227], v[68:71], v[0:15]
	ds_read2_b64 v[224:227], v73 offset0:12 offset1:14
	v_exp_f32_e32 v52, v52
	v_exp_f32_e32 v53, v53
	v_add_f32_e32 v232, v232, v50
	v_add_f32_e32 v233, v233, v51
	v_cvt_pk_bf16_f32 v65, v50, v51
	v_and_b32_e32 v65, v236, v65
	v_mfma_f32_32x32x16_bf16 v[16:31], v[228:231], v[68:71], v[16:31]
	ds_read2_b64 v[228:231], v74 offset0:44 offset1:46
	v_exp_f32_e32 v54, v54
	v_exp_f32_e32 v55, v55
	v_add_f32_e32 v232, v232, v52
	v_add_f32_e32 v233, v233, v53
	v_cvt_pk_bf16_f32 v66, v52, v53
	v_and_b32_e32 v66, v236, v66
	v_add_f32_e32 v232, v232, v54
	v_add_f32_e32 v233, v233, v55
	v_cvt_pk_bf16_f32 v67, v54, v55
	v_and_b32_e32 v67, v236, v67
	s_waitcnt lgkmcnt(7)
	v_mfma_f32_32x32x16_bf16 v[32:47], v[208:211], v[88:91], v[32:47]
	ds_read_b128 v[208:211], v72 offset:13888
	v_exp_f32_e32 v56, v56
	v_exp_f32_e32 v57, v57
	s_waitcnt lgkmcnt(7)
	v_mfma_f32_32x32x16_bf16 v[32:47], v[212:215], v[92:95], v[32:47]
	ds_read_b128 v[212:215], v72 offset:13920
	v_exp_f32_e32 v58, v58
	v_exp_f32_e32 v59, v59
	v_add_f32_e32 v232, v232, v56
	v_add_f32_e32 v233, v233, v57
	v_cvt_pk_bf16_f32 v68, v56, v57
	v_and_b32_e32 v68, v236, v68
	s_waitcnt lgkmcnt(7)
	v_mfma_f32_32x32x16_bf16 v[0:15], v[216:219], v[64:67], v[0:15]
	ds_read2_b64 v[216:219], v73 offset0:16 offset1:18
	v_exp_f32_e32 v60, v60
	v_exp_f32_e32 v61, v61
	v_add_f32_e32 v232, v232, v58
	v_add_f32_e32 v233, v233, v59
	v_cvt_pk_bf16_f32 v69, v58, v59
	v_and_b32_e32 v69, v236, v69
	s_waitcnt lgkmcnt(7)
	v_mfma_f32_32x32x16_bf16 v[16:31], v[220:223], v[64:67], v[16:31]
	ds_read2_b64 v[220:223], v74 offset0:48 offset1:50
	v_exp_f32_e32 v62, v62
	v_exp_f32_e32 v63, v63
	v_add_f32_e32 v232, v232, v60
	v_add_f32_e32 v233, v233, v61
	v_cvt_pk_bf16_f32 v70, v60, v61
	v_and_b32_e32 v70, v236, v70
	v_add_f32_e32 v232, v232, v62
	v_add_f32_e32 v233, v233, v63
	v_cvt_pk_bf16_f32 v71, v62, v63
	v_and_b32_e32 v71, v236, v71
	s_waitcnt lgkmcnt(7)
	v_mfma_f32_32x32x16_bf16 v[48:63], v[200:203], v[80:83], 0
	v_exp_f32_e32 v32, v32
	v_exp_f32_e32 v33, v33
	s_waitcnt lgkmcnt(6)
	v_mfma_f32_32x32x16_bf16 v[48:63], v[204:207], v[84:87], v[48:63]
	v_exp_f32_e32 v34, v34
	v_exp_f32_e32 v35, v35
	v_mov_b32_e32 v234, v32
	v_mov_b32_e32 v235, v33
	v_cvt_pk_bf16_f32 v64, v32, v33
	v_and_b32_e32 v64, v237, v64
	s_waitcnt lgkmcnt(5)
	v_mfma_f32_32x32x16_bf16 v[0:15], v[224:227], v[68:71], v[0:15]
	ds_read2_b64 v[224:227], v73 offset0:20 offset1:22
	v_exp_f32_e32 v36, v36
	v_exp_f32_e32 v37, v37
	v_add_f32_e32 v234, v234, v34
	v_add_f32_e32 v235, v235, v35
	v_cvt_pk_bf16_f32 v65, v34, v35
	v_and_b32_e32 v65, v237, v65
	s_waitcnt lgkmcnt(5)
	v_mfma_f32_32x32x16_bf16 v[16:31], v[228:231], v[68:71], v[16:31]
	ds_read2_b64 v[228:231], v74 offset0:52 offset1:54
	v_exp_f32_e32 v38, v38
	v_exp_f32_e32 v39, v39
	v_add_f32_e32 v234, v234, v36
	v_add_f32_e32 v235, v235, v37
	v_cvt_pk_bf16_f32 v66, v36, v37
	v_and_b32_e32 v66, v237, v66
	v_add_f32_e32 v234, v234, v38
	v_add_f32_e32 v235, v235, v39
	v_cvt_pk_bf16_f32 v67, v38, v39
	v_and_b32_e32 v67, v237, v67
	s_cmp_eq_u32 s45, 0
	s_cbranch_scc1 .Lt1_bias_nostage
	s_waitcnt vmcnt(3)
	ds_write_b128 v251, v[96:99]
	s_waitcnt vmcnt(2)
	ds_write_b128 v251, v[100:103] offset:9216
	s_waitcnt vmcnt(1)
	ds_write2_b64 v252, v[104:105], v[106:107] offset1:1
	s_waitcnt vmcnt(0)
	ds_write2_b64 v252, v[108:109], v[110:111] offset0:16 offset1:17
	s_mov_b32 s47, 1
	s_add_i32 s6, s44, 2
	s_add_i32 s7, s91, s44
	s_add_i32 s7, s7, 1
	s_add_i32 s0, s44, 1
	s_cmp_lt_i32 s0, s90
	s_cbranch_scc0 .Lt1_bias_nostage
	s_cmp_lt_u32 s0, s89
	s_cselect_b32 s0, s71, s75
	s_cselect_b32 s1, s72, s76
	s_cselect_b32 s4, s73, s77
	s_cselect_b32 s5, s74, s78
	s_cselect_b32 s6, s6, s7
	s_ashr_i32 s7, s6, 31
	s_lshl_b64 s[6:7], s[6:7], 14
	s_add_u32 s6, s6, s58
	s_addc_u32 s7, s7, s59
	s_add_u32 s0, s0, s6
	s_addc_u32 s1, s1, s7
	s_add_u32 s4, s4, s6
	s_addc_u32 s5, s5, s7
	global_load_dwordx4 v[96:99], v248, s[0:1]
	global_load_dwordx4 v[100:103], v249, s[0:1]
	global_load_dwordx4 v[104:107], v248, s[4:5]
	global_load_dwordx4 v[108:111], v249, s[4:5]
; #define LAS __attribute__((address_space(3)))
; #define MFMA32(a, b, c) __builtin_amdgcn_mfma_f32_32x32x16_bf16((a), (b), (c), 0, 0, 0)
; __device__ __forceinline__ float ex2(float x) { return __builtin_amdgcn_exp2f(x); }
; template <int MODE>
; __device__ __forceinline__ void attn_tile(const LAS unsigned char* Kb, const LAS unsigned char* Vb, const bf16x8_t (&qf)[4], f32x16 (&oacc)[2], float& l_run,
;                                           int r, int h, int dlt0, int dlt1, bool hiw) {
;     ...
; #pragma unroll
;     for (int mt = 0; mt < 4; ++mt) {
;         if (mt == 0) { if (hiw) __builtin_amdgcn_s_setprio(1); else __builtin_amdgcn_s_setprio(0); }
;         if (mt == 2) { if (hiw) __builtin_amdgcn_s_setprio(0); else __builtin_amdgcn_s_setprio(1); }
;         const int dl = mt < 2 ? dlt0 : dlt1;
;         f32x16 sacc = zero16();
; #pragma unroll
;         for (int ks = 0; ks < 4; ++ks) { const bf16x8_t ka = *(const LAS bf16x8_t*)(Kb + (32 * mt + r) * A_KSTR + 32 * ks + 16 * h); sacc = MFMA32(ka, qf[ks], sacc); }
; #pragma unroll
;         for (int i = 0; i < 16; ++i) {
;             float p;
;             if (MODE == 2) p = ex2(sacc[i]);
;             else if (MODE == 3) p = ex2(sacc[i] + __int_as_float(dl));
;             else { const int ci = 32 * mt + (i & 3) + 8 * (i >> 2); p = ((unsigned)(dl - ci) < ulim) ? ex2(sacc[i]) : 0.f; }
;             sacc[i] = p; ls += p;
;         }
; #pragma unroll
;         for (int s = 0; s < 2; ++s) {
;             const bf16x8_t pf = pack8(sacc, 8 * s);
; #pragma unroll
;             for (int dt = 0; dt < 2; ++dt) {
;                 const LAS unsigned char* vp = Vb + (32 * dt + r) * A_CVSTR + (32 * mt + 16 * s + 4 * h) * 2;
;                 const s16x4_t lo = *(const LAS s16x4_t*)vp, hi = *(const LAS s16x4_t*)(vp + 16);
;                 oacc[dt] = MFMA32(__builtin_shufflevector(lo, hi, 0, 1, 2, 3, 4, 5, 6, 7), pf, oacc[dt]);
;             }
;         }
;     }
;     l_run += ls;
.Lt1_bias_nostage:
	s_waitcnt lgkmcnt(5)
	v_mfma_f32_32x32x16_bf16 v[48:63], v[208:211], v[88:91], v[48:63]
	v_exp_f32_e32 v40, v40
	v_exp_f32_e32 v41, v41
	s_waitcnt lgkmcnt(4)
	v_mfma_f32_32x32x16_bf16 v[48:63], v[212:215], v[92:95], v[48:63]
	v_exp_f32_e32 v42, v42
	v_exp_f32_e32 v43, v43
	v_add_f32_e32 v234, v234, v40
	v_add_f32_e32 v235, v235, v41
	v_cvt_pk_bf16_f32 v68, v40, v41
	v_and_b32_e32 v68, v237, v68
	s_waitcnt lgkmcnt(3)
	v_mfma_f32_32x32x16_bf16 v[0:15], v[216:219], v[64:67], v[0:15]
	ds_read2_b64 v[216:219], v73 offset0:24 offset1:26
	v_exp_f32_e32 v44, v44
	v_exp_f32_e32 v45, v45
	v_add_f32_e32 v234, v234, v42
	v_add_f32_e32 v235, v235, v43
	v_cvt_pk_bf16_f32 v69, v42, v43
	v_and_b32_e32 v69, v237, v69
	s_waitcnt lgkmcnt(3)
	v_mfma_f32_32x32x16_bf16 v[16:31], v[220:223], v[64:67], v[16:31]
	ds_read2_b64 v[220:223], v74 offset0:56 offset1:58
	v_exp_f32_e32 v46, v46
	v_exp_f32_e32 v47, v47
	v_add_f32_e32 v234, v234, v44
	v_add_f32_e32 v235, v235, v45
	v_cvt_pk_bf16_f32 v70, v44, v45
	v_and_b32_e32 v70, v237, v70
	v_add_f32_e32 v234, v234, v46
	v_add_f32_e32 v235, v235, v47
	v_cvt_pk_bf16_f32 v71, v46, v47
	v_and_b32_e32 v71, v237, v71
	v_exp_f32_e32 v48, v48
	v_exp_f32_e32 v49, v49
	v_exp_f32_e32 v50, v50
	v_exp_f32_e32 v51, v51
	v_add_f32_e32 v234, v234, v48
	v_add_f32_e32 v235, v235, v49
	v_cvt_pk_bf16_f32 v64, v48, v49
	v_and_b32_e32 v64, v237, v64
	s_waitcnt lgkmcnt(3)
	v_mfma_f32_32x32x16_bf16 v[0:15], v[224:227], v[68:71], v[0:15]
	ds_read2_b64 v[224:227], v73 offset0:28 offset1:30
	v_exp_f32_e32 v52, v52
	v_exp_f32_e32 v53, v53
	v_add_f32_e32 v234, v234, v50
	v_add_f32_e32 v235, v235, v51
	v_cvt_pk_bf16_f32 v65, v50, v51
	v_and_b32_e32 v65, v237, v65
	s_waitcnt lgkmcnt(3)
	v_mfma_f32_32x32x16_bf16 v[16:31], v[228:231], v[68:71], v[16:31]
	ds_read2_b64 v[228:231], v74 offset0:60 offset1:62
	v_exp_f32_e32 v54, v54
	v_exp_f32_e32 v55, v55
	v_add_f32_e32 v234, v234, v52
	v_add_f32_e32 v235, v235, v53
	v_cvt_pk_bf16_f32 v66, v52, v53
	v_and_b32_e32 v66, v237, v66
	v_add_f32_e32 v234, v234, v54
	v_add_f32_e32 v235, v235, v55
	v_cvt_pk_bf16_f32 v67, v54, v55
	v_and_b32_e32 v67, v237, v67
	v_exp_f32_e32 v56, v56
	v_exp_f32_e32 v57, v57
	v_exp_f32_e32 v58, v58
	v_exp_f32_e32 v59, v59
	v_add_f32_e32 v234, v234, v56
	v_add_f32_e32 v235, v235, v57
	v_cvt_pk_bf16_f32 v68, v56, v57
	v_and_b32_e32 v68, v237, v68
	s_waitcnt lgkmcnt(3)
	v_mfma_f32_32x32x16_bf16 v[0:15], v[216:219], v[64:67], v[0:15]
	v_exp_f32_e32 v60, v60
	v_exp_f32_e32 v61, v61
	v_add_f32_e32 v234, v234, v58
	v_add_f32_e32 v235, v235, v59
	v_cvt_pk_bf16_f32 v69, v58, v59
	v_and_b32_e32 v69, v237, v69
	s_waitcnt lgkmcnt(2)
	v_mfma_f32_32x32x16_bf16 v[16:31], v[220:223], v[64:67], v[16:31]
	v_exp_f32_e32 v62, v62
	v_exp_f32_e32 v63, v63
	v_add_f32_e32 v234, v234, v60
	v_add_f32_e32 v235, v235, v61
	v_cvt_pk_bf16_f32 v70, v60, v61
	v_and_b32_e32 v70, v237, v70
	v_add_f32_e32 v234, v234, v62
	v_add_f32_e32 v235, v235, v63
	v_cvt_pk_bf16_f32 v71, v62, v63
	v_and_b32_e32 v71, v237, v71
	s_nop 1
	s_waitcnt lgkmcnt(1)
	v_mfma_f32_32x32x16_bf16 v[0:15], v[224:227], v[68:71], v[0:15]
	s_waitcnt lgkmcnt(0)
	v_mfma_f32_32x32x16_bf16 v[16:31], v[228:231], v[68:71], v[16:31]
	v_add_f32_e32 v232, v232, v233
	v_add_f32_e32 v234, v234, v235
	v_and_b32_e32 v239, 1.0, v236
	v_and_b32_e32 v240, 1.0, v237
	v_fmac_f32_e32 v112, v232, v239
	v_fmac_f32_e32 v112, v234, v240
	s_branch .Lt1_join

; #define LAS __attribute__((address_space(3)))
; #define MFMA32(a, b, c) __builtin_amdgcn_mfma_f32_32x32x16_bf16((a), (b), (c), 0, 0, 0)
; __device__ __forceinline__ float ex2(float x) { return __builtin_amdgcn_exp2f(x); }
; template <int MODE>
; __device__ __forceinline__ void attn_tile(const LAS unsigned char* Kb, const LAS unsigned char* Vb, const bf16x8_t (&qf)[4], f32x16 (&oacc)[2], float& l_run,
;                                           int r, int h, int dlt0, int dlt1, bool hiw) {
;     ...
; #pragma unroll
;     for (int mt = 0; mt < 4; ++mt) {
;         if (mt == 0) { if (hiw) __builtin_amdgcn_s_setprio(1); else __builtin_amdgcn_s_setprio(0); }
;         if (mt == 2) { if (hiw) __builtin_amdgcn_s_setprio(0); else __builtin_amdgcn_s_setprio(1); }
;         const int dl = mt < 2 ? dlt0 : dlt1;
;         f32x16 sacc = zero16();
; #pragma unroll
;         for (int ks = 0; ks < 4; ++ks) { const bf16x8_t ka = *(const LAS bf16x8_t*)(Kb + (32 * mt + r) * A_KSTR + 32 * ks + 16 * h); sacc = MFMA32(ka, qf[ks], sacc); }
; #pragma unroll
;         for (int i = 0; i < 16; ++i) {
;             float p;
;             if (MODE == 2) p = ex2(sacc[i]);
;             else if (MODE == 3) p = ex2(sacc[i] + __int_as_float(dl));
;             else { const int ci = 32 * mt + (i & 3) + 8 * (i >> 2); p = ((unsigned)(dl - ci) < ulim) ? ex2(sacc[i]) : 0.f; }
;             sacc[i] = p; ls += p;
;         }
; #pragma unroll
;         for (int s = 0; s < 2; ++s) {
;             const bf16x8_t pf = pack8(sacc, 8 * s);
; #pragma unroll
;             for (int dt = 0; dt < 2; ++dt) {
;                 const LAS unsigned char* vp = Vb + (32 * dt + r) * A_CVSTR + (32 * mt + 16 * s + 4 * h) * 2;
;                 const s16x4_t lo = *(const LAS s16x4_t*)vp, hi = *(const LAS s16x4_t*)(vp + 16);
;                 oacc[dt] = MFMA32(__builtin_shufflevector(lo, hi, 0, 1, 2, 3, 4, 5, 6, 7), pf, oacc[dt]);
;             }
;         }
;     }
;     l_run += ls;
.Lt1_d1:
	ds_read_b128 v[200:203], v72 offset:0
	ds_read_b128 v[204:207], v72 offset:32
	ds_read_b128 v[208:211], v72 offset:64
	ds_read_b128 v[212:215], v72 offset:96
	ds_read2_b64 v[216:219], v73 offset0:0 offset1:2
	ds_read2_b64 v[220:223], v74 offset0:32 offset1:34
	ds_read2_b64 v[224:227], v73 offset0:4 offset1:6
	ds_read2_b64 v[228:231], v74 offset0:36 offset1:38
	s_waitcnt lgkmcnt(7)
	v_mfma_f32_32x32x16_bf16 v[32:47], v[200:203], v[80:83], 0
	ds_read_b128 v[200:203], v72 offset:4608
	s_waitcnt lgkmcnt(7)
	v_mfma_f32_32x32x16_bf16 v[32:47], v[204:207], v[84:87], v[32:47]
	ds_read_b128 v[204:207], v72 offset:4640
	s_waitcnt lgkmcnt(7)
	v_mfma_f32_32x32x16_bf16 v[32:47], v[208:211], v[88:91], v[32:47]
	ds_read_b128 v[208:211], v72 offset:4672
	s_waitcnt lgkmcnt(7)
	v_mfma_f32_32x32x16_bf16 v[32:47], v[212:215], v[92:95], v[32:47]
	ds_read_b128 v[212:215], v72 offset:4704
	s_nop 7
	s_nop 3
	s_waitcnt lgkmcnt(3)
	v_mfma_f32_32x32x16_bf16 v[48:63], v[200:203], v[80:83], 0
	v_exp_f32_e32 v32, v32
	v_exp_f32_e32 v33, v33
	s_waitcnt lgkmcnt(2)
	v_mfma_f32_32x32x16_bf16 v[48:63], v[204:207], v[84:87], v[48:63]
	v_exp_f32_e32 v34, v34
	v_exp_f32_e32 v35, v35
	v_mov_b32_e32 v232, v32
	v_mov_b32_e32 v233, v33
	v_cvt_pk_bf16_f32 v64, v32, v33
	v_exp_f32_e32 v36, v36
	v_exp_f32_e32 v37, v37
	v_add_f32_e32 v232, v232, v34
	v_add_f32_e32 v233, v233, v35
	v_cvt_pk_bf16_f32 v65, v34, v35
	v_exp_f32_e32 v38, v38
	v_exp_f32_e32 v39, v39
	v_add_f32_e32 v232, v232, v36
	v_add_f32_e32 v233, v233, v37
	v_cvt_pk_bf16_f32 v66, v36, v37
	v_add_f32_e32 v232, v232, v38
	v_add_f32_e32 v233, v233, v39
	v_cvt_pk_bf16_f32 v67, v38, v39
	s_cmp_eq_u32 s45, 0
	s_cbranch_scc1 .Lt1_d1_nostage
	s_waitcnt vmcnt(3)
	ds_write_b128 v251, v[96:99]
	s_waitcnt vmcnt(2)
	ds_write_b128 v251, v[100:103] offset:9216
	s_waitcnt vmcnt(1)
	ds_write2_b64 v252, v[104:105], v[106:107] offset1:1
	s_waitcnt vmcnt(0)
	ds_write2_b64 v252, v[108:109], v[110:111] offset0:16 offset1:17
	s_mov_b32 s47, 1
	s_add_i32 s6, s44, 2
	s_add_i32 s7, s91, s44
	s_add_i32 s7, s7, 1
	s_add_i32 s0, s44, 1
	s_cmp_lt_i32 s0, s90
	s_cbranch_scc0 .Lt1_d1_nostage
	s_cmp_lt_u32 s0, s89
	s_cselect_b32 s0, s71, s75
	s_cselect_b32 s1, s72, s76
	s_cselect_b32 s4, s73, s77
	s_cselect_b32 s5, s74, s78
	s_cselect_b32 s6, s6, s7
	s_ashr_i32 s7, s6, 31
	s_lshl_b64 s[6:7], s[6:7], 14
	s_add_u32 s6, s6, s58
	s_addc_u32 s7, s7, s59
	s_add_u32 s0, s0, s6
	s_addc_u32 s1, s1, s7
	s_add_u32 s4, s4, s6
	s_addc_u32 s5, s5, s7
	global_load_dwordx4 v[96:99], v248, s[0:1]
	global_load_dwordx4 v[100:103], v249, s[0:1]
	global_load_dwordx4 v[104:107], v248, s[4:5]
	global_load_dwordx4 v[108:111], v249, s[4:5]
.Lt1_d1_nostage:
	s_waitcnt lgkmcnt(1)
	v_mfma_f32_32x32x16_bf16 v[48:63], v[208:211], v[88:91], v[48:63]
	v_exp_f32_e32 v40, v40
	v_exp_f32_e32 v41, v41
	s_waitcnt lgkmcnt(0)
	v_mfma_f32_32x32x16_bf16 v[48:63], v[212:215], v[92:95], v[48:63]
	v_exp_f32_e32 v42, v42
	v_exp_f32_e32 v43, v43
	v_add_f32_e32 v232, v232, v40
	v_add_f32_e32 v233, v233, v41
	v_cvt_pk_bf16_f32 v68, v40, v41
	v_mfma_f32_32x32x16_bf16 v[0:15], v[216:219], v[64:67], v[0:15]
	ds_read2_b64 v[216:219], v73 offset0:8 offset1:10
	v_exp_f32_e32 v44, v44
	v_exp_f32_e32 v45, v45
	v_add_f32_e32 v232, v232, v42
	v_add_f32_e32 v233, v233, v43
	v_cvt_pk_bf16_f32 v69, v42, v43
	v_mfma_f32_32x32x16_bf16 v[16:31], v[220:223], v[64:67], v[16:31]
	ds_read2_b64 v[220:223], v74 offset0:40 offset1:42
	v_exp_f32_e32 v46, v46
	v_exp_f32_e32 v47, v47
	v_add_f32_e32 v232, v232, v44
	v_add_f32_e32 v233, v233, v45
	v_cvt_pk_bf16_f32 v70, v44, v45
	v_add_f32_e32 v232, v232, v46
	v_add_f32_e32 v233, v233, v47
	v_cvt_pk_bf16_f32 v71, v46, v47
	v_cmp_le_i32_e64 s[0:1], 0, v250
	v_cmp_le_i32_e64 s[4:5], 1, v250
	v_exp_f32_e32 v48, v48
	v_exp_f32_e32 v49, v49
	v_cmp_le_i32_e64 s[6:7], 2, v250
	v_cmp_le_i32_e64 s[48:49], 3, v250
	v_exp_f32_e32 v50, v50
	v_exp_f32_e32 v51, v51
	v_cndmask_b32_e64 v48, 0, v48, s[0:1]
	v_cndmask_b32_e64 v49, 0, v49, s[4:5]
	v_add_f32_e32 v232, v232, v48
	v_add_f32_e32 v233, v233, v49
	v_cvt_pk_bf16_f32 v64, v48, v49
	v_mfma_f32_32x32x16_bf16 v[0:15], v[224:227], v[68:71], v[0:15]
	ds_read2_b64 v[224:227], v73 offset0:12 offset1:14
	v_cmp_le_i32_e64 s[0:1], 8, v250
	v_cmp_le_i32_e64 s[4:5], 9, v250
	v_exp_f32_e32 v52, v52
	v_exp_f32_e32 v53, v53
	v_cndmask_b32_e64 v50, 0, v50, s[6:7]
	v_cndmask_b32_e64 v51, 0, v51, s[48:49]
	v_add_f32_e32 v232, v232, v50
	v_add_f32_e32 v233, v233, v51
	v_cvt_pk_bf16_f32 v65, v50, v51
	v_mfma_f32_32x32x16_bf16 v[16:31], v[228:231], v[68:71], v[16:31]
	ds_read2_b64 v[228:231], v74 offset0:44 offset1:46
	v_cmp_le_i32_e64 s[6:7], 10, v250
	v_cmp_le_i32_e64 s[48:49], 11, v250
	v_exp_f32_e32 v54, v54
	v_exp_f32_e32 v55, v55
	v_cndmask_b32_e64 v52, 0, v52, s[0:1]
	v_cndmask_b32_e64 v53, 0, v53, s[4:5]
	v_add_f32_e32 v232, v232, v52
	v_add_f32_e32 v233, v233, v53
	v_cvt_pk_bf16_f32 v66, v52, v53
	v_cndmask_b32_e64 v54, 0, v54, s[6:7]
	v_cndmask_b32_e64 v55, 0, v55, s[48:49]
	v_add_f32_e32 v232, v232, v54
	v_add_f32_e32 v233, v233, v55
	v_cvt_pk_bf16_f32 v67, v54, v55
	v_cmp_le_i32_e64 s[0:1], 16, v250
	v_cmp_le_i32_e64 s[4:5], 17, v250
	v_exp_f32_e32 v56, v56
	v_exp_f32_e32 v57, v57
	v_cmp_le_i32_e64 s[6:7], 18, v250
	v_cmp_le_i32_e64 s[48:49], 19, v250
	v_exp_f32_e32 v58, v58
	v_exp_f32_e32 v59, v59
	v_cndmask_b32_e64 v56, 0, v56, s[0:1]
	v_cndmask_b32_e64 v57, 0, v57, s[4:5]
	v_add_f32_e32 v232, v232, v56
	v_add_f32_e32 v233, v233, v57
	v_cvt_pk_bf16_f32 v68, v56, v57
	s_waitcnt lgkmcnt(3)
	v_mfma_f32_32x32x16_bf16 v[0:15], v[216:219], v[64:67], v[0:15]
	v_cmp_le_i32_e64 s[0:1], 24, v250
	v_cmp_le_i32_e64 s[4:5], 25, v250
	v_exp_f32_e32 v60, v60
	v_exp_f32_e32 v61, v61
	v_cndmask_b32_e64 v58, 0, v58, s[6:7]
	v_cndmask_b32_e64 v59, 0, v59, s[48:49]
	v_add_f32_e32 v232, v232, v58
	v_add_f32_e32 v233, v233, v59
	v_cvt_pk_bf16_f32 v69, v58, v59
	s_waitcnt lgkmcnt(2)
	v_mfma_f32_32x32x16_bf16 v[16:31], v[220:223], v[64:67], v[16:31]
	v_cmp_le_i32_e64 s[6:7], 26, v250
	v_cmp_le_i32_e64 s[48:49], 27, v250
	v_exp_f32_e32 v62, v62
	v_exp_f32_e32 v63, v63
	v_cndmask_b32_e64 v60, 0, v60, s[0:1]
	v_cndmask_b32_e64 v61, 0, v61, s[4:5]
	v_add_f32_e32 v232, v232, v60
	v_add_f32_e32 v233, v233, v61
	v_cvt_pk_bf16_f32 v70, v60, v61
	v_cndmask_b32_e64 v62, 0, v62, s[6:7]
	v_cndmask_b32_e64 v63, 0, v63, s[48:49]
	v_add_f32_e32 v232, v232, v62
	v_add_f32_e32 v233, v233, v63
	v_cvt_pk_bf16_f32 v71, v62, v63
	s_nop 1
	s_waitcnt lgkmcnt(1)
	v_mfma_f32_32x32x16_bf16 v[0:15], v[224:227], v[68:71], v[0:15]
	s_waitcnt lgkmcnt(0)
	v_mfma_f32_32x32x16_bf16 v[16:31], v[228:231], v[68:71], v[16:31]
	v_add_f32_e32 v232, v232, v233
	v_add_f32_e32 v112, v112, v232
	s_branch .Lt1_join
; #define LAS __attribute__((address_space(3)))
; #define MFMA32(a, b, c) __builtin_amdgcn_mfma_f32_32x32x16_bf16((a), (b), (c), 0, 0, 0)
; __device__ __forceinline__ float ex2(float x) { return __builtin_amdgcn_exp2f(x); }
; template <int MODE>
; __device__ __forceinline__ void attn_tile(const LAS unsigned char* Kb, const LAS unsigned char* Vb, const bf16x8_t (&qf)[4], f32x16 (&oacc)[2], float& l_run,
;                                           int r, int h, int dlt0, int dlt1, bool hiw) {
;     ...
; #pragma unroll
;     for (int mt = 0; mt < 4; ++mt) {
;         if (mt == 0) { if (hiw) __builtin_amdgcn_s_setprio(1); else __builtin_amdgcn_s_setprio(0); }
;         if (mt == 2) { if (hiw) __builtin_amdgcn_s_setprio(0); else __builtin_amdgcn_s_setprio(1); }
;         const int dl = mt < 2 ? dlt0 : dlt1;
;         f32x16 sacc = zero16();
; #pragma unroll
;         for (int ks = 0; ks < 4; ++ks) { const bf16x8_t ka = *(const LAS bf16x8_t*)(Kb + (32 * mt + r) * A_KSTR + 32 * ks + 16 * h); sacc = MFMA32(ka, qf[ks], sacc); }
; #pragma unroll
;         for (int i = 0; i < 16; ++i) {
;             float p;
;             if (MODE == 2) p = ex2(sacc[i]);
;             else if (MODE == 3) p = ex2(sacc[i] + __int_as_float(dl));
;             else { const int ci = 32 * mt + (i & 3) + 8 * (i >> 2); p = ((unsigned)(dl - ci) < ulim) ? ex2(sacc[i]) : 0.f; }
;             sacc[i] = p; ls += p;
;         }
; #pragma unroll
;         for (int s = 0; s < 2; ++s) {
;             const bf16x8_t pf = pack8(sacc, 8 * s);
; #pragma unroll
;             for (int dt = 0; dt < 2; ++dt) {
;                 const LAS unsigned char* vp = Vb + (32 * dt + r) * A_CVSTR + (32 * mt + 16 * s + 4 * h) * 2;
;                 const s16x4_t lo = *(const LAS s16x4_t*)vp, hi = *(const LAS s16x4_t*)(vp + 16);
;                 oacc[dt] = MFMA32(__builtin_shufflevector(lo, hi, 0, 1, 2, 3, 4, 5, 6, 7), pf, oacc[dt]);
;             }
;         }
;     }
;     l_run += ls;
.Lt1_d2:
	ds_read_b128 v[200:203], v72 offset:0
	ds_read_b128 v[204:207], v72 offset:32
	ds_read_b128 v[208:211], v72 offset:64
	ds_read_b128 v[212:215], v72 offset:96
	ds_read2_b64 v[216:219], v73 offset0:0 offset1:2
	ds_read2_b64 v[220:223], v74 offset0:32 offset1:34
	ds_read2_b64 v[224:227], v73 offset0:4 offset1:6
	ds_read2_b64 v[228:231], v74 offset0:36 offset1:38
	s_waitcnt lgkmcnt(7)
	v_mfma_f32_32x32x16_bf16 v[32:47], v[200:203], v[80:83], 0
	ds_read_b128 v[200:203], v72 offset:4608
	s_waitcnt lgkmcnt(7)
	v_mfma_f32_32x32x16_bf16 v[32:47], v[204:207], v[84:87], v[32:47]
	ds_read_b128 v[204:207], v72 offset:4640
	s_waitcnt lgkmcnt(7)
	v_mfma_f32_32x32x16_bf16 v[32:47], v[208:211], v[88:91], v[32:47]
	ds_read_b128 v[208:211], v72 offset:4672
	s_waitcnt lgkmcnt(7)
	v_mfma_f32_32x32x16_bf16 v[32:47], v[212:215], v[92:95], v[32:47]
	ds_read_b128 v[212:215], v72 offset:4704
	s_nop 7
	s_nop 3
	s_waitcnt lgkmcnt(3)
	v_mfma_f32_32x32x16_bf16 v[48:63], v[200:203], v[80:83], 0
	ds_read_b128 v[200:203], v72 offset:9216
	v_exp_f32_e32 v32, v32
	v_exp_f32_e32 v33, v33
	s_waitcnt lgkmcnt(3)
	v_mfma_f32_32x32x16_bf16 v[48:63], v[204:207], v[84:87], v[48:63]
	ds_read_b128 v[204:207], v72 offset:9248
	v_exp_f32_e32 v34, v34
	v_exp_f32_e32 v35, v35
	v_mov_b32_e32 v232, v32
	v_mov_b32_e32 v233, v33
	v_cvt_pk_bf16_f32 v64, v32, v33
	v_exp_f32_e32 v36, v36
	v_exp_f32_e32 v37, v37
	v_add_f32_e32 v232, v232, v34
	v_add_f32_e32 v233, v233, v35
	v_cvt_pk_bf16_f32 v65, v34, v35
	v_exp_f32_e32 v38, v38
	v_exp_f32_e32 v39, v39
	v_add_f32_e32 v232, v232, v36
	v_add_f32_e32 v233, v233, v37
	v_cvt_pk_bf16_f32 v66, v36, v37
	v_add_f32_e32 v232, v232, v38
	v_add_f32_e32 v233, v233, v39
	v_cvt_pk_bf16_f32 v67, v38, v39
	s_waitcnt lgkmcnt(3)
	v_mfma_f32_32x32x16_bf16 v[48:63], v[208:211], v[88:91], v[48:63]
	ds_read_b128 v[208:211], v72 offset:9280
	v_exp_f32_e32 v40, v40
	v_exp_f32_e32 v41, v41
	s_waitcnt lgkmcnt(3)
	v_mfma_f32_32x32x16_bf16 v[48:63], v[212:215], v[92:95], v[48:63]
	ds_read_b128 v[212:215], v72 offset:9312
	v_exp_f32_e32 v42, v42
	v_exp_f32_e32 v43, v43
	v_add_f32_e32 v232, v232, v40
	v_add_f32_e32 v233, v233, v41
	v_cvt_pk_bf16_f32 v68, v40, v41
	v_mfma_f32_32x32x16_bf16 v[0:15], v[216:219], v[64:67], v[0:15]
	ds_read2_b64 v[216:219], v73 offset0:8 offset1:10
	v_exp_f32_e32 v44, v44
	v_exp_f32_e32 v45, v45
	v_add_f32_e32 v232, v232, v42
	v_add_f32_e32 v233, v233, v43
	v_cvt_pk_bf16_f32 v69, v42, v43
	v_mfma_f32_32x32x16_bf16 v[16:31], v[220:223], v[64:67], v[16:31]
	ds_read2_b64 v[220:223], v74 offset0:40 offset1:42
	v_exp_f32_e32 v46, v46
	v_exp_f32_e32 v47, v47
	v_add_f32_e32 v232, v232, v44
	v_add_f32_e32 v233, v233, v45
	v_cvt_pk_bf16_f32 v70, v44, v45
	v_add_f32_e32 v232, v232, v46
	v_add_f32_e32 v233, v233, v47
	v_cvt_pk_bf16_f32 v71, v46, v47
	s_waitcnt lgkmcnt(5)
	v_mfma_f32_32x32x16_bf16 v[32:47], v[200:203], v[80:83], 0
	v_exp_f32_e32 v48, v48
	v_exp_f32_e32 v49, v49
	s_waitcnt lgkmcnt(4)
	v_mfma_f32_32x32x16_bf16 v[32:47], v[204:207], v[84:87], v[32:47]
	v_exp_f32_e32 v50, v50
	v_exp_f32_e32 v51, v51
	v_add_f32_e32 v232, v232, v48
	v_add_f32_e32 v233, v233, v49
	v_cvt_pk_bf16_f32 v64, v48, v49
	v_mfma_f32_32x32x16_bf16 v[0:15], v[224:227], v[68:71], v[0:15]
	ds_read2_b64 v[224:227], v73 offset0:12 offset1:14
	v_exp_f32_e32 v52, v52
	v_exp_f32_e32 v53, v53
	v_add_f32_e32 v232, v232, v50
	v_add_f32_e32 v233, v233, v51
	v_cvt_pk_bf16_f32 v65, v50, v51
	v_mfma_f32_32x32x16_bf16 v[16:31], v[228:231], v[68:71], v[16:31]
	ds_read2_b64 v[228:231], v74 offset0:44 offset1:46
	v_exp_f32_e32 v54, v54
	v_exp_f32_e32 v55, v55
	v_add_f32_e32 v232, v232, v52
	v_add_f32_e32 v233, v233, v53
	v_cvt_pk_bf16_f32 v66, v52, v53
	v_add_f32_e32 v232, v232, v54
	v_add_f32_e32 v233, v233, v55
	v_cvt_pk_bf16_f32 v67, v54, v55
	s_cmp_eq_u32 s45, 0
	s_cbranch_scc1 .Lt1_d2_nostage
	s_waitcnt vmcnt(3)
	ds_write_b128 v251, v[96:99]
	s_waitcnt vmcnt(2)
	ds_write_b128 v251, v[100:103] offset:9216
	s_waitcnt vmcnt(1)
	ds_write2_b64 v252, v[104:105], v[106:107] offset1:1
	s_waitcnt vmcnt(0)
	ds_write2_b64 v252, v[108:109], v[110:111] offset0:16 offset1:17
	s_mov_b32 s47, 1
	s_add_i32 s6, s44, 2
	s_add_i32 s7, s91, s44
	s_add_i32 s7, s7, 1
	s_add_i32 s0, s44, 1
	s_cmp_lt_i32 s0, s90
	s_cbranch_scc0 .Lt1_d2_nostage
	s_cmp_lt_u32 s0, s89
	s_cselect_b32 s0, s71, s75
	s_cselect_b32 s1, s72, s76
	s_cselect_b32 s4, s73, s77
	s_cselect_b32 s5, s74, s78
	s_cselect_b32 s6, s6, s7
	s_ashr_i32 s7, s6, 31
	s_lshl_b64 s[6:7], s[6:7], 14
	s_add_u32 s6, s6, s58
	s_addc_u32 s7, s7, s59
	s_add_u32 s0, s0, s6
	s_addc_u32 s1, s1, s7
	s_add_u32 s4, s4, s6
	s_addc_u32 s5, s5, s7
	global_load_dwordx4 v[96:99], v248, s[0:1]
	global_load_dwordx4 v[100:103], v249, s[0:1]
	global_load_dwordx4 v[104:107], v248, s[4:5]
	global_load_dwordx4 v[108:111], v249, s[4:5]
; #define LAS __attribute__((address_space(3)))
; #define MFMA32(a, b, c) __builtin_amdgcn_mfma_f32_32x32x16_bf16((a), (b), (c), 0, 0, 0)
; __device__ __forceinline__ float ex2(float x) { return __builtin_amdgcn_exp2f(x); }
; template <int MODE>
; __device__ __forceinline__ void attn_tile(const LAS unsigned char* Kb, const LAS unsigned char* Vb, const bf16x8_t (&qf)[4], f32x16 (&oacc)[2], float& l_run,
;                                           int r, int h, int dlt0, int dlt1, bool hiw) {
;     ...
; #pragma unroll
;     for (int mt = 0; mt < 4; ++mt) {
;         if (mt == 0) { if (hiw) __builtin_amdgcn_s_setprio(1); else __builtin_amdgcn_s_setprio(0); }
;         if (mt == 2) { if (hiw) __builtin_amdgcn_s_setprio(0); else __builtin_amdgcn_s_setprio(1); }
;         const int dl = mt < 2 ? dlt0 : dlt1;
;         f32x16 sacc = zero16();
; #pragma unroll
;         for (int ks = 0; ks < 4; ++ks) { const bf16x8_t ka = *(const LAS bf16x8_t*)(Kb + (32 * mt + r) * A_KSTR + 32 * ks + 16 * h); sacc = MFMA32(ka, qf[ks], sacc); }
; #pragma unroll
;         for (int i = 0; i < 16; ++i) {
;             float p;
;             if (MODE == 2) p = ex2(sacc[i]);
;             else if (MODE == 3) p = ex2(sacc[i] + __int_as_float(dl));
;             else { const int ci = 32 * mt + (i & 3) + 8 * (i >> 2); p = ((unsigned)(dl - ci) < ulim) ? ex2(sacc[i]) : 0.f; }
;             sacc[i] = p; ls += p;
;         }
; #pragma unroll
;         for (int s = 0; s < 2; ++s) {
;             const bf16x8_t pf = pack8(sacc, 8 * s);
; #pragma unroll
;             for (int dt = 0; dt < 2; ++dt) {
;                 const LAS unsigned char* vp = Vb + (32 * dt + r) * A_CVSTR + (32 * mt + 16 * s + 4 * h) * 2;
;                 const s16x4_t lo = *(const LAS s16x4_t*)vp, hi = *(const LAS s16x4_t*)(vp + 16);
;                 oacc[dt] = MFMA32(__builtin_shufflevector(lo, hi, 0, 1, 2, 3, 4, 5, 6, 7), pf, oacc[dt]);
;             }
;         }
;     }
;     l_run += ls;
.Lt1_d2_nostage:
	s_waitcnt lgkmcnt(5)
	v_mfma_f32_32x32x16_bf16 v[32:47], v[208:211], v[88:91], v[32:47]
	v_exp_f32_e32 v56, v56
	v_exp_f32_e32 v57, v57
	s_waitcnt lgkmcnt(4)
	v_mfma_f32_32x32x16_bf16 v[32:47], v[212:215], v[92:95], v[32:47]
	v_exp_f32_e32 v58, v58
	v_exp_f32_e32 v59, v59
	v_add_f32_e32 v232, v232, v56
	v_add_f32_e32 v233, v233, v57
	v_cvt_pk_bf16_f32 v68, v56, v57
	s_waitcnt lgkmcnt(3)
	v_mfma_f32_32x32x16_bf16 v[0:15], v[216:219], v[64:67], v[0:15]
	ds_read2_b64 v[216:219], v73 offset0:16 offset1:18
	v_exp_f32_e32 v60, v60
	v_exp_f32_e32 v61, v61
	v_add_f32_e32 v232, v232, v58
	v_add_f32_e32 v233, v233, v59
	v_cvt_pk_bf16_f32 v69, v58, v59
	s_waitcnt lgkmcnt(3)
	v_mfma_f32_32x32x16_bf16 v[16:31], v[220:223], v[64:67], v[16:31]
	ds_read2_b64 v[220:223], v74 offset0:48 offset1:50
	v_exp_f32_e32 v62, v62
	v_exp_f32_e32 v63, v63
	v_add_f32_e32 v232, v232, v60
	v_add_f32_e32 v233, v233, v61
	v_cvt_pk_bf16_f32 v70, v60, v61
	v_add_f32_e32 v232, v232, v62
	v_add_f32_e32 v233, v233, v63
	v_cvt_pk_bf16_f32 v71, v62, v63
	v_cmp_le_i32_e64 s[0:1], 0, v250
	v_cmp_le_i32_e64 s[4:5], 1, v250
	v_exp_f32_e32 v32, v32
	v_exp_f32_e32 v33, v33
	v_cmp_le_i32_e64 s[6:7], 2, v250
	v_cmp_le_i32_e64 s[48:49], 3, v250
	v_exp_f32_e32 v34, v34
	v_exp_f32_e32 v35, v35
	v_cndmask_b32_e64 v32, 0, v32, s[0:1]
	v_cndmask_b32_e64 v33, 0, v33, s[4:5]
	v_add_f32_e32 v232, v232, v32
	v_add_f32_e32 v233, v233, v33
	v_cvt_pk_bf16_f32 v64, v32, v33
	s_waitcnt lgkmcnt(3)
	v_mfma_f32_32x32x16_bf16 v[0:15], v[224:227], v[68:71], v[0:15]
	ds_read2_b64 v[224:227], v73 offset0:20 offset1:22
	v_cmp_le_i32_e64 s[0:1], 8, v250
	v_cmp_le_i32_e64 s[4:5], 9, v250
	v_exp_f32_e32 v36, v36
	v_exp_f32_e32 v37, v37
	v_cndmask_b32_e64 v34, 0, v34, s[6:7]
	v_cndmask_b32_e64 v35, 0, v35, s[48:49]
	v_add_f32_e32 v232, v232, v34
	v_add_f32_e32 v233, v233, v35
	v_cvt_pk_bf16_f32 v65, v34, v35
	s_waitcnt lgkmcnt(3)
	v_mfma_f32_32x32x16_bf16 v[16:31], v[228:231], v[68:71], v[16:31]
	ds_read2_b64 v[228:231], v74 offset0:52 offset1:54
	v_cmp_le_i32_e64 s[6:7], 10, v250
	v_cmp_le_i32_e64 s[48:49], 11, v250
	v_exp_f32_e32 v38, v38
	v_exp_f32_e32 v39, v39
	v_cndmask_b32_e64 v36, 0, v36, s[0:1]
	v_cndmask_b32_e64 v37, 0, v37, s[4:5]
	v_add_f32_e32 v232, v232, v36
	v_add_f32_e32 v233, v233, v37
	v_cvt_pk_bf16_f32 v66, v36, v37
	v_cndmask_b32_e64 v38, 0, v38, s[6:7]
	v_cndmask_b32_e64 v39, 0, v39, s[48:49]
	v_add_f32_e32 v232, v232, v38
	v_add_f32_e32 v233, v233, v39
	v_cvt_pk_bf16_f32 v67, v38, v39
	v_cmp_le_i32_e64 s[0:1], 16, v250
	v_cmp_le_i32_e64 s[4:5], 17, v250
	v_exp_f32_e32 v40, v40
	v_exp_f32_e32 v41, v41
	v_cmp_le_i32_e64 s[6:7], 18, v250
	v_cmp_le_i32_e64 s[48:49], 19, v250
	v_exp_f32_e32 v42, v42
	v_exp_f32_e32 v43, v43
	v_cndmask_b32_e64 v40, 0, v40, s[0:1]
	v_cndmask_b32_e64 v41, 0, v41, s[4:5]
	v_add_f32_e32 v232, v232, v40
	v_add_f32_e32 v233, v233, v41
	v_cvt_pk_bf16_f32 v68, v40, v41
	s_waitcnt lgkmcnt(3)
	v_mfma_f32_32x32x16_bf16 v[0:15], v[216:219], v[64:67], v[0:15]
	v_cmp_le_i32_e64 s[0:1], 24, v250
	v_cmp_le_i32_e64 s[4:5], 25, v250
	v_exp_f32_e32 v44, v44
	v_exp_f32_e32 v45, v45
	v_cndmask_b32_e64 v42, 0, v42, s[6:7]
	v_cndmask_b32_e64 v43, 0, v43, s[48:49]
	v_add_f32_e32 v232, v232, v42
	v_add_f32_e32 v233, v233, v43
	v_cvt_pk_bf16_f32 v69, v42, v43
	s_waitcnt lgkmcnt(2)
	v_mfma_f32_32x32x16_bf16 v[16:31], v[220:223], v[64:67], v[16:31]
	v_cmp_le_i32_e64 s[6:7], 26, v250
	v_cmp_le_i32_e64 s[48:49], 27, v250
	v_exp_f32_e32 v46, v46
	v_exp_f32_e32 v47, v47
	v_cndmask_b32_e64 v44, 0, v44, s[0:1]
	v_cndmask_b32_e64 v45, 0, v45, s[4:5]
	v_add_f32_e32 v232, v232, v44
	v_add_f32_e32 v233, v233, v45
	v_cvt_pk_bf16_f32 v70, v44, v45
	v_cndmask_b32_e64 v46, 0, v46, s[6:7]
	v_cndmask_b32_e64 v47, 0, v47, s[48:49]
	v_add_f32_e32 v232, v232, v46
	v_add_f32_e32 v233, v233, v47
	v_cvt_pk_bf16_f32 v71, v46, v47
	s_nop 1
	s_waitcnt lgkmcnt(1)
	v_mfma_f32_32x32x16_bf16 v[0:15], v[224:227], v[68:71], v[0:15]
	s_waitcnt lgkmcnt(0)
	v_mfma_f32_32x32x16_bf16 v[16:31], v[228:231], v[68:71], v[16:31]
	v_add_f32_e32 v232, v232, v233
	v_add_f32_e32 v112, v112, v232
	s_branch .Lt1_join

; #define LAS __attribute__((address_space(3)))
; #define MFMA32(a, b, c) __builtin_amdgcn_mfma_f32_32x32x16_bf16((a), (b), (c), 0, 0, 0)
; __device__ __forceinline__ float ex2(float x) { return __builtin_amdgcn_exp2f(x); }
; template <int MODE>
; __device__ __forceinline__ void attn_tile(const LAS unsigned char* Kb, const LAS unsigned char* Vb, const bf16x8_t (&qf)[4], f32x16 (&oacc)[2], float& l_run,
;                                           int r, int h, int dlt0, int dlt1, bool hiw) {
;     ...
; #pragma unroll
;     for (int mt = 0; mt < 4; ++mt) {
;         if (mt == 0) { if (hiw) __builtin_amdgcn_s_setprio(1); else __builtin_amdgcn_s_setprio(0); }
;         if (mt == 2) { if (hiw) __builtin_amdgcn_s_setprio(0); else __builtin_amdgcn_s_setprio(1); }
;         const int dl = mt < 2 ? dlt0 : dlt1;
;         f32x16 sacc = zero16();
; #pragma unroll
;         for (int ks = 0; ks < 4; ++ks) { const bf16x8_t ka = *(const LAS bf16x8_t*)(Kb + (32 * mt + r) * A_KSTR + 32 * ks + 16 * h); sacc = MFMA32(ka, qf[ks], sacc); }
; #pragma unroll
;         for (int i = 0; i < 16; ++i) {
;             float p;
;             if (MODE == 2) p = ex2(sacc[i]);
;             else if (MODE == 3) p = ex2(sacc[i] + __int_as_float(dl));
;             else { const int ci = 32 * mt + (i & 3) + 8 * (i >> 2); p = ((unsigned)(dl - ci) < ulim) ? ex2(sacc[i]) : 0.f; }
;             sacc[i] = p; ls += p;
;         }
; #pragma unroll
;         for (int s = 0; s < 2; ++s) {
;             const bf16x8_t pf = pack8(sacc, 8 * s);
; #pragma unroll
;             for (int dt = 0; dt < 2; ++dt) {
;                 const LAS unsigned char* vp = Vb + (32 * dt + r) * A_CVSTR + (32 * mt + 16 * s + 4 * h) * 2;
;                 const s16x4_t lo = *(const LAS s16x4_t*)vp, hi = *(const LAS s16x4_t*)(vp + 16);
;                 oacc[dt] = MFMA32(__builtin_shufflevector(lo, hi, 0, 1, 2, 3, 4, 5, 6, 7), pf, oacc[dt]);
;             }
;         }
;     }
;     l_run += ls;
.Lt1_d3_nostage:
	s_waitcnt lgkmcnt(5)
	v_mfma_f32_32x32x16_bf16 v[48:63], v[208:211], v[88:91], v[48:63]
	v_exp_f32_e32 v40, v40
	v_exp_f32_e32 v41, v41
	s_waitcnt lgkmcnt(4)
	v_mfma_f32_32x32x16_bf16 v[48:63], v[212:215], v[92:95], v[48:63]
	v_exp_f32_e32 v42, v42
	v_exp_f32_e32 v43, v43
	v_add_f32_e32 v232, v232, v40
	v_add_f32_e32 v233, v233, v41
	v_cvt_pk_bf16_f32 v68, v40, v41
	s_waitcnt lgkmcnt(3)
	v_mfma_f32_32x32x16_bf16 v[0:15], v[216:219], v[64:67], v[0:15]
	ds_read2_b64 v[216:219], v73 offset0:24 offset1:26
	v_exp_f32_e32 v44, v44
	v_exp_f32_e32 v45, v45
	v_add_f32_e32 v232, v232, v42
	v_add_f32_e32 v233, v233, v43
	v_cvt_pk_bf16_f32 v69, v42, v43
	s_waitcnt lgkmcnt(3)
	v_mfma_f32_32x32x16_bf16 v[16:31], v[220:223], v[64:67], v[16:31]
	ds_read2_b64 v[220:223], v74 offset0:56 offset1:58
	v_exp_f32_e32 v46, v46
	v_exp_f32_e32 v47, v47
	v_add_f32_e32 v232, v232, v44
	v_add_f32_e32 v233, v233, v45
	v_cvt_pk_bf16_f32 v70, v44, v45
	v_add_f32_e32 v232, v232, v46
	v_add_f32_e32 v233, v233, v47
	v_cvt_pk_bf16_f32 v71, v46, v47
	v_cmp_le_i32_e64 s[0:1], 0, v250
	v_cmp_le_i32_e64 s[4:5], 1, v250
	v_exp_f32_e32 v48, v48
	v_exp_f32_e32 v49, v49
	v_cmp_le_i32_e64 s[6:7], 2, v250
	v_cmp_le_i32_e64 s[48:49], 3, v250
	v_exp_f32_e32 v50, v50
	v_exp_f32_e32 v51, v51
	v_cndmask_b32_e64 v48, 0, v48, s[0:1]
	v_cndmask_b32_e64 v49, 0, v49, s[4:5]
	v_add_f32_e32 v232, v232, v48
	v_add_f32_e32 v233, v233, v49
	v_cvt_pk_bf16_f32 v64, v48, v49
	s_waitcnt lgkmcnt(3)
	v_mfma_f32_32x32x16_bf16 v[0:15], v[224:227], v[68:71], v[0:15]
	ds_read2_b64 v[224:227], v73 offset0:28 offset1:30
	v_cmp_le_i32_e64 s[0:1], 8, v250
	v_cmp_le_i32_e64 s[4:5], 9, v250
	v_exp_f32_e32 v52, v52
	v_exp_f32_e32 v53, v53
	v_cndmask_b32_e64 v50, 0, v50, s[6:7]
	v_cndmask_b32_e64 v51, 0, v51, s[48:49]
	v_add_f32_e32 v232, v232, v50
	v_add_f32_e32 v233, v233, v51
	v_cvt_pk_bf16_f32 v65, v50, v51
	s_waitcnt lgkmcnt(3)
	v_mfma_f32_32x32x16_bf16 v[16:31], v[228:231], v[68:71], v[16:31]
	ds_read2_b64 v[228:231], v74 offset0:60 offset1:62
	v_cmp_le_i32_e64 s[6:7], 10, v250
	v_cmp_le_i32_e64 s[48:49], 11, v250
	v_exp_f32_e32 v54, v54
	v_exp_f32_e32 v55, v55
	v_cndmask_b32_e64 v52, 0, v52, s[0:1]
	v_cndmask_b32_e64 v53, 0, v53, s[4:5]
	v_add_f32_e32 v232, v232, v52
	v_add_f32_e32 v233, v233, v53
	v_cvt_pk_bf16_f32 v66, v52, v53
	v_cndmask_b32_e64 v54, 0, v54, s[6:7]
	v_cndmask_b32_e64 v55, 0, v55, s[48:49]
	v_add_f32_e32 v232, v232, v54
	v_add_f32_e32 v233, v233, v55
	v_cvt_pk_bf16_f32 v67, v54, v55
	v_cmp_le_i32_e64 s[0:1], 16, v250
	v_cmp_le_i32_e64 s[4:5], 17, v250
	v_exp_f32_e32 v56, v56
	v_exp_f32_e32 v57, v57
	v_cmp_le_i32_e64 s[6:7], 18, v250
	v_cmp_le_i32_e64 s[48:49], 19, v250
	v_exp_f32_e32 v58, v58
	v_exp_f32_e32 v59, v59
	v_cndmask_b32_e64 v56, 0, v56, s[0:1]
	v_cndmask_b32_e64 v57, 0, v57, s[4:5]
	v_add_f32_e32 v232, v232, v56
	v_add_f32_e32 v233, v233, v57
	v_cvt_pk_bf16_f32 v68, v56, v57
	s_waitcnt lgkmcnt(3)
	v_mfma_f32_32x32x16_bf16 v[0:15], v[216:219], v[64:67], v[0:15]
	v_cmp_le_i32_e64 s[0:1], 24, v250
	v_cmp_le_i32_e64 s[4:5], 25, v250
	v_exp_f32_e32 v60, v60
	v_exp_f32_e32 v61, v61
	v_cndmask_b32_e64 v58, 0, v58, s[6:7]
	v_cndmask_b32_e64 v59, 0, v59, s[48:49]
	v_add_f32_e32 v232, v232, v58
	v_add_f32_e32 v233, v233, v59
	v_cvt_pk_bf16_f32 v69, v58, v59
	s_waitcnt lgkmcnt(2)
	v_mfma_f32_32x32x16_bf16 v[16:31], v[220:223], v[64:67], v[16:31]
	v_cmp_le_i32_e64 s[6:7], 26, v250
	v_cmp_le_i32_e64 s[48:49], 27, v250
	v_exp_f32_e32 v62, v62
	v_exp_f32_e32 v63, v63
	v_cndmask_b32_e64 v60, 0, v60, s[0:1]
	v_cndmask_b32_e64 v61, 0, v61, s[4:5]
	v_add_f32_e32 v232, v232, v60
	v_add_f32_e32 v233, v233, v61
	v_cvt_pk_bf16_f32 v70, v60, v61
	v_cndmask_b32_e64 v62, 0, v62, s[6:7]
	v_cndmask_b32_e64 v63, 0, v63, s[48:49]
	v_add_f32_e32 v232, v232, v62
	v_add_f32_e32 v233, v233, v63
	v_cvt_pk_bf16_f32 v71, v62, v63
	s_nop 1
	s_waitcnt lgkmcnt(1)
	v_mfma_f32_32x32x16_bf16 v[0:15], v[224:227], v[68:71], v[0:15]
	s_waitcnt lgkmcnt(0)
	v_mfma_f32_32x32x16_bf16 v[16:31], v[228:231], v[68:71], v[16:31]
	v_add_f32_e32 v232, v232, v233
	v_add_f32_e32 v112, v112, v232
	s_branch .Lt1_join
.Lt1_e0:
	ds_read_b128 v[200:203], v72 offset:0
	ds_read_b128 v[204:207], v72 offset:32
	ds_read_b128 v[208:211], v72 offset:64
	ds_read_b128 v[212:215], v72 offset:96
	ds_read2_b64 v[216:219], v73 offset0:0 offset1:2
	ds_read2_b64 v[220:223], v74 offset0:32 offset1:34
	ds_read2_b64 v[224:227], v73 offset0:4 offset1:6
	ds_read2_b64 v[228:231], v74 offset0:36 offset1:38
	s_waitcnt lgkmcnt(7)
	v_mfma_f32_32x32x16_bf16 v[32:47], v[200:203], v[80:83], 0
	ds_read_b128 v[200:203], v72 offset:4608
	s_waitcnt lgkmcnt(7)
	v_mfma_f32_32x32x16_bf16 v[32:47], v[204:207], v[84:87], v[32:47]
	ds_read_b128 v[204:207], v72 offset:4640
	s_waitcnt lgkmcnt(7)
	v_mfma_f32_32x32x16_bf16 v[32:47], v[208:211], v[88:91], v[32:47]
	ds_read_b128 v[208:211], v72 offset:4672
	s_waitcnt lgkmcnt(7)
	v_mfma_f32_32x32x16_bf16 v[32:47], v[212:215], v[92:95], v[32:47]
	ds_read_b128 v[212:215], v72 offset:4704
	s_nop 7
	s_nop 3
	s_waitcnt lgkmcnt(3)
	v_mfma_f32_32x32x16_bf16 v[48:63], v[200:203], v[80:83], 0
	ds_read_b128 v[200:203], v72 offset:9216
	v_cmp_le_i32_e64 s[0:1], 0, v250
	v_cmp_le_i32_e64 s[4:5], 1, v250
	v_exp_f32_e32 v32, v32
	v_exp_f32_e32 v33, v33
	s_waitcnt lgkmcnt(3)
; #define LAS __attribute__((address_space(3)))
; #define MFMA32(a, b, c) __builtin_amdgcn_mfma_f32_32x32x16_bf16((a), (b), (c), 0, 0, 0)
; __device__ __forceinline__ float ex2(float x) { return __builtin_amdgcn_exp2f(x); }
; template <int MODE>
; __device__ __forceinline__ void attn_tile(const LAS unsigned char* Kb, const LAS unsigned char* Vb, const bf16x8_t (&qf)[4], f32x16 (&oacc)[2], float& l_run,
;                                           int r, int h, int dlt0, int dlt1, bool hiw) {
;     ...
; #pragma unroll
;     for (int mt = 0; mt < 4; ++mt) {
;         if (mt == 0) { if (hiw) __builtin_amdgcn_s_setprio(1); else __builtin_amdgcn_s_setprio(0); }
;         if (mt == 2) { if (hiw) __builtin_amdgcn_s_setprio(0); else __builtin_amdgcn_s_setprio(1); }
;         const int dl = mt < 2 ? dlt0 : dlt1;
;         f32x16 sacc = zero16();
; #pragma unroll
;         for (int ks = 0; ks < 4; ++ks) { const bf16x8_t ka = *(const LAS bf16x8_t*)(Kb + (32 * mt + r) * A_KSTR + 32 * ks + 16 * h); sacc = MFMA32(ka, qf[ks], sacc); }
; #pragma unroll
;         for (int i = 0; i < 16; ++i) {
;             float p;
;             if (MODE == 2) p = ex2(sacc[i]);
;             else if (MODE == 3) p = ex2(sacc[i] + __int_as_float(dl));
;             else { const int ci = 32 * mt + (i & 3) + 8 * (i >> 2); p = ((unsigned)(dl - ci) < ulim) ? ex2(sacc[i]) : 0.f; }
;             sacc[i] = p; ls += p;
;         }
; #pragma unroll
;         for (int s = 0; s < 2; ++s) {
;             const bf16x8_t pf = pack8(sacc, 8 * s);
; #pragma unroll
;             for (int dt = 0; dt < 2; ++dt) {
;                 const LAS unsigned char* vp = Vb + (32 * dt + r) * A_CVSTR + (32 * mt + 16 * s + 4 * h) * 2;
;                 const s16x4_t lo = *(const LAS s16x4_t*)vp, hi = *(const LAS s16x4_t*)(vp + 16);
;                 oacc[dt] = MFMA32(__builtin_shufflevector(lo, hi, 0, 1, 2, 3, 4, 5, 6, 7), pf, oacc[dt]);
;             }
;         }
;     }
;     l_run += ls;
	v_mfma_f32_32x32x16_bf16 v[48:63], v[204:207], v[84:87], v[48:63]
	ds_read_b128 v[204:207], v72 offset:9248
	v_cmp_le_i32_e64 s[6:7], 2, v250
	v_cmp_le_i32_e64 s[48:49], 3, v250
	v_exp_f32_e32 v34, v34
	v_exp_f32_e32 v35, v35
	v_cndmask_b32_e64 v32, v32, 0, s[0:1]
	v_cndmask_b32_e64 v33, v33, 0, s[4:5]
	v_mov_b32_e32 v232, v32
	v_mov_b32_e32 v233, v33
	v_cvt_pk_bf16_f32 v64, v32, v33
	v_cmp_le_i32_e64 s[0:1], 8, v250
	v_cmp_le_i32_e64 s[4:5], 9, v250
	v_exp_f32_e32 v36, v36
	v_exp_f32_e32 v37, v37
	v_cndmask_b32_e64 v34, v34, 0, s[6:7]
	v_cndmask_b32_e64 v35, v35, 0, s[48:49]
	v_add_f32_e32 v232, v232, v34
	v_add_f32_e32 v233, v233, v35
	v_cvt_pk_bf16_f32 v65, v34, v35
	v_cmp_le_i32_e64 s[6:7], 10, v250
	v_cmp_le_i32_e64 s[48:49], 11, v250
	v_exp_f32_e32 v38, v38
	v_exp_f32_e32 v39, v39
	v_cndmask_b32_e64 v36, v36, 0, s[0:1]
	v_cndmask_b32_e64 v37, v37, 0, s[4:5]
	v_add_f32_e32 v232, v232, v36
	v_add_f32_e32 v233, v233, v37
	v_cvt_pk_bf16_f32 v66, v36, v37
	v_cndmask_b32_e64 v38, v38, 0, s[6:7]
	v_cndmask_b32_e64 v39, v39, 0, s[48:49]
	v_add_f32_e32 v232, v232, v38
	v_add_f32_e32 v233, v233, v39
	v_cvt_pk_bf16_f32 v67, v38, v39
	s_waitcnt lgkmcnt(3)
	v_mfma_f32_32x32x16_bf16 v[48:63], v[208:211], v[88:91], v[48:63]
	ds_read_b128 v[208:211], v72 offset:9280
	v_cmp_le_i32_e64 s[0:1], 16, v250
	v_cmp_le_i32_e64 s[4:5], 17, v250
	v_exp_f32_e32 v40, v40
	v_exp_f32_e32 v41, v41
	s_waitcnt lgkmcnt(3)
	v_mfma_f32_32x32x16_bf16 v[48:63], v[212:215], v[92:95], v[48:63]
	ds_read_b128 v[212:215], v72 offset:9312
	v_cmp_le_i32_e64 s[6:7], 18, v250
	v_cmp_le_i32_e64 s[48:49], 19, v250
	v_exp_f32_e32 v42, v42
	v_exp_f32_e32 v43, v43
	v_cndmask_b32_e64 v40, v40, 0, s[0:1]
	v_cndmask_b32_e64 v41, v41, 0, s[4:5]
	v_add_f32_e32 v232, v232, v40
	v_add_f32_e32 v233, v233, v41
	v_cvt_pk_bf16_f32 v68, v40, v41
	v_mfma_f32_32x32x16_bf16 v[0:15], v[216:219], v[64:67], v[0:15]
	ds_read2_b64 v[216:219], v73 offset0:8 offset1:10
	v_cmp_le_i32_e64 s[0:1], 24, v250
	v_cmp_le_i32_e64 s[4:5], 25, v250
	v_exp_f32_e32 v44, v44
	v_exp_f32_e32 v45, v45
	v_cndmask_b32_e64 v42, v42, 0, s[6:7]
	v_cndmask_b32_e64 v43, v43, 0, s[48:49]
	v_add_f32_e32 v232, v232, v42
	v_add_f32_e32 v233, v233, v43
	v_cvt_pk_bf16_f32 v69, v42, v43
	v_mfma_f32_32x32x16_bf16 v[16:31], v[220:223], v[64:67], v[16:31]
	ds_read2_b64 v[220:223], v74 offset0:40 offset1:42
	v_cmp_le_i32_e64 s[6:7], 26, v250
	v_cmp_le_i32_e64 s[48:49], 27, v250
	v_exp_f32_e32 v46, v46
	v_exp_f32_e32 v47, v47
	v_cndmask_b32_e64 v44, v44, 0, s[0:1]
	v_cndmask_b32_e64 v45, v45, 0, s[4:5]
	v_add_f32_e32 v232, v232, v44
	v_add_f32_e32 v233, v233, v45
	v_cvt_pk_bf16_f32 v70, v44, v45
	v_cndmask_b32_e64 v46, v46, 0, s[6:7]
	v_cndmask_b32_e64 v47, v47, 0, s[48:49]
	v_add_f32_e32 v232, v232, v46
	v_add_f32_e32 v233, v233, v47
	v_cvt_pk_bf16_f32 v71, v46, v47
	s_waitcnt lgkmcnt(5)
	v_mfma_f32_32x32x16_bf16 v[32:47], v[200:203], v[80:83], 0
	ds_read_b128 v[200:203], v72 offset:13824
	v_exp_f32_e32 v48, v48
	v_exp_f32_e32 v49, v49
	s_waitcnt lgkmcnt(5)
	v_mfma_f32_32x32x16_bf16 v[32:47], v[204:207], v[84:87], v[32:47]
	ds_read_b128 v[204:207], v72 offset:13856
	v_exp_f32_e32 v50, v50
	v_exp_f32_e32 v51, v51
	v_add_f32_e32 v232, v232, v48
	v_add_f32_e32 v233, v233, v49
	v_cvt_pk_bf16_f32 v64, v48, v49
	v_mfma_f32_32x32x16_bf16 v[0:15], v[224:227], v[68:71], v[0:15]
	ds_read2_b64 v[224:227], v73 offset0:12 offset1:14
	v_exp_f32_e32 v52, v52
	v_exp_f32_e32 v53, v53
	v_add_f32_e32 v232, v232, v50
	v_add_f32_e32 v233, v233, v51
	v_cvt_pk_bf16_f32 v65, v50, v51
	v_mfma_f32_32x32x16_bf16 v[16:31], v[228:231], v[68:71], v[16:31]
	ds_read2_b64 v[228:231], v74 offset0:44 offset1:46
	v_exp_f32_e32 v54, v54
	v_exp_f32_e32 v55, v55
	v_add_f32_e32 v232, v232, v52
	v_add_f32_e32 v233, v233, v53
	v_cvt_pk_bf16_f32 v66, v52, v53
	v_add_f32_e32 v232, v232, v54
	v_add_f32_e32 v233, v233, v55
	v_cvt_pk_bf16_f32 v67, v54, v55
	s_waitcnt lgkmcnt(7)
	v_mfma_f32_32x32x16_bf16 v[32:47], v[208:211], v[88:91], v[32:47]
	ds_read_b128 v[208:211], v72 offset:13888
	v_exp_f32_e32 v56, v56
	v_exp_f32_e32 v57, v57
	s_waitcnt lgkmcnt(7)
	v_mfma_f32_32x32x16_bf16 v[32:47], v[212:215], v[92:95], v[32:47]
	ds_read_b128 v[212:215], v72 offset:13920
	v_exp_f32_e32 v58, v58
	v_exp_f32_e32 v59, v59
	v_add_f32_e32 v232, v232, v56
	v_add_f32_e32 v233, v233, v57
	v_cvt_pk_bf16_f32 v68, v56, v57
	s_waitcnt lgkmcnt(7)
	v_mfma_f32_32x32x16_bf16 v[0:15], v[216:219], v[64:67], v[0:15]
	ds_read2_b64 v[216:219], v73 offset0:16 offset1:18
	v_exp_f32_e32 v60, v60
	v_exp_f32_e32 v61, v61
	v_add_f32_e32 v232, v232, v58
	v_add_f32_e32 v233, v233, v59
	v_cvt_pk_bf16_f32 v69, v58, v59
	s_waitcnt lgkmcnt(7)
	v_mfma_f32_32x32x16_bf16 v[16:31], v[220:223], v[64:67], v[16:31]
	ds_read2_b64 v[220:223], v74 offset0:48 offset1:50
	v_exp_f32_e32 v62, v62
	v_exp_f32_e32 v63, v63
	v_add_f32_e32 v232, v232, v60
	v_add_f32_e32 v233, v233, v61
	v_cvt_pk_bf16_f32 v70, v60, v61
	v_add_f32_e32 v232, v232, v62
	v_add_f32_e32 v233, v233, v63
	v_cvt_pk_bf16_f32 v71, v62, v63
	s_waitcnt lgkmcnt(7)
	v_mfma_f32_32x32x16_bf16 v[48:63], v[200:203], v[80:83], 0
	v_exp_f32_e32 v32, v32
	v_exp_f32_e32 v33, v33
	s_waitcnt lgkmcnt(6)
	v_mfma_f32_32x32x16_bf16 v[48:63], v[204:207], v[84:87], v[48:63]
	v_exp_f32_e32 v34, v34
	v_exp_f32_e32 v35, v35
	v_add_f32_e32 v232, v232, v32
	v_add_f32_e32 v233, v233, v33
	v_cvt_pk_bf16_f32 v64, v32, v33
	s_waitcnt lgkmcnt(5)
	v_mfma_f32_32x32x16_bf16 v[0:15], v[224:227], v[68:71], v[0:15]
	ds_read2_b64 v[224:227], v73 offset0:20 offset1:22
	v_exp_f32_e32 v36, v36
	v_exp_f32_e32 v37, v37
	v_add_f32_e32 v232, v232, v34
	v_add_f32_e32 v233, v233, v35
	v_cvt_pk_bf16_f32 v65, v34, v35
	s_waitcnt lgkmcnt(5)
	v_mfma_f32_32x32x16_bf16 v[16:31], v[228:231], v[68:71], v[16:31]
	ds_read2_b64 v[228:231], v74 offset0:52 offset1:54
	v_exp_f32_e32 v38, v38
	v_exp_f32_e32 v39, v39
	v_add_f32_e32 v232, v232, v36
	v_add_f32_e32 v233, v233, v37
	v_cvt_pk_bf16_f32 v66, v36, v37
	v_add_f32_e32 v232, v232, v38
	v_add_f32_e32 v233, v233, v39
	v_cvt_pk_bf16_f32 v67, v38, v39
	s_cmp_eq_u32 s45, 0
	s_cbranch_scc1 .Lt1_e0_nostage
	s_waitcnt vmcnt(3)
	ds_write_b128 v251, v[96:99]
	s_waitcnt vmcnt(2)
	ds_write_b128 v251, v[100:103] offset:9216
	s_waitcnt vmcnt(1)
	ds_write2_b64 v252, v[104:105], v[106:107] offset1:1
	s_waitcnt vmcnt(0)
	ds_write2_b64 v252, v[108:109], v[110:111] offset0:16 offset1:17
	s_mov_b32 s47, 1
	s_add_i32 s6, s44, 2
	s_add_i32 s7, s91, s44
	s_add_i32 s7, s7, 1
	s_add_i32 s0, s44, 1
	s_cmp_lt_i32 s0, s90
	s_cbranch_scc0 .Lt1_e0_nostage
	s_cmp_lt_u32 s0, s89
	s_cselect_b32 s0, s71, s75
	s_cselect_b32 s1, s72, s76
	s_cselect_b32 s4, s73, s77
	s_cselect_b32 s5, s74, s78
	s_cselect_b32 s6, s6, s7
	s_ashr_i32 s7, s6, 31
	s_lshl_b64 s[6:7], s[6:7], 14
	s_add_u32 s6, s6, s58
	s_addc_u32 s7, s7, s59
	s_add_u32 s0, s0, s6
	s_addc_u32 s1, s1, s7
	s_add_u32 s4, s4, s6
	s_addc_u32 s5, s5, s7
	global_load_dwordx4 v[96:99], v248, s[0:1]
	global_load_dwordx4 v[100:103], v249, s[0:1]
	global_load_dwordx4 v[104:107], v248, s[4:5]
	global_load_dwordx4 v[108:111], v249, s[4:5]

; #define LAS __attribute__((address_space(3)))
; #define MFMA32(a, b, c) __builtin_amdgcn_mfma_f32_32x32x16_bf16((a), (b), (c), 0, 0, 0)
; __device__ __forceinline__ float ex2(float x) { return __builtin_amdgcn_exp2f(x); }
; template <int MODE>
; __device__ __forceinline__ void attn_tile(const LAS unsigned char* Kb, const LAS unsigned char* Vb, const bf16x8_t (&qf)[4], f32x16 (&oacc)[2], float& l_run,
;                                           int r, int h, int dlt0, int dlt1, bool hiw) {
;     ...
; #pragma unroll
;     for (int mt = 0; mt < 4; ++mt) {
;         if (mt == 0) { if (hiw) __builtin_amdgcn_s_setprio(1); else __builtin_amdgcn_s_setprio(0); }
;         if (mt == 2) { if (hiw) __builtin_amdgcn_s_setprio(0); else __builtin_amdgcn_s_setprio(1); }
;         const int dl = mt < 2 ? dlt0 : dlt1;
;         f32x16 sacc = zero16();
; #pragma unroll
;         for (int ks = 0; ks < 4; ++ks) { const bf16x8_t ka = *(const LAS bf16x8_t*)(Kb + (32 * mt + r) * A_KSTR + 32 * ks + 16 * h); sacc = MFMA32(ka, qf[ks], sacc); }
; #pragma unroll
;         for (int i = 0; i < 16; ++i) {
;             float p;
;             if (MODE == 2) p = ex2(sacc[i]);
;             else if (MODE == 3) p = ex2(sacc[i] + __int_as_float(dl));
;             else { const int ci = 32 * mt + (i & 3) + 8 * (i >> 2); p = ((unsigned)(dl - ci) < ulim) ? ex2(sacc[i]) : 0.f; }
;             sacc[i] = p; ls += p;
;         }
; #pragma unroll
;         for (int s = 0; s < 2; ++s) {
;             const bf16x8_t pf = pack8(sacc, 8 * s);
; #pragma unroll
;             for (int dt = 0; dt < 2; ++dt) {
;                 const LAS unsigned char* vp = Vb + (32 * dt + r) * A_CVSTR + (32 * mt + 16 * s + 4 * h) * 2;
;                 const s16x4_t lo = *(const LAS s16x4_t*)vp, hi = *(const LAS s16x4_t*)(vp + 16);
;                 oacc[dt] = MFMA32(__builtin_shufflevector(lo, hi, 0, 1, 2, 3, 4, 5, 6, 7), pf, oacc[dt]);
;             }
;         }
;     }
;     l_run += ls;
.Lt1_e1:
	ds_read_b128 v[200:203], v72 offset:4608
	ds_read_b128 v[204:207], v72 offset:4640
	ds_read_b128 v[208:211], v72 offset:4672
	ds_read_b128 v[212:215], v72 offset:4704
	ds_read2_b64 v[216:219], v73 offset0:8 offset1:10
	ds_read2_b64 v[220:223], v74 offset0:40 offset1:42
	ds_read2_b64 v[224:227], v73 offset0:12 offset1:14
	ds_read2_b64 v[228:231], v74 offset0:44 offset1:46
	s_waitcnt lgkmcnt(7)
	v_mfma_f32_32x32x16_bf16 v[32:47], v[200:203], v[80:83], 0
	ds_read_b128 v[200:203], v72 offset:9216
	s_waitcnt lgkmcnt(7)
	v_mfma_f32_32x32x16_bf16 v[32:47], v[204:207], v[84:87], v[32:47]
	ds_read_b128 v[204:207], v72 offset:9248
	s_waitcnt lgkmcnt(7)
	v_mfma_f32_32x32x16_bf16 v[32:47], v[208:211], v[88:91], v[32:47]
	ds_read_b128 v[208:211], v72 offset:9280
	s_waitcnt lgkmcnt(7)
	v_mfma_f32_32x32x16_bf16 v[32:47], v[212:215], v[92:95], v[32:47]
	ds_read_b128 v[212:215], v72 offset:9312
	s_nop 7
	s_nop 3
	s_waitcnt lgkmcnt(3)
	v_mfma_f32_32x32x16_bf16 v[48:63], v[200:203], v[80:83], 0
	ds_read_b128 v[200:203], v72 offset:13824
	v_cmp_le_i32_e64 s[0:1], 0, v250
	v_cmp_le_i32_e64 s[4:5], 1, v250
	v_exp_f32_e32 v32, v32
	v_exp_f32_e32 v33, v33
	s_waitcnt lgkmcnt(3)
	v_mfma_f32_32x32x16_bf16 v[48:63], v[204:207], v[84:87], v[48:63]
	ds_read_b128 v[204:207], v72 offset:13856
	v_cmp_le_i32_e64 s[6:7], 2, v250
	v_cmp_le_i32_e64 s[48:49], 3, v250
	v_exp_f32_e32 v34, v34
	v_exp_f32_e32 v35, v35
	v_cndmask_b32_e64 v32, v32, 0, s[0:1]
	v_cndmask_b32_e64 v33, v33, 0, s[4:5]
	v_mov_b32_e32 v232, v32
	v_mov_b32_e32 v233, v33
	v_cvt_pk_bf16_f32 v64, v32, v33
	v_cmp_le_i32_e64 s[0:1], 8, v250
	v_cmp_le_i32_e64 s[4:5], 9, v250
	v_exp_f32_e32 v36, v36
	v_exp_f32_e32 v37, v37
	v_cndmask_b32_e64 v34, v34, 0, s[6:7]
	v_cndmask_b32_e64 v35, v35, 0, s[48:49]
	v_add_f32_e32 v232, v232, v34
	v_add_f32_e32 v233, v233, v35
	v_cvt_pk_bf16_f32 v65, v34, v35
	v_cmp_le_i32_e64 s[6:7], 10, v250
	v_cmp_le_i32_e64 s[48:49], 11, v250
	v_exp_f32_e32 v38, v38
	v_exp_f32_e32 v39, v39
	v_cndmask_b32_e64 v36, v36, 0, s[0:1]
	v_cndmask_b32_e64 v37, v37, 0, s[4:5]
	v_add_f32_e32 v232, v232, v36
	v_add_f32_e32 v233, v233, v37
	v_cvt_pk_bf16_f32 v66, v36, v37
	v_cndmask_b32_e64 v38, v38, 0, s[6:7]
	v_cndmask_b32_e64 v39, v39, 0, s[48:49]
	v_add_f32_e32 v232, v232, v38
	v_add_f32_e32 v233, v233, v39
	v_cvt_pk_bf16_f32 v67, v38, v39
	s_waitcnt lgkmcnt(3)
	v_mfma_f32_32x32x16_bf16 v[48:63], v[208:211], v[88:91], v[48:63]
	ds_read_b128 v[208:211], v72 offset:13888
	v_cmp_le_i32_e64 s[0:1], 16, v250
	v_cmp_le_i32_e64 s[4:5], 17, v250
	v_exp_f32_e32 v40, v40
	v_exp_f32_e32 v41, v41
	s_waitcnt lgkmcnt(3)
	v_mfma_f32_32x32x16_bf16 v[48:63], v[212:215], v[92:95], v[48:63]
	ds_read_b128 v[212:215], v72 offset:13920
	v_cmp_le_i32_e64 s[6:7], 18, v250
	v_cmp_le_i32_e64 s[48:49], 19, v250
	v_exp_f32_e32 v42, v42
	v_exp_f32_e32 v43, v43
	v_cndmask_b32_e64 v40, v40, 0, s[0:1]
	v_cndmask_b32_e64 v41, v41, 0, s[4:5]
	v_add_f32_e32 v232, v232, v40
	v_add_f32_e32 v233, v233, v41
	v_cvt_pk_bf16_f32 v68, v40, v41
	v_mfma_f32_32x32x16_bf16 v[0:15], v[216:219], v[64:67], v[0:15]
	ds_read2_b64 v[216:219], v73 offset0:16 offset1:18
	v_cmp_le_i32_e64 s[0:1], 24, v250
	v_cmp_le_i32_e64 s[4:5], 25, v250
	v_exp_f32_e32 v44, v44
	v_exp_f32_e32 v45, v45
	v_cndmask_b32_e64 v42, v42, 0, s[6:7]
	v_cndmask_b32_e64 v43, v43, 0, s[48:49]
	v_add_f32_e32 v232, v232, v42
	v_add_f32_e32 v233, v233, v43
	v_cvt_pk_bf16_f32 v69, v42, v43
	v_mfma_f32_32x32x16_bf16 v[16:31], v[220:223], v[64:67], v[16:31]
	ds_read2_b64 v[220:223], v74 offset0:48 offset1:50
	v_cmp_le_i32_e64 s[6:7], 26, v250
	v_cmp_le_i32_e64 s[48:49], 27, v250
	v_exp_f32_e32 v46, v46
	v_exp_f32_e32 v47, v47
	v_cndmask_b32_e64 v44, v44, 0, s[0:1]
	v_cndmask_b32_e64 v45, v45, 0, s[4:5]
	v_add_f32_e32 v232, v232, v44
	v_add_f32_e32 v233, v233, v45
	v_cvt_pk_bf16_f32 v70, v44, v45
	v_cndmask_b32_e64 v46, v46, 0, s[6:7]
	v_cndmask_b32_e64 v47, v47, 0, s[48:49]
	v_add_f32_e32 v232, v232, v46
	v_add_f32_e32 v233, v233, v47
	v_cvt_pk_bf16_f32 v71, v46, v47
	s_waitcnt lgkmcnt(5)
	v_mfma_f32_32x32x16_bf16 v[32:47], v[200:203], v[80:83], 0
	v_exp_f32_e32 v48, v48
	v_exp_f32_e32 v49, v49
	s_waitcnt lgkmcnt(4)
	v_mfma_f32_32x32x16_bf16 v[32:47], v[204:207], v[84:87], v[32:47]
	v_exp_f32_e32 v50, v50
	v_exp_f32_e32 v51, v51
	v_add_f32_e32 v232, v232, v48
	v_add_f32_e32 v233, v233, v49
	v_cvt_pk_bf16_f32 v64, v48, v49
	v_mfma_f32_32x32x16_bf16 v[0:15], v[224:227], v[68:71], v[0:15]
	ds_read2_b64 v[224:227], v73 offset0:20 offset1:22
	v_exp_f32_e32 v52, v52
	v_exp_f32_e32 v53, v53
	v_add_f32_e32 v232, v232, v50
	v_add_f32_e32 v233, v233, v51
	v_cvt_pk_bf16_f32 v65, v50, v51
	v_mfma_f32_32x32x16_bf16 v[16:31], v[228:231], v[68:71], v[16:31]
	ds_read2_b64 v[228:231], v74 offset0:52 offset1:54
	v_exp_f32_e32 v54, v54
	v_exp_f32_e32 v55, v55
	v_add_f32_e32 v232, v232, v52
	v_add_f32_e32 v233, v233, v53
	v_cvt_pk_bf16_f32 v66, v52, v53
	v_add_f32_e32 v232, v232, v54
	v_add_f32_e32 v233, v233, v55
	v_cvt_pk_bf16_f32 v67, v54, v55
	s_cmp_eq_u32 s45, 0
	s_cbranch_scc1 .Lt1_e1_nostage
	s_waitcnt vmcnt(3)
	ds_write_b128 v251, v[96:99]
	s_waitcnt vmcnt(2)
	ds_write_b128 v251, v[100:103] offset:9216
	s_waitcnt vmcnt(1)
	ds_write2_b64 v252, v[104:105], v[106:107] offset1:1
	s_waitcnt vmcnt(0)
	ds_write2_b64 v252, v[108:109], v[110:111] offset0:16 offset1:17
	s_mov_b32 s47, 1
	s_add_i32 s6, s44, 2
	s_add_i32 s7, s91, s44
	s_add_i32 s7, s7, 1
	s_add_i32 s0, s44, 1
	s_cmp_lt_i32 s0, s90
	s_cbranch_scc0 .Lt1_e1_nostage
	s_cmp_lt_u32 s0, s89
	s_cselect_b32 s0, s71, s75
	s_cselect_b32 s1, s72, s76
	s_cselect_b32 s4, s73, s77
	s_cselect_b32 s5, s74, s78
	s_cselect_b32 s6, s6, s7
	s_ashr_i32 s7, s6, 31
	s_lshl_b64 s[6:7], s[6:7], 14
	s_add_u32 s6, s6, s58
	s_addc_u32 s7, s7, s59
	s_add_u32 s0, s0, s6
	s_addc_u32 s1, s1, s7
	s_add_u32 s4, s4, s6
	s_addc_u32 s5, s5, s7
	global_load_dwordx4 v[96:99], v248, s[0:1]
	global_load_dwordx4 v[100:103], v249, s[0:1]
	global_load_dwordx4 v[104:107], v248, s[4:5]
	global_load_dwordx4 v[108:111], v249, s[4:5]
; #define LAS __attribute__((address_space(3)))
; #define MFMA32(a, b, c) __builtin_amdgcn_mfma_f32_32x32x16_bf16((a), (b), (c), 0, 0, 0)
; __device__ __forceinline__ float ex2(float x) { return __builtin_amdgcn_exp2f(x); }
; template <int MODE>
; __device__ __forceinline__ void attn_tile(const LAS unsigned char* Kb, const LAS unsigned char* Vb, const bf16x8_t (&qf)[4], f32x16 (&oacc)[2], float& l_run,
;                                           int r, int h, int dlt0, int dlt1, bool hiw) {
;     ...
; #pragma unroll
;     for (int mt = 0; mt < 4; ++mt) {
;         if (mt == 0) { if (hiw) __builtin_amdgcn_s_setprio(1); else __builtin_amdgcn_s_setprio(0); }
;         if (mt == 2) { if (hiw) __builtin_amdgcn_s_setprio(0); else __builtin_amdgcn_s_setprio(1); }
;         const int dl = mt < 2 ? dlt0 : dlt1;
;         f32x16 sacc = zero16();
; #pragma unroll
;         for (int ks = 0; ks < 4; ++ks) { const bf16x8_t ka = *(const LAS bf16x8_t*)(Kb + (32 * mt + r) * A_KSTR + 32 * ks + 16 * h); sacc = MFMA32(ka, qf[ks], sacc); }
; #pragma unroll
;         for (int i = 0; i < 16; ++i) {
;             float p;
;             if (MODE == 2) p = ex2(sacc[i]);
;             else if (MODE == 3) p = ex2(sacc[i] + __int_as_float(dl));
;             else { const int ci = 32 * mt + (i & 3) + 8 * (i >> 2); p = ((unsigned)(dl - ci) < ulim) ? ex2(sacc[i]) : 0.f; }
;             sacc[i] = p; ls += p;
;         }
; #pragma unroll
;         for (int s = 0; s < 2; ++s) {
;             const bf16x8_t pf = pack8(sacc, 8 * s);
; #pragma unroll
;             for (int dt = 0; dt < 2; ++dt) {
;                 const LAS unsigned char* vp = Vb + (32 * dt + r) * A_CVSTR + (32 * mt + 16 * s + 4 * h) * 2;
;                 const s16x4_t lo = *(const LAS s16x4_t*)vp, hi = *(const LAS s16x4_t*)(vp + 16);
;                 oacc[dt] = MFMA32(__builtin_shufflevector(lo, hi, 0, 1, 2, 3, 4, 5, 6, 7), pf, oacc[dt]);
;             }
;         }
;     }
;     l_run += ls;
.Lt1_e1_nostage:
	s_waitcnt lgkmcnt(5)
	v_mfma_f32_32x32x16_bf16 v[32:47], v[208:211], v[88:91], v[32:47]
	v_exp_f32_e32 v56, v56
	v_exp_f32_e32 v57, v57
	s_waitcnt lgkmcnt(4)
	v_mfma_f32_32x32x16_bf16 v[32:47], v[212:215], v[92:95], v[32:47]
	v_exp_f32_e32 v58, v58
	v_exp_f32_e32 v59, v59
	v_add_f32_e32 v232, v232, v56
	v_add_f32_e32 v233, v233, v57
	v_cvt_pk_bf16_f32 v68, v56, v57
	s_waitcnt lgkmcnt(3)
	v_mfma_f32_32x32x16_bf16 v[0:15], v[216:219], v[64:67], v[0:15]
	ds_read2_b64 v[216:219], v73 offset0:24 offset1:26
	v_exp_f32_e32 v60, v60
	v_exp_f32_e32 v61, v61
	v_add_f32_e32 v232, v232, v58
	v_add_f32_e32 v233, v233, v59
	v_cvt_pk_bf16_f32 v69, v58, v59
	s_waitcnt lgkmcnt(3)
	v_mfma_f32_32x32x16_bf16 v[16:31], v[220:223], v[64:67], v[16:31]
	ds_read2_b64 v[220:223], v74 offset0:56 offset1:58
	v_exp_f32_e32 v62, v62
	v_exp_f32_e32 v63, v63
	v_add_f32_e32 v232, v232, v60
	v_add_f32_e32 v233, v233, v61
	v_cvt_pk_bf16_f32 v70, v60, v61
	v_add_f32_e32 v232, v232, v62
	v_add_f32_e32 v233, v233, v63
	v_cvt_pk_bf16_f32 v71, v62, v63
	v_exp_f32_e32 v32, v32
	v_exp_f32_e32 v33, v33
	v_exp_f32_e32 v34, v34
	v_exp_f32_e32 v35, v35
	v_add_f32_e32 v232, v232, v32
	v_add_f32_e32 v233, v233, v33
	v_cvt_pk_bf16_f32 v64, v32, v33
	s_waitcnt lgkmcnt(3)
	v_mfma_f32_32x32x16_bf16 v[0:15], v[224:227], v[68:71], v[0:15]
	ds_read2_b64 v[224:227], v73 offset0:28 offset1:30
	v_exp_f32_e32 v36, v36
	v_exp_f32_e32 v37, v37
	v_add_f32_e32 v232, v232, v34
	v_add_f32_e32 v233, v233, v35
	v_cvt_pk_bf16_f32 v65, v34, v35
	s_waitcnt lgkmcnt(3)
	v_mfma_f32_32x32x16_bf16 v[16:31], v[228:231], v[68:71], v[16:31]
	ds_read2_b64 v[228:231], v74 offset0:60 offset1:62
	v_exp_f32_e32 v38, v38
	v_exp_f32_e32 v39, v39
	v_add_f32_e32 v232, v232, v36
	v_add_f32_e32 v233, v233, v37
	v_cvt_pk_bf16_f32 v66, v36, v37
	v_add_f32_e32 v232, v232, v38
	v_add_f32_e32 v233, v233, v39
	v_cvt_pk_bf16_f32 v67, v38, v39
	v_exp_f32_e32 v40, v40
	v_exp_f32_e32 v41, v41
	v_exp_f32_e32 v42, v42
	v_exp_f32_e32 v43, v43
	v_add_f32_e32 v232, v232, v40
	v_add_f32_e32 v233, v233, v41
	v_cvt_pk_bf16_f32 v68, v40, v41
	s_waitcnt lgkmcnt(3)
	v_mfma_f32_32x32x16_bf16 v[0:15], v[216:219], v[64:67], v[0:15]
	v_exp_f32_e32 v44, v44
	v_exp_f32_e32 v45, v45
	v_add_f32_e32 v232, v232, v42
	v_add_f32_e32 v233, v233, v43
	v_cvt_pk_bf16_f32 v69, v42, v43
	s_waitcnt lgkmcnt(2)
	v_mfma_f32_32x32x16_bf16 v[16:31], v[220:223], v[64:67], v[16:31]
	v_exp_f32_e32 v46, v46
	v_exp_f32_e32 v47, v47
	v_add_f32_e32 v232, v232, v44
	v_add_f32_e32 v233, v233, v45
	v_cvt_pk_bf16_f32 v70, v44, v45
	v_add_f32_e32 v232, v232, v46
	v_add_f32_e32 v233, v233, v47
	v_cvt_pk_bf16_f32 v71, v46, v47
	s_nop 1
	s_waitcnt lgkmcnt(1)
	v_mfma_f32_32x32x16_bf16 v[0:15], v[224:227], v[68:71], v[0:15]
	s_waitcnt lgkmcnt(0)
	v_mfma_f32_32x32x16_bf16 v[16:31], v[228:231], v[68:71], v[16:31]
	v_add_f32_e32 v232, v232, v233
	v_add_f32_e32 v112, v112, v232
	s_branch .Lt1_join
.Lt1_e2:
	ds_read_b128 v[200:203], v72 offset:9216
	ds_read_b128 v[204:207], v72 offset:9248
	ds_read_b128 v[208:211], v72 offset:9280
	ds_read_b128 v[212:215], v72 offset:9312
	ds_read2_b64 v[216:219], v73 offset0:16 offset1:18
	ds_read2_b64 v[220:223], v74 offset0:48 offset1:50
	ds_read2_b64 v[224:227], v73 offset0:20 offset1:22
	ds_read2_b64 v[228:231], v74 offset0:52 offset1:54
	s_waitcnt lgkmcnt(7)
	v_mfma_f32_32x32x16_bf16 v[32:47], v[200:203], v[80:83], 0
	ds_read_b128 v[200:203], v72 offset:13824
	s_waitcnt lgkmcnt(7)
	v_mfma_f32_32x32x16_bf16 v[32:47], v[204:207], v[84:87], v[32:47]
	ds_read_b128 v[204:207], v72 offset:13856
	s_waitcnt lgkmcnt(7)
	v_mfma_f32_32x32x16_bf16 v[32:47], v[208:211], v[88:91], v[32:47]
	ds_read_b128 v[208:211], v72 offset:13888
	s_waitcnt lgkmcnt(7)
	v_mfma_f32_32x32x16_bf16 v[32:47], v[212:215], v[92:95], v[32:47]
	ds_read_b128 v[212:215], v72 offset:13920
	s_nop 7
	s_nop 3
	s_waitcnt lgkmcnt(3)
	v_mfma_f32_32x32x16_bf16 v[48:63], v[200:203], v[80:83], 0
	v_cmp_le_i32_e64 s[0:1], 0, v250
	v_cmp_le_i32_e64 s[4:5], 1, v250
	v_exp_f32_e32 v32, v32
	v_exp_f32_e32 v33, v33
	s_waitcnt lgkmcnt(2)
	v_mfma_f32_32x32x16_bf16 v[48:63], v[204:207], v[84:87], v[48:63]
	v_cmp_le_i32_e64 s[6:7], 2, v250
	v_cmp_le_i32_e64 s[48:49], 3, v250
	v_exp_f32_e32 v34, v34
	v_exp_f32_e32 v35, v35
	v_cndmask_b32_e64 v32, v32, 0, s[0:1]
	v_cndmask_b32_e64 v33, v33, 0, s[4:5]
	v_mov_b32_e32 v232, v32
	v_mov_b32_e32 v233, v33
	v_cvt_pk_bf16_f32 v64, v32, v33
	v_cmp_le_i32_e64 s[0:1], 8, v250
	v_cmp_le_i32_e64 s[4:5], 9, v250
	v_exp_f32_e32 v36, v36
	v_exp_f32_e32 v37, v37
	v_cndmask_b32_e64 v34, v34, 0, s[6:7]
	v_cndmask_b32_e64 v35, v35, 0, s[48:49]
	v_add_f32_e32 v232, v232, v34
	v_add_f32_e32 v233, v233, v35
	v_cvt_pk_bf16_f32 v65, v34, v35
	v_cmp_le_i32_e64 s[6:7], 10, v250
	v_cmp_le_i32_e64 s[48:49], 11, v250
	v_exp_f32_e32 v38, v38
	v_exp_f32_e32 v39, v39
	v_cndmask_b32_e64 v36, v36, 0, s[0:1]
	v_cndmask_b32_e64 v37, v37, 0, s[4:5]
	v_add_f32_e32 v232, v232, v36
	v_add_f32_e32 v233, v233, v37
	v_cvt_pk_bf16_f32 v66, v36, v37
	v_cndmask_b32_e64 v38, v38, 0, s[6:7]
	v_cndmask_b32_e64 v39, v39, 0, s[48:49]
	v_add_f32_e32 v232, v232, v38
	v_add_f32_e32 v233, v233, v39
	v_cvt_pk_bf16_f32 v67, v38, v39
	s_cmp_eq_u32 s45, 0
	s_cbranch_scc1 .Lt1_e2_nostage
	s_waitcnt vmcnt(3)
	ds_write_b128 v251, v[96:99]
	s_waitcnt vmcnt(2)
	ds_write_b128 v251, v[100:103] offset:9216
	s_waitcnt vmcnt(1)
	ds_write2_b64 v252, v[104:105], v[106:107] offset1:1
	s_waitcnt vmcnt(0)
	ds_write2_b64 v252, v[108:109], v[110:111] offset0:16 offset1:17
	s_mov_b32 s47, 1
	s_add_i32 s6, s44, 2
	s_add_i32 s7, s91, s44
	s_add_i32 s7, s7, 1
	s_add_i32 s0, s44, 1
	s_cmp_lt_i32 s0, s90
	s_cbranch_scc0 .Lt1_e2_nostage
	s_cmp_lt_u32 s0, s89
	s_cselect_b32 s0, s71, s75
	s_cselect_b32 s1, s72, s76
	s_cselect_b32 s4, s73, s77
	s_cselect_b32 s5, s74, s78
	s_cselect_b32 s6, s6, s7
	s_ashr_i32 s7, s6, 31
	s_lshl_b64 s[6:7], s[6:7], 14
	s_add_u32 s6, s6, s58
	s_addc_u32 s7, s7, s59
	s_add_u32 s0, s0, s6
	s_addc_u32 s1, s1, s7
	s_add_u32 s4, s4, s6
	s_addc_u32 s5, s5, s7
	global_load_dwordx4 v[96:99], v248, s[0:1]
	global_load_dwordx4 v[100:103], v249, s[0:1]
	global_load_dwordx4 v[104:107], v248, s[4:5]
	global_load_dwordx4 v[108:111], v249, s[4:5]
; #define LAS __attribute__((address_space(3)))
; #define MFMA32(a, b, c) __builtin_amdgcn_mfma_f32_32x32x16_bf16((a), (b), (c), 0, 0, 0)
; __device__ __forceinline__ float ex2(float x) { return __builtin_amdgcn_exp2f(x); }
; template <int MODE>
; __device__ __forceinline__ void attn_tile(const LAS unsigned char* Kb, const LAS unsigned char* Vb, const bf16x8_t (&qf)[4], f32x16 (&oacc)[2], float& l_run,
;                                           int r, int h, int dlt0, int dlt1, bool hiw) {
;     ...
; #pragma unroll
;     for (int mt = 0; mt < 4; ++mt) {
;         if (mt == 0) { if (hiw) __builtin_amdgcn_s_setprio(1); else __builtin_amdgcn_s_setprio(0); }
;         if (mt == 2) { if (hiw) __builtin_amdgcn_s_setprio(0); else __builtin_amdgcn_s_setprio(1); }
;         const int dl = mt < 2 ? dlt0 : dlt1;
;         f32x16 sacc = zero16();
; #pragma unroll
;         for (int ks = 0; ks < 4; ++ks) { const bf16x8_t ka = *(const LAS bf16x8_t*)(Kb + (32 * mt + r) * A_KSTR + 32 * ks + 16 * h); sacc = MFMA32(ka, qf[ks], sacc); }
; #pragma unroll
;         for (int i = 0; i < 16; ++i) {
;             float p;
;             if (MODE == 2) p = ex2(sacc[i]);
;             else if (MODE == 3) p = ex2(sacc[i] + __int_as_float(dl));
;             else { const int ci = 32 * mt + (i & 3) + 8 * (i >> 2); p = ((unsigned)(dl - ci) < ulim) ? ex2(sacc[i]) : 0.f; }
;             sacc[i] = p; ls += p;
;         }
; #pragma unroll
;         for (int s = 0; s < 2; ++s) {
;             const bf16x8_t pf = pack8(sacc, 8 * s);
; #pragma unroll
;             for (int dt = 0; dt < 2; ++dt) {
;                 const LAS unsigned char* vp = Vb + (32 * dt + r) * A_CVSTR + (32 * mt + 16 * s + 4 * h) * 2;
;                 const s16x4_t lo = *(const LAS s16x4_t*)vp, hi = *(const LAS s16x4_t*)(vp + 16);
;                 oacc[dt] = MFMA32(__builtin_shufflevector(lo, hi, 0, 1, 2, 3, 4, 5, 6, 7), pf, oacc[dt]);
;             }
;         }
;     }
;     l_run += ls;
.Lt1_e2_nostage:
	s_waitcnt lgkmcnt(1)
	v_mfma_f32_32x32x16_bf16 v[48:63], v[208:211], v[88:91], v[48:63]
	v_cmp_le_i32_e64 s[0:1], 16, v250
	v_cmp_le_i32_e64 s[4:5], 17, v250
	v_exp_f32_e32 v40, v40
	v_exp_f32_e32 v41, v41
	s_waitcnt lgkmcnt(0)
	v_mfma_f32_32x32x16_bf16 v[48:63], v[212:215], v[92:95], v[48:63]
	v_cmp_le_i32_e64 s[6:7], 18, v250
	v_cmp_le_i32_e64 s[48:49], 19, v250
	v_exp_f32_e32 v42, v42
	v_exp_f32_e32 v43, v43
	v_cndmask_b32_e64 v40, v40, 0, s[0:1]
	v_cndmask_b32_e64 v41, v41, 0, s[4:5]
	v_add_f32_e32 v232, v232, v40
	v_add_f32_e32 v233, v233, v41
	v_cvt_pk_bf16_f32 v68, v40, v41
	v_mfma_f32_32x32x16_bf16 v[0:15], v[216:219], v[64:67], v[0:15]
	ds_read2_b64 v[216:219], v73 offset0:24 offset1:26
	v_cmp_le_i32_e64 s[0:1], 24, v250
	v_cmp_le_i32_e64 s[4:5], 25, v250
	v_exp_f32_e32 v44, v44
	v_exp_f32_e32 v45, v45
	v_cndmask_b32_e64 v42, v42, 0, s[6:7]
	v_cndmask_b32_e64 v43, v43, 0, s[48:49]
	v_add_f32_e32 v232, v232, v42
	v_add_f32_e32 v233, v233, v43
	v_cvt_pk_bf16_f32 v69, v42, v43
	v_mfma_f32_32x32x16_bf16 v[16:31], v[220:223], v[64:67], v[16:31]
	ds_read2_b64 v[220:223], v74 offset0:56 offset1:58
	v_cmp_le_i32_e64 s[6:7], 26, v250
	v_cmp_le_i32_e64 s[48:49], 27, v250
	v_exp_f32_e32 v46, v46
	v_exp_f32_e32 v47, v47
	v_cndmask_b32_e64 v44, v44, 0, s[0:1]
	v_cndmask_b32_e64 v45, v45, 0, s[4:5]
	v_add_f32_e32 v232, v232, v44
	v_add_f32_e32 v233, v233, v45
	v_cvt_pk_bf16_f32 v70, v44, v45
	v_cndmask_b32_e64 v46, v46, 0, s[6:7]
	v_cndmask_b32_e64 v47, v47, 0, s[48:49]
	v_add_f32_e32 v232, v232, v46
	v_add_f32_e32 v233, v233, v47
	v_cvt_pk_bf16_f32 v71, v46, v47
	v_exp_f32_e32 v48, v48
	v_exp_f32_e32 v49, v49
	v_exp_f32_e32 v50, v50
	v_exp_f32_e32 v51, v51
	v_add_f32_e32 v232, v232, v48
	v_add_f32_e32 v233, v233, v49
	v_cvt_pk_bf16_f32 v64, v48, v49
	v_mfma_f32_32x32x16_bf16 v[0:15], v[224:227], v[68:71], v[0:15]
	ds_read2_b64 v[224:227], v73 offset0:28 offset1:30
	v_exp_f32_e32 v52, v52
	v_exp_f32_e32 v53, v53
	v_add_f32_e32 v232, v232, v50
	v_add_f32_e32 v233, v233, v51
	v_cvt_pk_bf16_f32 v65, v50, v51
	v_mfma_f32_32x32x16_bf16 v[16:31], v[228:231], v[68:71], v[16:31]
	ds_read2_b64 v[228:231], v74 offset0:60 offset1:62
	v_exp_f32_e32 v54, v54
	v_exp_f32_e32 v55, v55
	v_add_f32_e32 v232, v232, v52
	v_add_f32_e32 v233, v233, v53
	v_cvt_pk_bf16_f32 v66, v52, v53
	v_add_f32_e32 v232, v232, v54
	v_add_f32_e32 v233, v233, v55
	v_cvt_pk_bf16_f32 v67, v54, v55
	v_exp_f32_e32 v56, v56
	v_exp_f32_e32 v57, v57
	v_exp_f32_e32 v58, v58
	v_exp_f32_e32 v59, v59
	v_add_f32_e32 v232, v232, v56
	v_add_f32_e32 v233, v233, v57
	v_cvt_pk_bf16_f32 v68, v56, v57
	s_waitcnt lgkmcnt(3)
	v_mfma_f32_32x32x16_bf16 v[0:15], v[216:219], v[64:67], v[0:15]
	v_exp_f32_e32 v60, v60
	v_exp_f32_e32 v61, v61
	v_add_f32_e32 v232, v232, v58
	v_add_f32_e32 v233, v233, v59
	v_cvt_pk_bf16_f32 v69, v58, v59
	s_waitcnt lgkmcnt(2)
	v_mfma_f32_32x32x16_bf16 v[16:31], v[220:223], v[64:67], v[16:31]
	v_exp_f32_e32 v62, v62
	v_exp_f32_e32 v63, v63
	v_add_f32_e32 v232, v232, v60
	v_add_f32_e32 v233, v233, v61
	v_cvt_pk_bf16_f32 v70, v60, v61
	v_add_f32_e32 v232, v232, v62
	v_add_f32_e32 v233, v233, v63
	v_cvt_pk_bf16_f32 v71, v62, v63
	s_nop 1
	s_waitcnt lgkmcnt(1)
	v_mfma_f32_32x32x16_bf16 v[0:15], v[224:227], v[68:71], v[0:15]
	s_waitcnt lgkmcnt(0)
	v_mfma_f32_32x32x16_bf16 v[16:31], v[228:231], v[68:71], v[16:31]
	v_add_f32_e32 v232, v232, v233
	v_add_f32_e32 v112, v112, v232
	s_branch .Lt1_join

; __device__ __forceinline__ void phase4_attn(const Args& a, LAS unsigned char* lds) {
;     ...
;                     if (i + 1 < n_all) A_STAGE(bufo ^ 1);
;                     __syncthreads();
.Lt1_stage:
	s_cmp_eq_u32 s45, 0
	s_cbranch_scc1 .Lt1_latch
	s_cmp_eq_u32 s47, 1
	s_cbranch_scc1 .Lt1_latch
	s_waitcnt vmcnt(3)
	ds_write_b128 v251, v[96:99]
	s_waitcnt vmcnt(2)
	ds_write_b128 v251, v[100:103] offset:9216
	s_waitcnt vmcnt(1)
	ds_write2_b64 v252, v[104:105], v[106:107] offset1:1
	s_waitcnt vmcnt(0)
	ds_write2_b64 v252, v[108:109], v[110:111] offset0:16 offset1:17
	s_add_i32 s6, s44, 2
	s_add_i32 s7, s91, s44
	s_add_i32 s7, s7, 1
	s_add_i32 s0, s44, 1
	s_cmp_lt_i32 s0, s90
	s_cbranch_scc0 .Lt1_latch
	s_cmp_lt_u32 s0, s89
	s_cselect_b32 s0, s71, s75
	s_cselect_b32 s1, s72, s76
	s_cselect_b32 s4, s73, s77
	s_cselect_b32 s5, s74, s78
	s_cselect_b32 s6, s6, s7
	s_ashr_i32 s7, s6, 31
	s_lshl_b64 s[6:7], s[6:7], 14
	s_add_u32 s6, s6, s58
	s_addc_u32 s7, s7, s59
	s_add_u32 s0, s0, s6
	s_addc_u32 s1, s1, s7
	s_add_u32 s4, s4, s6
	s_addc_u32 s5, s5, s7
	global_load_dwordx4 v[96:99], v248, s[0:1]
	global_load_dwordx4 v[100:103], v249, s[0:1]
	global_load_dwordx4 v[104:107], v248, s[4:5]
	global_load_dwordx4 v[108:111], v249, s[4:5]

; #define LAS __attribute__((address_space(3)))
; __device__ __forceinline__ void phase4_attn(const Args& a, LAS unsigned char* lds) {
;     ...
;                 const int kt_lo = t >= 8 ? t - 8 : 0, wlo = kt_lo >> 1, n_sel = (t >> 1) + 1, n_all = n_sel + ((t >> 1) - wlo + 1);
;                 const bf16_t* Ks = ksl + (size_t)bh * 2048 * 64; const bf16_t* Vs = vslT + (size_t)bh * 64 * 2048;
;                 const bf16_t* Kw = kwn + (size_t)bh * 2048 * 64; const bf16_t* Vw = vwnT + (size_t)bh * 64 * 2048;
;     ...
;                 u32x4 kR0, kR1, vR0, vR1;
;                 A_ISSUE(0);
;                 A_STAGE(0);
;                 __syncthreads();
;                 f32x16 oacc[2]; oacc[0] = zero16(); oacc[1] = zero16();
;                 float l_run = 0.f;
; #pragma unroll 1
;                 for (int i = 0; i < n_all; ++i) {
;                     const int bufo = i & 1;
;                     if (i + 1 < n_all) A_ISSUE(i + 1);
;                     const LAS unsigned char* Kb = lds + A_KBUF + bufo * A_KT; const LAS unsigned char* Vb = lds + A_VBUF + bufo * A_VT;
;                     const bool issel = i < n_sel;
;                     const int st = issel ? i : wlo + (i - n_sel);
;                     const int dlt = 64 * t + ql - 128 * st - 4 * h;
.LBB0_806:
	v_add_u32_e32 v244, v118, v153
	v_add_u32_e32 v245, v196, v197
	v_add_u32_e32 v245, 0x9000, v245
	v_ashrrev_i32_e32 v239, 3, v152
	v_lshlrev_b32_e32 v240, 4, v152
	v_and_b32_e32 v240, 0x70, v240
	v_mul_u32_u24_e32 v246, 0x90, v239
	v_add_u32_e32 v246, v246, v240
	v_mul_u32_u24_e32 v247, 0x108, v239
	v_add_u32_e32 v247, v247, v240
	v_add_u32_e32 v247, 0x9000, v247
	v_lshlrev_b32_e32 v248, 4, v152
	v_add_u32_e32 v249, 0x2000, v248
	v_and_b32_e32 v250, 31, v152
	v_sub_u32_e32 v250, v250, v195
	v_readfirstlane_b32 s50, v152
	s_bfe_u32 s50, s50, 0x10006
	s_lshl_b32 s0, s38, 1
	s_add_i32 s50, s50, s0
	s_add_i32 s6, s44, 1
	s_add_i32 s7, s91, s44
	s_add_i32 s0, s44, 0
	s_cmp_lt_i32 s0, s90
	s_cbranch_scc0 .Lt2_pre_noissue
	s_cmp_lt_u32 s0, s89
	s_cselect_b32 s0, s71, s75
	s_cselect_b32 s1, s72, s76
	s_cselect_b32 s4, s73, s77
	s_cselect_b32 s5, s74, s78
	s_cselect_b32 s6, s6, s7
	s_ashr_i32 s7, s6, 31
	s_lshl_b64 s[6:7], s[6:7], 14
	s_add_u32 s6, s6, s60
	s_addc_u32 s7, s7, s61
	s_add_u32 s0, s0, s6
	s_addc_u32 s1, s1, s7
	s_add_u32 s4, s4, s6
	s_addc_u32 s5, s5, s7
	global_load_dwordx4 v[96:99], v248, s[0:1]
	global_load_dwordx4 v[100:103], v249, s[0:1]
	global_load_dwordx4 v[104:107], v248, s[4:5]
	global_load_dwordx4 v[108:111], v249, s[4:5]
.Lt2_pre_noissue:
.Lt2_head:
	s_cmp_lt_i32 s44, s90
	s_cselect_b32 s45, 1, 0
	s_branch .Lt2_noissue
	s_add_i32 s6, s44, 1
	s_add_i32 s7, s91, s44
	s_cmp_lt_i32 s44, s90
	s_cselect_b32 s45, 1, 0
	s_cbranch_scc0 .Lt2_noissue
	s_cmp_lt_u32 s44, s89
	s_cselect_b32 s0, s71, s75
	s_cselect_b32 s1, s72, s76
	s_cselect_b32 s4, s73, s77
	s_cselect_b32 s5, s74, s78
	s_cselect_b32 s6, s6, s7
	s_ashr_i32 s7, s6, 31
	s_lshl_b64 s[6:7], s[6:7], 14
	s_add_u32 s6, s6, s60
	s_addc_u32 s7, s7, s61
	s_add_u32 s0, s0, s6
	s_addc_u32 s1, s1, s7
	s_add_u32 s4, s4, s6
	s_addc_u32 s5, s5, s7
	global_load_dwordx4 v[96:99], v248, s[0:1]
	global_load_dwordx4 v[100:103], v249, s[0:1]
	global_load_dwordx4 v[104:107], v248, s[4:5]
	global_load_dwordx4 v[108:111], v249, s[4:5]

; #define LAS __attribute__((address_space(3)))
; #define MFMA32(a, b, c) __builtin_amdgcn_mfma_f32_32x32x16_bf16((a), (b), (c), 0, 0, 0)
; __device__ __forceinline__ float ex2(float x) { return __builtin_amdgcn_exp2f(x); }
; template <int MODE>
; __device__ __forceinline__ void attn_tile(const LAS unsigned char* Kb, const LAS unsigned char* Vb, const bf16x8_t (&qf)[4], f32x16 (&oacc)[2], float& l_run,
;                                           int r, int h, int dlt0, int dlt1, bool hiw) {
;     ...
; #pragma unroll
;     for (int mt = 0; mt < 4; ++mt) {
;         if (mt == 0) { if (hiw) __builtin_amdgcn_s_setprio(1); else __builtin_amdgcn_s_setprio(0); }
;         if (mt == 2) { if (hiw) __builtin_amdgcn_s_setprio(0); else __builtin_amdgcn_s_setprio(1); }
;         const int dl = mt < 2 ? dlt0 : dlt1;
;         f32x16 sacc = zero16();
; #pragma unroll
;         for (int ks = 0; ks < 4; ++ks) { const bf16x8_t ka = *(const LAS bf16x8_t*)(Kb + (32 * mt + r) * A_KSTR + 32 * ks + 16 * h); sacc = MFMA32(ka, qf[ks], sacc); }
; #pragma unroll
;         for (int i = 0; i < 16; ++i) {
;             float p;
;             if (MODE == 2) p = ex2(sacc[i]);
;             else if (MODE == 3) p = ex2(sacc[i] + __int_as_float(dl));
;             else { const int ci = 32 * mt + (i & 3) + 8 * (i >> 2); p = ((unsigned)(dl - ci) < ulim) ? ex2(sacc[i]) : 0.f; }
;             sacc[i] = p; ls += p;
;         }
; #pragma unroll
;         for (int s = 0; s < 2; ++s) {
;             const bf16x8_t pf = pack8(sacc, 8 * s);
; #pragma unroll
;             for (int dt = 0; dt < 2; ++dt) {
;                 const LAS unsigned char* vp = Vb + (32 * dt + r) * A_CVSTR + (32 * mt + 16 * s + 4 * h) * 2;
;                 const s16x4_t lo = *(const LAS s16x4_t*)vp, hi = *(const LAS s16x4_t*)(vp + 16);
;                 oacc[dt] = MFMA32(__builtin_shufflevector(lo, hi, 0, 1, 2, 3, 4, 5, 6, 7), pf, oacc[dt]);
;             }
;         }
;     }
;     l_run += ls;
.Lt2_full:
	ds_read_b128 v[200:203], v72 offset:0
	ds_read_b128 v[204:207], v72 offset:32
	ds_read_b128 v[208:211], v72 offset:64
	ds_read_b128 v[212:215], v72 offset:96
	ds_read2_b64 v[216:219], v73 offset0:0 offset1:2
	ds_read2_b64 v[220:223], v74 offset0:32 offset1:34
	ds_read2_b64 v[224:227], v73 offset0:4 offset1:6
	ds_read2_b64 v[228:231], v74 offset0:36 offset1:38
	s_waitcnt lgkmcnt(7)
	v_mfma_f32_32x32x16_bf16 v[32:47], v[200:203], v[80:83], 0
	ds_read_b128 v[200:203], v72 offset:4608
	s_waitcnt lgkmcnt(7)
	v_mfma_f32_32x32x16_bf16 v[32:47], v[204:207], v[84:87], v[32:47]
	ds_read_b128 v[204:207], v72 offset:4640
	s_waitcnt lgkmcnt(7)
	v_mfma_f32_32x32x16_bf16 v[32:47], v[208:211], v[88:91], v[32:47]
	ds_read_b128 v[208:211], v72 offset:4672
	s_waitcnt lgkmcnt(7)
	v_mfma_f32_32x32x16_bf16 v[32:47], v[212:215], v[92:95], v[32:47]
	ds_read_b128 v[212:215], v72 offset:4704
	s_nop 7
	s_nop 3
	s_waitcnt lgkmcnt(3)
	v_mfma_f32_32x32x16_bf16 v[48:63], v[200:203], v[80:83], 0
	ds_read_b128 v[200:203], v72 offset:9216
	v_exp_f32_e32 v32, v32
	v_exp_f32_e32 v33, v33
	s_waitcnt lgkmcnt(3)
	v_mfma_f32_32x32x16_bf16 v[48:63], v[204:207], v[84:87], v[48:63]
	ds_read_b128 v[204:207], v72 offset:9248
	v_exp_f32_e32 v34, v34
	v_exp_f32_e32 v35, v35
	v_mov_b32_e32 v232, v32
	v_mov_b32_e32 v233, v33
	v_cvt_pk_bf16_f32 v64, v32, v33
	v_exp_f32_e32 v36, v36
	v_exp_f32_e32 v37, v37
	v_add_f32_e32 v232, v232, v34
	v_add_f32_e32 v233, v233, v35
	v_cvt_pk_bf16_f32 v65, v34, v35
	v_exp_f32_e32 v38, v38
	v_exp_f32_e32 v39, v39
	v_add_f32_e32 v232, v232, v36
	v_add_f32_e32 v233, v233, v37
	v_cvt_pk_bf16_f32 v66, v36, v37
	v_add_f32_e32 v232, v232, v38
	v_add_f32_e32 v233, v233, v39
	v_cvt_pk_bf16_f32 v67, v38, v39
	s_waitcnt lgkmcnt(3)
	v_mfma_f32_32x32x16_bf16 v[48:63], v[208:211], v[88:91], v[48:63]
	ds_read_b128 v[208:211], v72 offset:9280
	v_exp_f32_e32 v40, v40
	v_exp_f32_e32 v41, v41
	s_waitcnt lgkmcnt(3)
	v_mfma_f32_32x32x16_bf16 v[48:63], v[212:215], v[92:95], v[48:63]
	ds_read_b128 v[212:215], v72 offset:9312
	v_exp_f32_e32 v42, v42
	v_exp_f32_e32 v43, v43
	v_add_f32_e32 v232, v232, v40
	v_add_f32_e32 v233, v233, v41
	v_cvt_pk_bf16_f32 v68, v40, v41
	v_mfma_f32_32x32x16_bf16 v[0:15], v[216:219], v[64:67], v[0:15]
	ds_read2_b64 v[216:219], v73 offset0:8 offset1:10
	v_exp_f32_e32 v44, v44
	v_exp_f32_e32 v45, v45
	v_add_f32_e32 v232, v232, v42
	v_add_f32_e32 v233, v233, v43
	v_cvt_pk_bf16_f32 v69, v42, v43
	v_mfma_f32_32x32x16_bf16 v[16:31], v[220:223], v[64:67], v[16:31]
	ds_read2_b64 v[220:223], v74 offset0:40 offset1:42
	v_exp_f32_e32 v46, v46
	v_exp_f32_e32 v47, v47
	v_add_f32_e32 v232, v232, v44
	v_add_f32_e32 v233, v233, v45
	v_cvt_pk_bf16_f32 v70, v44, v45
	v_add_f32_e32 v232, v232, v46
	v_add_f32_e32 v233, v233, v47
	v_cvt_pk_bf16_f32 v71, v46, v47
	s_waitcnt lgkmcnt(5)
	v_mfma_f32_32x32x16_bf16 v[32:47], v[200:203], v[80:83], 0
	ds_read_b128 v[200:203], v72 offset:13824
	v_exp_f32_e32 v48, v48
	v_exp_f32_e32 v49, v49
	s_waitcnt lgkmcnt(5)
	v_mfma_f32_32x32x16_bf16 v[32:47], v[204:207], v[84:87], v[32:47]
	ds_read_b128 v[204:207], v72 offset:13856
	v_exp_f32_e32 v50, v50
	v_exp_f32_e32 v51, v51
	v_add_f32_e32 v232, v232, v48
	v_add_f32_e32 v233, v233, v49
	v_cvt_pk_bf16_f32 v64, v48, v49
	v_mfma_f32_32x32x16_bf16 v[0:15], v[224:227], v[68:71], v[0:15]
	ds_read2_b64 v[224:227], v73 offset0:12 offset1:14
	v_exp_f32_e32 v52, v52
	v_exp_f32_e32 v53, v53
	v_add_f32_e32 v232, v232, v50
	v_add_f32_e32 v233, v233, v51
	v_cvt_pk_bf16_f32 v65, v50, v51
	v_mfma_f32_32x32x16_bf16 v[16:31], v[228:231], v[68:71], v[16:31]
	ds_read2_b64 v[228:231], v74 offset0:44 offset1:46
	v_exp_f32_e32 v54, v54
	v_exp_f32_e32 v55, v55
	v_add_f32_e32 v232, v232, v52
	v_add_f32_e32 v233, v233, v53
	v_cvt_pk_bf16_f32 v66, v52, v53
	v_add_f32_e32 v232, v232, v54
	v_add_f32_e32 v233, v233, v55
	v_cvt_pk_bf16_f32 v67, v54, v55
	s_waitcnt lgkmcnt(7)
	v_mfma_f32_32x32x16_bf16 v[32:47], v[208:211], v[88:91], v[32:47]
	ds_read_b128 v[208:211], v72 offset:13888
	v_exp_f32_e32 v56, v56
	v_exp_f32_e32 v57, v57
	s_waitcnt lgkmcnt(7)
	v_mfma_f32_32x32x16_bf16 v[32:47], v[212:215], v[92:95], v[32:47]
	ds_read_b128 v[212:215], v72 offset:13920
	v_exp_f32_e32 v58, v58
	v_exp_f32_e32 v59, v59
	v_add_f32_e32 v232, v232, v56
	v_add_f32_e32 v233, v233, v57
	v_cvt_pk_bf16_f32 v68, v56, v57
	s_waitcnt lgkmcnt(7)
	v_mfma_f32_32x32x16_bf16 v[0:15], v[216:219], v[64:67], v[0:15]
	ds_read2_b64 v[216:219], v73 offset0:16 offset1:18
	v_exp_f32_e32 v60, v60
	v_exp_f32_e32 v61, v61
	v_add_f32_e32 v232, v232, v58
	v_add_f32_e32 v233, v233, v59
	v_cvt_pk_bf16_f32 v69, v58, v59
	s_waitcnt lgkmcnt(7)
	v_mfma_f32_32x32x16_bf16 v[16:31], v[220:223], v[64:67], v[16:31]
	ds_read2_b64 v[220:223], v74 offset0:48 offset1:50
	v_exp_f32_e32 v62, v62
	v_exp_f32_e32 v63, v63
	v_add_f32_e32 v232, v232, v60
	v_add_f32_e32 v233, v233, v61
	v_cvt_pk_bf16_f32 v70, v60, v61
	v_add_f32_e32 v232, v232, v62
	v_add_f32_e32 v233, v233, v63
	v_cvt_pk_bf16_f32 v71, v62, v63
	s_waitcnt lgkmcnt(7)
	v_mfma_f32_32x32x16_bf16 v[48:63], v[200:203], v[80:83], 0
	v_exp_f32_e32 v32, v32
	v_exp_f32_e32 v33, v33
	s_waitcnt lgkmcnt(6)
	v_mfma_f32_32x32x16_bf16 v[48:63], v[204:207], v[84:87], v[48:63]
	v_exp_f32_e32 v34, v34
	v_exp_f32_e32 v35, v35
	v_add_f32_e32 v232, v232, v32
	v_add_f32_e32 v233, v233, v33
	v_cvt_pk_bf16_f32 v64, v32, v33
	s_waitcnt lgkmcnt(5)
	v_mfma_f32_32x32x16_bf16 v[0:15], v[224:227], v[68:71], v[0:15]
	ds_read2_b64 v[224:227], v73 offset0:20 offset1:22
	v_exp_f32_e32 v36, v36
	v_exp_f32_e32 v37, v37
	v_add_f32_e32 v232, v232, v34
	v_add_f32_e32 v233, v233, v35
	v_cvt_pk_bf16_f32 v65, v34, v35
	s_waitcnt lgkmcnt(5)
	v_mfma_f32_32x32x16_bf16 v[16:31], v[228:231], v[68:71], v[16:31]
	ds_read2_b64 v[228:231], v74 offset0:52 offset1:54
	v_exp_f32_e32 v38, v38
	v_exp_f32_e32 v39, v39
	v_add_f32_e32 v232, v232, v36
	v_add_f32_e32 v233, v233, v37
	v_cvt_pk_bf16_f32 v66, v36, v37
	v_add_f32_e32 v232, v232, v38
	v_add_f32_e32 v233, v233, v39
	v_cvt_pk_bf16_f32 v67, v38, v39
	s_cmp_eq_u32 s45, 0
	s_cbranch_scc1 .Lt2_full_nostage
	s_waitcnt vmcnt(3)
	ds_write_b128 v251, v[96:99]
	s_waitcnt vmcnt(2)
	ds_write_b128 v251, v[100:103] offset:9216
	s_waitcnt vmcnt(1)
	ds_write2_b64 v252, v[104:105], v[106:107] offset1:1
	s_waitcnt vmcnt(0)
	ds_write2_b64 v252, v[108:109], v[110:111] offset0:16 offset1:17
	s_mov_b32 s47, 1
	s_add_i32 s6, s44, 2
	s_add_i32 s7, s91, s44
	s_add_i32 s7, s7, 1
	s_add_i32 s0, s44, 1
	s_cmp_lt_i32 s0, s90
	s_cbranch_scc0 .Lt2_full_nostage
	s_cmp_lt_u32 s0, s89
	s_cselect_b32 s0, s71, s75
	s_cselect_b32 s1, s72, s76
	s_cselect_b32 s4, s73, s77
	s_cselect_b32 s5, s74, s78
	s_cselect_b32 s6, s6, s7
	s_ashr_i32 s7, s6, 31
	s_lshl_b64 s[6:7], s[6:7], 14
	s_add_u32 s6, s6, s60
	s_addc_u32 s7, s7, s61
	s_add_u32 s0, s0, s6
	s_addc_u32 s1, s1, s7
	s_add_u32 s4, s4, s6
	s_addc_u32 s5, s5, s7
	global_load_dwordx4 v[96:99], v248, s[0:1]
	global_load_dwordx4 v[100:103], v249, s[0:1]
	global_load_dwordx4 v[104:107], v248, s[4:5]
	global_load_dwordx4 v[108:111], v249, s[4:5]

; #define LAS __attribute__((address_space(3)))
; template <int MODE>
; __device__ __forceinline__ void attn_tile(const LAS unsigned char* Kb, const LAS unsigned char* Vb, const bf16x8_t (&qf)[4], f32x16 (&oacc)[2], float& l_run,
;                                           int r, int h, int dlt0, int dlt1, bool hiw) {
;     ...
; #pragma unroll
;     for (int mt = 0; mt < 4; ++mt) {
;         if (mt == 0) { if (hiw) __builtin_amdgcn_s_setprio(1); else __builtin_amdgcn_s_setprio(0); }
;         if (mt == 2) { if (hiw) __builtin_amdgcn_s_setprio(0); else __builtin_amdgcn_s_setprio(1); }
;         const int dl = mt < 2 ? dlt0 : dlt1;
;         f32x16 sacc = zero16();
; #pragma unroll
;         for (int ks = 0; ks < 4; ++ks) { const bf16x8_t ka = *(const LAS bf16x8_t*)(Kb + (32 * mt + r) * A_KSTR + 32 * ks + 16 * h); sacc = MFMA32(ka, qf[ks], sacc); }
; #pragma unroll
;         for (int i = 0; i < 16; ++i) {
;             float p;
;             if (MODE == 2) p = ex2(sacc[i]);
;             else if (MODE == 3) p = ex2(sacc[i] + __int_as_float(dl));
;             else { const int ci = 32 * mt + (i & 3) + 8 * (i >> 2); p = ((unsigned)(dl - ci) < ulim) ? ex2(sacc[i]) : 0.f; }
;             sacc[i] = p; ls += p;
;         }
; #pragma unroll
;         for (int s = 0; s < 2; ++s) {
;             const bf16x8_t pf = pack8(sacc, 8 * s);
; #pragma unroll
;             for (int dt = 0; dt < 2; ++dt) {
;                 const LAS unsigned char* vp = Vb + (32 * dt + r) * A_CVSTR + (32 * mt + 16 * s + 4 * h) * 2;
;                 const s16x4_t lo = *(const LAS s16x4_t*)vp, hi = *(const LAS s16x4_t*)(vp + 16);
;                 oacc[dt] = MFMA32(__builtin_shufflevector(lo, hi, 0, 1, 2, 3, 4, 5, 6, 7), pf, oacc[dt]);
;             }
;         }
;     }
; __device__ __forceinline__ void phase4_attn(const Args& a, LAS unsigned char* lds) {
;     ...
;                     if (issel) {
;                         const bool b0 = (selw >> (2 * st)) & 1u, b1 = (selw >> (2 * st + 1)) & 1u;
;                         if (__ballot(b0 || b1) != 0ull) {
;                             if (2 * st + 1 < t) {
;                                 if (__ballot(b0 && b1) == ~0ull) attn_tile<2>(Kb, Vb, qf, oacc, l_run, r, h, dlt, dlt, (w & 4) != 0);
;                                 else attn_tile<3>(Kb, Vb, qf, oacc, l_run, r, h, __float_as_int(b0 ? 0.f : -1e30f), __float_as_int(b1 ? 0.f : -1e30f), (w & 4) != 0);
.Lt2_bias:
	ds_read_b128 v[200:203], v72 offset:0
	ds_read_b128 v[204:207], v72 offset:32
	ds_read_b128 v[208:211], v72 offset:64
	ds_read_b128 v[212:215], v72 offset:96
	ds_read2_b64 v[216:219], v73 offset0:0 offset1:2
	ds_read2_b64 v[220:223], v74 offset0:32 offset1:34
	ds_read2_b64 v[224:227], v73 offset0:4 offset1:6
	ds_read2_b64 v[228:231], v74 offset0:36 offset1:38
	v_bfe_i32 v236, v198, s49, 1
	s_add_i32 s49, s49, 1
	v_bfe_i32 v237, v198, s49, 1
	s_waitcnt lgkmcnt(7)
	v_mfma_f32_32x32x16_bf16 v[32:47], v[200:203], v[80:83], 0
	ds_read_b128 v[200:203], v72 offset:4608
	s_waitcnt lgkmcnt(7)
	v_mfma_f32_32x32x16_bf16 v[32:47], v[204:207], v[84:87], v[32:47]
	ds_read_b128 v[204:207], v72 offset:4640
	s_waitcnt lgkmcnt(7)
	v_mfma_f32_32x32x16_bf16 v[32:47], v[208:211], v[88:91], v[32:47]
	ds_read_b128 v[208:211], v72 offset:4672
	s_waitcnt lgkmcnt(7)
	v_mfma_f32_32x32x16_bf16 v[32:47], v[212:215], v[92:95], v[32:47]
	ds_read_b128 v[212:215], v72 offset:4704
	s_nop 7
	s_nop 3
	s_waitcnt lgkmcnt(3)
	v_mfma_f32_32x32x16_bf16 v[48:63], v[200:203], v[80:83], 0
	ds_read_b128 v[200:203], v72 offset:9216
	v_exp_f32_e32 v32, v32
	v_exp_f32_e32 v33, v33
	s_waitcnt lgkmcnt(3)
	v_mfma_f32_32x32x16_bf16 v[48:63], v[204:207], v[84:87], v[48:63]
	ds_read_b128 v[204:207], v72 offset:9248
	v_exp_f32_e32 v34, v34
	v_exp_f32_e32 v35, v35
	v_mov_b32_e32 v232, v32
	v_mov_b32_e32 v233, v33
	v_cvt_pk_bf16_f32 v64, v32, v33
	v_and_b32_e32 v64, v236, v64
	v_exp_f32_e32 v36, v36
	v_exp_f32_e32 v37, v37
	v_add_f32_e32 v232, v232, v34
	v_add_f32_e32 v233, v233, v35
	v_cvt_pk_bf16_f32 v65, v34, v35
	v_and_b32_e32 v65, v236, v65
	v_exp_f32_e32 v38, v38
	v_exp_f32_e32 v39, v39
	v_add_f32_e32 v232, v232, v36
	v_add_f32_e32 v233, v233, v37
	v_cvt_pk_bf16_f32 v66, v36, v37
	v_and_b32_e32 v66, v236, v66
	v_add_f32_e32 v232, v232, v38
	v_add_f32_e32 v233, v233, v39
	v_cvt_pk_bf16_f32 v67, v38, v39
	v_and_b32_e32 v67, v236, v67
	s_waitcnt lgkmcnt(3)
	v_mfma_f32_32x32x16_bf16 v[48:63], v[208:211], v[88:91], v[48:63]
	ds_read_b128 v[208:211], v72 offset:9280
	v_exp_f32_e32 v40, v40
	v_exp_f32_e32 v41, v41
	s_waitcnt lgkmcnt(3)
	v_mfma_f32_32x32x16_bf16 v[48:63], v[212:215], v[92:95], v[48:63]
	ds_read_b128 v[212:215], v72 offset:9312
	v_exp_f32_e32 v42, v42
	v_exp_f32_e32 v43, v43
	v_add_f32_e32 v232, v232, v40
	v_add_f32_e32 v233, v233, v41
	v_cvt_pk_bf16_f32 v68, v40, v41
	v_and_b32_e32 v68, v236, v68
	v_mfma_f32_32x32x16_bf16 v[0:15], v[216:219], v[64:67], v[0:15]
	ds_read2_b64 v[216:219], v73 offset0:8 offset1:10
	v_exp_f32_e32 v44, v44
	v_exp_f32_e32 v45, v45
	v_add_f32_e32 v232, v232, v42
	v_add_f32_e32 v233, v233, v43
	v_cvt_pk_bf16_f32 v69, v42, v43
	v_and_b32_e32 v69, v236, v69
	v_mfma_f32_32x32x16_bf16 v[16:31], v[220:223], v[64:67], v[16:31]
	ds_read2_b64 v[220:223], v74 offset0:40 offset1:42
	v_exp_f32_e32 v46, v46
	v_exp_f32_e32 v47, v47
	v_add_f32_e32 v232, v232, v44
	v_add_f32_e32 v233, v233, v45
	v_cvt_pk_bf16_f32 v70, v44, v45
	v_and_b32_e32 v70, v236, v70
	v_add_f32_e32 v232, v232, v46
	v_add_f32_e32 v233, v233, v47
	v_cvt_pk_bf16_f32 v71, v46, v47
	v_and_b32_e32 v71, v236, v71
	s_waitcnt lgkmcnt(5)
	v_mfma_f32_32x32x16_bf16 v[32:47], v[200:203], v[80:83], 0
	ds_read_b128 v[200:203], v72 offset:13824
	v_exp_f32_e32 v48, v48
	v_exp_f32_e32 v49, v49
	s_waitcnt lgkmcnt(5)
	v_mfma_f32_32x32x16_bf16 v[32:47], v[204:207], v[84:87], v[32:47]
	ds_read_b128 v[204:207], v72 offset:13856
	v_exp_f32_e32 v50, v50
	v_exp_f32_e32 v51, v51
	v_add_f32_e32 v232, v232, v48
	v_add_f32_e32 v233, v233, v49
	v_cvt_pk_bf16_f32 v64, v48, v49
	v_and_b32_e32 v64, v236, v64
	v_mfma_f32_32x32x16_bf16 v[0:15], v[224:227], v[68:71], v[0:15]
	ds_read2_b64 v[224:227], v73 offset0:12 offset1:14
	v_exp_f32_e32 v52, v52
	v_exp_f32_e32 v53, v53
	v_add_f32_e32 v232, v232, v50
	v_add_f32_e32 v233, v233, v51
	v_cvt_pk_bf16_f32 v65, v50, v51
	v_and_b32_e32 v65, v236, v65
	v_mfma_f32_32x32x16_bf16 v[16:31], v[228:231], v[68:71], v[16:31]
	ds_read2_b64 v[228:231], v74 offset0:44 offset1:46
	v_exp_f32_e32 v54, v54
	v_exp_f32_e32 v55, v55
	v_add_f32_e32 v232, v232, v52
	v_add_f32_e32 v233, v233, v53
	v_cvt_pk_bf16_f32 v66, v52, v53
	v_and_b32_e32 v66, v236, v66
	v_add_f32_e32 v232, v232, v54
	v_add_f32_e32 v233, v233, v55
	v_cvt_pk_bf16_f32 v67, v54, v55
	v_and_b32_e32 v67, v236, v67
	s_waitcnt lgkmcnt(7)
	v_mfma_f32_32x32x16_bf16 v[32:47], v[208:211], v[88:91], v[32:47]
	ds_read_b128 v[208:211], v72 offset:13888
	v_exp_f32_e32 v56, v56
	v_exp_f32_e32 v57, v57
	s_waitcnt lgkmcnt(7)
	v_mfma_f32_32x32x16_bf16 v[32:47], v[212:215], v[92:95], v[32:47]
	ds_read_b128 v[212:215], v72 offset:13920
	v_exp_f32_e32 v58, v58
	v_exp_f32_e32 v59, v59
	v_add_f32_e32 v232, v232, v56
	v_add_f32_e32 v233, v233, v57
	v_cvt_pk_bf16_f32 v68, v56, v57
	v_and_b32_e32 v68, v236, v68
	s_waitcnt lgkmcnt(7)
	v_mfma_f32_32x32x16_bf16 v[0:15], v[216:219], v[64:67], v[0:15]
	ds_read2_b64 v[216:219], v73 offset0:16 offset1:18
	v_exp_f32_e32 v60, v60
	v_exp_f32_e32 v61, v61
	v_add_f32_e32 v232, v232, v58
	v_add_f32_e32 v233, v233, v59
	v_cvt_pk_bf16_f32 v69, v58, v59
	v_and_b32_e32 v69, v236, v69
	s_waitcnt lgkmcnt(7)
	v_mfma_f32_32x32x16_bf16 v[16:31], v[220:223], v[64:67], v[16:31]
	ds_read2_b64 v[220:223], v74 offset0:48 offset1:50
	v_exp_f32_e32 v62, v62
	v_exp_f32_e32 v63, v63
	v_add_f32_e32 v232, v232, v60
	v_add_f32_e32 v233, v233, v61
	v_cvt_pk_bf16_f32 v70, v60, v61
	v_and_b32_e32 v70, v236, v70
	v_add_f32_e32 v232, v232, v62
	v_add_f32_e32 v233, v233, v63
	v_cvt_pk_bf16_f32 v71, v62, v63
	v_and_b32_e32 v71, v236, v71
	s_waitcnt lgkmcnt(7)
	v_mfma_f32_32x32x16_bf16 v[48:63], v[200:203], v[80:83], 0
	v_exp_f32_e32 v32, v32
	v_exp_f32_e32 v33, v33
	s_waitcnt lgkmcnt(6)
	v_mfma_f32_32x32x16_bf16 v[48:63], v[204:207], v[84:87], v[48:63]
	v_exp_f32_e32 v34, v34
	v_exp_f32_e32 v35, v35
	v_mov_b32_e32 v234, v32
	v_mov_b32_e32 v235, v33
	v_cvt_pk_bf16_f32 v64, v32, v33
	v_and_b32_e32 v64, v237, v64
	s_waitcnt lgkmcnt(5)
	v_mfma_f32_32x32x16_bf16 v[0:15], v[224:227], v[68:71], v[0:15]
	ds_read2_b64 v[224:227], v73 offset0:20 offset1:22
	v_exp_f32_e32 v36, v36
	v_exp_f32_e32 v37, v37
	v_add_f32_e32 v234, v234, v34
	v_add_f32_e32 v235, v235, v35
	v_cvt_pk_bf16_f32 v65, v34, v35
	v_and_b32_e32 v65, v237, v65
	s_waitcnt lgkmcnt(5)
	v_mfma_f32_32x32x16_bf16 v[16:31], v[228:231], v[68:71], v[16:31]
	ds_read2_b64 v[228:231], v74 offset0:52 offset1:54
	v_exp_f32_e32 v38, v38
	v_exp_f32_e32 v39, v39
	v_add_f32_e32 v234, v234, v36
	v_add_f32_e32 v235, v235, v37
	v_cvt_pk_bf16_f32 v66, v36, v37
	v_and_b32_e32 v66, v237, v66
	v_add_f32_e32 v234, v234, v38
	v_add_f32_e32 v235, v235, v39
	v_cvt_pk_bf16_f32 v67, v38, v39
	v_and_b32_e32 v67, v237, v67
	s_cmp_eq_u32 s45, 0
	s_cbranch_scc1 .Lt2_bias_nostage
	s_waitcnt vmcnt(3)
	ds_write_b128 v251, v[96:99]
	s_waitcnt vmcnt(2)
	ds_write_b128 v251, v[100:103] offset:9216
	s_waitcnt vmcnt(1)
	ds_write2_b64 v252, v[104:105], v[106:107] offset1:1
	s_waitcnt vmcnt(0)
	ds_write2_b64 v252, v[108:109], v[110:111] offset0:16 offset1:17
	s_mov_b32 s47, 1
	s_add_i32 s6, s44, 2
	s_add_i32 s7, s91, s44
	s_add_i32 s7, s7, 1
	s_add_i32 s0, s44, 1
	s_cmp_lt_i32 s0, s90
	s_cbranch_scc0 .Lt2_bias_nostage
	s_cmp_lt_u32 s0, s89
	s_cselect_b32 s0, s71, s75
	s_cselect_b32 s1, s72, s76
	s_cselect_b32 s4, s73, s77
	s_cselect_b32 s5, s74, s78
	s_cselect_b32 s6, s6, s7
	s_ashr_i32 s7, s6, 31
	s_lshl_b64 s[6:7], s[6:7], 14
	s_add_u32 s6, s6, s60
	s_addc_u32 s7, s7, s61
	s_add_u32 s0, s0, s6
	s_addc_u32 s1, s1, s7
	s_add_u32 s4, s4, s6
	s_addc_u32 s5, s5, s7
	global_load_dwordx4 v[96:99], v248, s[0:1]
	global_load_dwordx4 v[100:103], v249, s[0:1]
	global_load_dwordx4 v[104:107], v248, s[4:5]
	global_load_dwordx4 v[108:111], v249, s[4:5]

; #define LAS __attribute__((address_space(3)))
; #define MFMA32(a, b, c) __builtin_amdgcn_mfma_f32_32x32x16_bf16((a), (b), (c), 0, 0, 0)
; __device__ __forceinline__ float ex2(float x) { return __builtin_amdgcn_exp2f(x); }
; template <int MODE>
; __device__ __forceinline__ void attn_tile(const LAS unsigned char* Kb, const LAS unsigned char* Vb, const bf16x8_t (&qf)[4], f32x16 (&oacc)[2], float& l_run,
;                                           int r, int h, int dlt0, int dlt1, bool hiw) {
;     ...
; #pragma unroll
;     for (int mt = 0; mt < 4; ++mt) {
;         if (mt == 0) { if (hiw) __builtin_amdgcn_s_setprio(1); else __builtin_amdgcn_s_setprio(0); }
;         if (mt == 2) { if (hiw) __builtin_amdgcn_s_setprio(0); else __builtin_amdgcn_s_setprio(1); }
;         const int dl = mt < 2 ? dlt0 : dlt1;
;         f32x16 sacc = zero16();
; #pragma unroll
;         for (int ks = 0; ks < 4; ++ks) { const bf16x8_t ka = *(const LAS bf16x8_t*)(Kb + (32 * mt + r) * A_KSTR + 32 * ks + 16 * h); sacc = MFMA32(ka, qf[ks], sacc); }
; #pragma unroll
;         for (int i = 0; i < 16; ++i) {
;             float p;
;             if (MODE == 2) p = ex2(sacc[i]);
;             else if (MODE == 3) p = ex2(sacc[i] + __int_as_float(dl));
;             else { const int ci = 32 * mt + (i & 3) + 8 * (i >> 2); p = ((unsigned)(dl - ci) < ulim) ? ex2(sacc[i]) : 0.f; }
;             sacc[i] = p; ls += p;
;         }
; #pragma unroll
;         for (int s = 0; s < 2; ++s) {
;             const bf16x8_t pf = pack8(sacc, 8 * s);
; #pragma unroll
;             for (int dt = 0; dt < 2; ++dt) {
;                 const LAS unsigned char* vp = Vb + (32 * dt + r) * A_CVSTR + (32 * mt + 16 * s + 4 * h) * 2;
;                 const s16x4_t lo = *(const LAS s16x4_t*)vp, hi = *(const LAS s16x4_t*)(vp + 16);
;                 oacc[dt] = MFMA32(__builtin_shufflevector(lo, hi, 0, 1, 2, 3, 4, 5, 6, 7), pf, oacc[dt]);
;             }
;         }
;     }
.Lt2_d1:
	ds_read_b128 v[200:203], v72 offset:0
	ds_read_b128 v[204:207], v72 offset:32
	ds_read_b128 v[208:211], v72 offset:64
	ds_read_b128 v[212:215], v72 offset:96
	ds_read2_b64 v[216:219], v73 offset0:0 offset1:2
	ds_read2_b64 v[220:223], v74 offset0:32 offset1:34
	ds_read2_b64 v[224:227], v73 offset0:4 offset1:6
	ds_read2_b64 v[228:231], v74 offset0:36 offset1:38
	s_waitcnt lgkmcnt(7)
	v_mfma_f32_32x32x16_bf16 v[32:47], v[200:203], v[80:83], 0
	ds_read_b128 v[200:203], v72 offset:4608
	s_waitcnt lgkmcnt(7)
	v_mfma_f32_32x32x16_bf16 v[32:47], v[204:207], v[84:87], v[32:47]
	ds_read_b128 v[204:207], v72 offset:4640
	s_waitcnt lgkmcnt(7)
	v_mfma_f32_32x32x16_bf16 v[32:47], v[208:211], v[88:91], v[32:47]
	ds_read_b128 v[208:211], v72 offset:4672
	s_waitcnt lgkmcnt(7)
	v_mfma_f32_32x32x16_bf16 v[32:47], v[212:215], v[92:95], v[32:47]
	ds_read_b128 v[212:215], v72 offset:4704
	s_nop 7
	s_nop 3
	s_waitcnt lgkmcnt(3)
	v_mfma_f32_32x32x16_bf16 v[48:63], v[200:203], v[80:83], 0
	v_exp_f32_e32 v32, v32
	v_exp_f32_e32 v33, v33
	s_waitcnt lgkmcnt(2)
	v_mfma_f32_32x32x16_bf16 v[48:63], v[204:207], v[84:87], v[48:63]
	v_exp_f32_e32 v34, v34
	v_exp_f32_e32 v35, v35
	v_mov_b32_e32 v232, v32
	v_mov_b32_e32 v233, v33
	v_cvt_pk_bf16_f32 v64, v32, v33
	v_exp_f32_e32 v36, v36
	v_exp_f32_e32 v37, v37
	v_add_f32_e32 v232, v232, v34
	v_add_f32_e32 v233, v233, v35
	v_cvt_pk_bf16_f32 v65, v34, v35
	v_exp_f32_e32 v38, v38
	v_exp_f32_e32 v39, v39
	v_add_f32_e32 v232, v232, v36
	v_add_f32_e32 v233, v233, v37
	v_cvt_pk_bf16_f32 v66, v36, v37
	v_add_f32_e32 v232, v232, v38
	v_add_f32_e32 v233, v233, v39
	v_cvt_pk_bf16_f32 v67, v38, v39
	s_cmp_eq_u32 s45, 0
	s_cbranch_scc1 .Lt2_d1_nostage
	s_waitcnt vmcnt(3)
	ds_write_b128 v251, v[96:99]
	s_waitcnt vmcnt(2)
	ds_write_b128 v251, v[100:103] offset:9216
	s_waitcnt vmcnt(1)
	ds_write2_b64 v252, v[104:105], v[106:107] offset1:1
	s_waitcnt vmcnt(0)
	ds_write2_b64 v252, v[108:109], v[110:111] offset0:16 offset1:17
	s_mov_b32 s47, 1
	s_add_i32 s6, s44, 2
	s_add_i32 s7, s91, s44
	s_add_i32 s7, s7, 1
	s_add_i32 s0, s44, 1
	s_cmp_lt_i32 s0, s90
	s_cbranch_scc0 .Lt2_d1_nostage
	s_cmp_lt_u32 s0, s89
	s_cselect_b32 s0, s71, s75
	s_cselect_b32 s1, s72, s76
	s_cselect_b32 s4, s73, s77
	s_cselect_b32 s5, s74, s78
	s_cselect_b32 s6, s6, s7
	s_ashr_i32 s7, s6, 31
	s_lshl_b64 s[6:7], s[6:7], 14
	s_add_u32 s6, s6, s60
	s_addc_u32 s7, s7, s61
	s_add_u32 s0, s0, s6
	s_addc_u32 s1, s1, s7
	s_add_u32 s4, s4, s6
	s_addc_u32 s5, s5, s7
	global_load_dwordx4 v[96:99], v248, s[0:1]
	global_load_dwordx4 v[100:103], v249, s[0:1]
	global_load_dwordx4 v[104:107], v248, s[4:5]
	global_load_dwordx4 v[108:111], v249, s[4:5]

; #define LAS __attribute__((address_space(3)))
; #define MFMA32(a, b, c) __builtin_amdgcn_mfma_f32_32x32x16_bf16((a), (b), (c), 0, 0, 0)
; __device__ __forceinline__ float ex2(float x) { return __builtin_amdgcn_exp2f(x); }
; template <int MODE>
; __device__ __forceinline__ void attn_tile(const LAS unsigned char* Kb, const LAS unsigned char* Vb, const bf16x8_t (&qf)[4], f32x16 (&oacc)[2], float& l_run,
;                                           int r, int h, int dlt0, int dlt1, bool hiw) {
;     ...
; #pragma unroll
;     for (int mt = 0; mt < 4; ++mt) {
;         if (mt == 0) { if (hiw) __builtin_amdgcn_s_setprio(1); else __builtin_amdgcn_s_setprio(0); }
;         if (mt == 2) { if (hiw) __builtin_amdgcn_s_setprio(0); else __builtin_amdgcn_s_setprio(1); }
;         const int dl = mt < 2 ? dlt0 : dlt1;
;         f32x16 sacc = zero16();
; #pragma unroll
;         for (int ks = 0; ks < 4; ++ks) { const bf16x8_t ka = *(const LAS bf16x8_t*)(Kb + (32 * mt + r) * A_KSTR + 32 * ks + 16 * h); sacc = MFMA32(ka, qf[ks], sacc); }
; #pragma unroll
;         for (int i = 0; i < 16; ++i) {
;             float p;
;             if (MODE == 2) p = ex2(sacc[i]);
;             else if (MODE == 3) p = ex2(sacc[i] + __int_as_float(dl));
;             else { const int ci = 32 * mt + (i & 3) + 8 * (i >> 2); p = ((unsigned)(dl - ci) < ulim) ? ex2(sacc[i]) : 0.f; }
;             sacc[i] = p; ls += p;
;         }
; #pragma unroll
;         for (int s = 0; s < 2; ++s) {
;             const bf16x8_t pf = pack8(sacc, 8 * s);
; #pragma unroll
;             for (int dt = 0; dt < 2; ++dt) {
;                 const LAS unsigned char* vp = Vb + (32 * dt + r) * A_CVSTR + (32 * mt + 16 * s + 4 * h) * 2;
;                 const s16x4_t lo = *(const LAS s16x4_t*)vp, hi = *(const LAS s16x4_t*)(vp + 16);
;                 oacc[dt] = MFMA32(__builtin_shufflevector(lo, hi, 0, 1, 2, 3, 4, 5, 6, 7), pf, oacc[dt]);
;             }
;         }
;     }
.Lt2_d2:
	ds_read_b128 v[200:203], v72 offset:0
	ds_read_b128 v[204:207], v72 offset:32
	ds_read_b128 v[208:211], v72 offset:64
	ds_read_b128 v[212:215], v72 offset:96
	ds_read2_b64 v[216:219], v73 offset0:0 offset1:2
	ds_read2_b64 v[220:223], v74 offset0:32 offset1:34
	ds_read2_b64 v[224:227], v73 offset0:4 offset1:6
	ds_read2_b64 v[228:231], v74 offset0:36 offset1:38
	s_waitcnt lgkmcnt(7)
	v_mfma_f32_32x32x16_bf16 v[32:47], v[200:203], v[80:83], 0
	ds_read_b128 v[200:203], v72 offset:4608
	s_waitcnt lgkmcnt(7)
	v_mfma_f32_32x32x16_bf16 v[32:47], v[204:207], v[84:87], v[32:47]
	ds_read_b128 v[204:207], v72 offset:4640
	s_waitcnt lgkmcnt(7)
	v_mfma_f32_32x32x16_bf16 v[32:47], v[208:211], v[88:91], v[32:47]
	ds_read_b128 v[208:211], v72 offset:4672
	s_waitcnt lgkmcnt(7)
	v_mfma_f32_32x32x16_bf16 v[32:47], v[212:215], v[92:95], v[32:47]
	ds_read_b128 v[212:215], v72 offset:4704
	s_nop 7
	s_nop 3
	s_waitcnt lgkmcnt(3)
	v_mfma_f32_32x32x16_bf16 v[48:63], v[200:203], v[80:83], 0
	ds_read_b128 v[200:203], v72 offset:9216
	v_exp_f32_e32 v32, v32
	v_exp_f32_e32 v33, v33
	s_waitcnt lgkmcnt(3)
	v_mfma_f32_32x32x16_bf16 v[48:63], v[204:207], v[84:87], v[48:63]
	ds_read_b128 v[204:207], v72 offset:9248
	v_exp_f32_e32 v34, v34
	v_exp_f32_e32 v35, v35
	v_mov_b32_e32 v232, v32
	v_mov_b32_e32 v233, v33
	v_cvt_pk_bf16_f32 v64, v32, v33
	v_exp_f32_e32 v36, v36
	v_exp_f32_e32 v37, v37
	v_add_f32_e32 v232, v232, v34
	v_add_f32_e32 v233, v233, v35
	v_cvt_pk_bf16_f32 v65, v34, v35
	v_exp_f32_e32 v38, v38
	v_exp_f32_e32 v39, v39
	v_add_f32_e32 v232, v232, v36
	v_add_f32_e32 v233, v233, v37
	v_cvt_pk_bf16_f32 v66, v36, v37
	v_add_f32_e32 v232, v232, v38
	v_add_f32_e32 v233, v233, v39
	v_cvt_pk_bf16_f32 v67, v38, v39
	s_waitcnt lgkmcnt(3)
	v_mfma_f32_32x32x16_bf16 v[48:63], v[208:211], v[88:91], v[48:63]
	ds_read_b128 v[208:211], v72 offset:9280
	v_exp_f32_e32 v40, v40
	v_exp_f32_e32 v41, v41
	s_waitcnt lgkmcnt(3)
	v_mfma_f32_32x32x16_bf16 v[48:63], v[212:215], v[92:95], v[48:63]
	ds_read_b128 v[212:215], v72 offset:9312
	v_exp_f32_e32 v42, v42
	v_exp_f32_e32 v43, v43
	v_add_f32_e32 v232, v232, v40
	v_add_f32_e32 v233, v233, v41
	v_cvt_pk_bf16_f32 v68, v40, v41
	v_mfma_f32_32x32x16_bf16 v[0:15], v[216:219], v[64:67], v[0:15]
	ds_read2_b64 v[216:219], v73 offset0:8 offset1:10
	v_exp_f32_e32 v44, v44
	v_exp_f32_e32 v45, v45
	v_add_f32_e32 v232, v232, v42
	v_add_f32_e32 v233, v233, v43
	v_cvt_pk_bf16_f32 v69, v42, v43
	v_mfma_f32_32x32x16_bf16 v[16:31], v[220:223], v[64:67], v[16:31]
	ds_read2_b64 v[220:223], v74 offset0:40 offset1:42
	v_exp_f32_e32 v46, v46
	v_exp_f32_e32 v47, v47
	v_add_f32_e32 v232, v232, v44
	v_add_f32_e32 v233, v233, v45
	v_cvt_pk_bf16_f32 v70, v44, v45
	v_add_f32_e32 v232, v232, v46
	v_add_f32_e32 v233, v233, v47
	v_cvt_pk_bf16_f32 v71, v46, v47
	s_waitcnt lgkmcnt(5)
	v_mfma_f32_32x32x16_bf16 v[32:47], v[200:203], v[80:83], 0
	v_exp_f32_e32 v48, v48
	v_exp_f32_e32 v49, v49
	s_waitcnt lgkmcnt(4)
	v_mfma_f32_32x32x16_bf16 v[32:47], v[204:207], v[84:87], v[32:47]
	v_exp_f32_e32 v50, v50
	v_exp_f32_e32 v51, v51
	v_add_f32_e32 v232, v232, v48
	v_add_f32_e32 v233, v233, v49
	v_cvt_pk_bf16_f32 v64, v48, v49
	v_mfma_f32_32x32x16_bf16 v[0:15], v[224:227], v[68:71], v[0:15]
	ds_read2_b64 v[224:227], v73 offset0:12 offset1:14
	v_exp_f32_e32 v52, v52
	v_exp_f32_e32 v53, v53
	v_add_f32_e32 v232, v232, v50
	v_add_f32_e32 v233, v233, v51
	v_cvt_pk_bf16_f32 v65, v50, v51
	v_mfma_f32_32x32x16_bf16 v[16:31], v[228:231], v[68:71], v[16:31]
	ds_read2_b64 v[228:231], v74 offset0:44 offset1:46
	v_exp_f32_e32 v54, v54
	v_exp_f32_e32 v55, v55
	v_add_f32_e32 v232, v232, v52
	v_add_f32_e32 v233, v233, v53
	v_cvt_pk_bf16_f32 v66, v52, v53
	v_add_f32_e32 v232, v232, v54
	v_add_f32_e32 v233, v233, v55
	v_cvt_pk_bf16_f32 v67, v54, v55
	s_cmp_eq_u32 s45, 0
	s_cbranch_scc1 .Lt2_d2_nostage
	s_waitcnt vmcnt(3)
	ds_write_b128 v251, v[96:99]
	s_waitcnt vmcnt(2)
	ds_write_b128 v251, v[100:103] offset:9216
	s_waitcnt vmcnt(1)
	ds_write2_b64 v252, v[104:105], v[106:107] offset1:1
	s_waitcnt vmcnt(0)
	ds_write2_b64 v252, v[108:109], v[110:111] offset0:16 offset1:17
	s_mov_b32 s47, 1
	s_add_i32 s6, s44, 2
	s_add_i32 s7, s91, s44
	s_add_i32 s7, s7, 1
	s_add_i32 s0, s44, 1
	s_cmp_lt_i32 s0, s90
	s_cbranch_scc0 .Lt2_d2_nostage
	s_cmp_lt_u32 s0, s89
	s_cselect_b32 s0, s71, s75
	s_cselect_b32 s1, s72, s76
	s_cselect_b32 s4, s73, s77
	s_cselect_b32 s5, s74, s78
	s_cselect_b32 s6, s6, s7
	s_ashr_i32 s7, s6, 31
	s_lshl_b64 s[6:7], s[6:7], 14
	s_add_u32 s6, s6, s60
	s_addc_u32 s7, s7, s61
	s_add_u32 s0, s0, s6
	s_addc_u32 s1, s1, s7
	s_add_u32 s4, s4, s6
	s_addc_u32 s5, s5, s7
	global_load_dwordx4 v[96:99], v248, s[0:1]
	global_load_dwordx4 v[100:103], v249, s[0:1]
	global_load_dwordx4 v[104:107], v248, s[4:5]
	global_load_dwordx4 v[108:111], v249, s[4:5]

; #define LAS __attribute__((address_space(3)))
; #define MFMA32(a, b, c) __builtin_amdgcn_mfma_f32_32x32x16_bf16((a), (b), (c), 0, 0, 0)
; __device__ __forceinline__ float ex2(float x) { return __builtin_amdgcn_exp2f(x); }
; template <int MODE>
; __device__ __forceinline__ void attn_tile(const LAS unsigned char* Kb, const LAS unsigned char* Vb, const bf16x8_t (&qf)[4], f32x16 (&oacc)[2], float& l_run,
;                                           int r, int h, int dlt0, int dlt1, bool hiw) {
;     ...
; #pragma unroll
;     for (int mt = 0; mt < 4; ++mt) {
;         if (mt == 0) { if (hiw) __builtin_amdgcn_s_setprio(1); else __builtin_amdgcn_s_setprio(0); }
;         if (mt == 2) { if (hiw) __builtin_amdgcn_s_setprio(0); else __builtin_amdgcn_s_setprio(1); }
;         const int dl = mt < 2 ? dlt0 : dlt1;
;         f32x16 sacc = zero16();
; #pragma unroll
;         for (int ks = 0; ks < 4; ++ks) { const bf16x8_t ka = *(const LAS bf16x8_t*)(Kb + (32 * mt + r) * A_KSTR + 32 * ks + 16 * h); sacc = MFMA32(ka, qf[ks], sacc); }
; #pragma unroll
;         for (int i = 0; i < 16; ++i) {
;             float p;
;             if (MODE == 2) p = ex2(sacc[i]);
;             else if (MODE == 3) p = ex2(sacc[i] + __int_as_float(dl));
;             else { const int ci = 32 * mt + (i & 3) + 8 * (i >> 2); p = ((unsigned)(dl - ci) < ulim) ? ex2(sacc[i]) : 0.f; }
;             sacc[i] = p; ls += p;
;         }
; #pragma unroll
;         for (int s = 0; s < 2; ++s) {
;             const bf16x8_t pf = pack8(sacc, 8 * s);
; #pragma unroll
;             for (int dt = 0; dt < 2; ++dt) {
;                 const LAS unsigned char* vp = Vb + (32 * dt + r) * A_CVSTR + (32 * mt + 16 * s + 4 * h) * 2;
;                 const s16x4_t lo = *(const LAS s16x4_t*)vp, hi = *(const LAS s16x4_t*)(vp + 16);
;                 oacc[dt] = MFMA32(__builtin_shufflevector(lo, hi, 0, 1, 2, 3, 4, 5, 6, 7), pf, oacc[dt]);
;             }
;         }
;     }
.Lt2_e0:
	ds_read_b128 v[200:203], v72 offset:0
	ds_read_b128 v[204:207], v72 offset:32
	ds_read_b128 v[208:211], v72 offset:64
	ds_read_b128 v[212:215], v72 offset:96
	ds_read2_b64 v[216:219], v73 offset0:0 offset1:2
	ds_read2_b64 v[220:223], v74 offset0:32 offset1:34
	ds_read2_b64 v[224:227], v73 offset0:4 offset1:6
	ds_read2_b64 v[228:231], v74 offset0:36 offset1:38
	s_waitcnt lgkmcnt(7)
	v_mfma_f32_32x32x16_bf16 v[32:47], v[200:203], v[80:83], 0
	ds_read_b128 v[200:203], v72 offset:4608
	s_waitcnt lgkmcnt(7)
	v_mfma_f32_32x32x16_bf16 v[32:47], v[204:207], v[84:87], v[32:47]
	ds_read_b128 v[204:207], v72 offset:4640
	s_waitcnt lgkmcnt(7)
	v_mfma_f32_32x32x16_bf16 v[32:47], v[208:211], v[88:91], v[32:47]
	ds_read_b128 v[208:211], v72 offset:4672
	s_waitcnt lgkmcnt(7)
	v_mfma_f32_32x32x16_bf16 v[32:47], v[212:215], v[92:95], v[32:47]
	ds_read_b128 v[212:215], v72 offset:4704
	s_nop 7
	s_nop 3
	s_waitcnt lgkmcnt(3)
	v_mfma_f32_32x32x16_bf16 v[48:63], v[200:203], v[80:83], 0
	ds_read_b128 v[200:203], v72 offset:9216
	v_cmp_le_i32_e64 s[0:1], 0, v250
	v_cmp_le_i32_e64 s[4:5], 1, v250
	v_exp_f32_e32 v32, v32
	v_exp_f32_e32 v33, v33
	s_waitcnt lgkmcnt(3)
	v_mfma_f32_32x32x16_bf16 v[48:63], v[204:207], v[84:87], v[48:63]
	ds_read_b128 v[204:207], v72 offset:9248
	v_cmp_le_i32_e64 s[6:7], 2, v250
	v_cmp_le_i32_e64 s[48:49], 3, v250
	v_exp_f32_e32 v34, v34
	v_exp_f32_e32 v35, v35
	v_cndmask_b32_e64 v32, v32, 0, s[0:1]
	v_cndmask_b32_e64 v33, v33, 0, s[4:5]
	v_mov_b32_e32 v232, v32
	v_mov_b32_e32 v233, v33
	v_cvt_pk_bf16_f32 v64, v32, v33
	v_cmp_le_i32_e64 s[0:1], 8, v250
	v_cmp_le_i32_e64 s[4:5], 9, v250
	v_exp_f32_e32 v36, v36
	v_exp_f32_e32 v37, v37
	v_cndmask_b32_e64 v34, v34, 0, s[6:7]
	v_cndmask_b32_e64 v35, v35, 0, s[48:49]
	v_add_f32_e32 v232, v232, v34
	v_add_f32_e32 v233, v233, v35
	v_cvt_pk_bf16_f32 v65, v34, v35
	v_cmp_le_i32_e64 s[6:7], 10, v250
	v_cmp_le_i32_e64 s[48:49], 11, v250
	v_exp_f32_e32 v38, v38
	v_exp_f32_e32 v39, v39
	v_cndmask_b32_e64 v36, v36, 0, s[0:1]
	v_cndmask_b32_e64 v37, v37, 0, s[4:5]
	v_add_f32_e32 v232, v232, v36
	v_add_f32_e32 v233, v233, v37
	v_cvt_pk_bf16_f32 v66, v36, v37
	v_cndmask_b32_e64 v38, v38, 0, s[6:7]
	v_cndmask_b32_e64 v39, v39, 0, s[48:49]
	v_add_f32_e32 v232, v232, v38
	v_add_f32_e32 v233, v233, v39
	v_cvt_pk_bf16_f32 v67, v38, v39
	s_waitcnt lgkmcnt(3)
	v_mfma_f32_32x32x16_bf16 v[48:63], v[208:211], v[88:91], v[48:63]
	ds_read_b128 v[208:211], v72 offset:9280
	v_cmp_le_i32_e64 s[0:1], 16, v250
	v_cmp_le_i32_e64 s[4:5], 17, v250
	v_exp_f32_e32 v40, v40
	v_exp_f32_e32 v41, v41
	s_waitcnt lgkmcnt(3)
	v_mfma_f32_32x32x16_bf16 v[48:63], v[212:215], v[92:95], v[48:63]
	ds_read_b128 v[212:215], v72 offset:9312
	v_cmp_le_i32_e64 s[6:7], 18, v250
	v_cmp_le_i32_e64 s[48:49], 19, v250
	v_exp_f32_e32 v42, v42
	v_exp_f32_e32 v43, v43
	v_cndmask_b32_e64 v40, v40, 0, s[0:1]
	v_cndmask_b32_e64 v41, v41, 0, s[4:5]
	v_add_f32_e32 v232, v232, v40
	v_add_f32_e32 v233, v233, v41
	v_cvt_pk_bf16_f32 v68, v40, v41
	v_mfma_f32_32x32x16_bf16 v[0:15], v[216:219], v[64:67], v[0:15]
	ds_read2_b64 v[216:219], v73 offset0:8 offset1:10
	v_cmp_le_i32_e64 s[0:1], 24, v250
	v_cmp_le_i32_e64 s[4:5], 25, v250
	v_exp_f32_e32 v44, v44
	v_exp_f32_e32 v45, v45
	v_cndmask_b32_e64 v42, v42, 0, s[6:7]
	v_cndmask_b32_e64 v43, v43, 0, s[48:49]
	v_add_f32_e32 v232, v232, v42
	v_add_f32_e32 v233, v233, v43
	v_cvt_pk_bf16_f32 v69, v42, v43
	v_mfma_f32_32x32x16_bf16 v[16:31], v[220:223], v[64:67], v[16:31]
	ds_read2_b64 v[220:223], v74 offset0:40 offset1:42
	v_cmp_le_i32_e64 s[6:7], 26, v250
	v_cmp_le_i32_e64 s[48:49], 27, v250
	v_exp_f32_e32 v46, v46
	v_exp_f32_e32 v47, v47
	v_cndmask_b32_e64 v44, v44, 0, s[0:1]
	v_cndmask_b32_e64 v45, v45, 0, s[4:5]
	v_add_f32_e32 v232, v232, v44
	v_add_f32_e32 v233, v233, v45
	v_cvt_pk_bf16_f32 v70, v44, v45
	v_cndmask_b32_e64 v46, v46, 0, s[6:7]
	v_cndmask_b32_e64 v47, v47, 0, s[48:49]
	v_add_f32_e32 v232, v232, v46
	v_add_f32_e32 v233, v233, v47
	v_cvt_pk_bf16_f32 v71, v46, v47
	s_waitcnt lgkmcnt(5)
	v_mfma_f32_32x32x16_bf16 v[32:47], v[200:203], v[80:83], 0
	ds_read_b128 v[200:203], v72 offset:13824
	v_exp_f32_e32 v48, v48
	v_exp_f32_e32 v49, v49
	s_waitcnt lgkmcnt(5)
; #define LAS __attribute__((address_space(3)))
; #define MFMA32(a, b, c) __builtin_amdgcn_mfma_f32_32x32x16_bf16((a), (b), (c), 0, 0, 0)
; __device__ __forceinline__ float ex2(float x) { return __builtin_amdgcn_exp2f(x); }
; template <int MODE>
; __device__ __forceinline__ void attn_tile(const LAS unsigned char* Kb, const LAS unsigned char* Vb, const bf16x8_t (&qf)[4], f32x16 (&oacc)[2], float& l_run,
;                                           int r, int h, int dlt0, int dlt1, bool hiw) {
;     ...
; #pragma unroll
;     for (int mt = 0; mt < 4; ++mt) {
;         if (mt == 0) { if (hiw) __builtin_amdgcn_s_setprio(1); else __builtin_amdgcn_s_setprio(0); }
;         if (mt == 2) { if (hiw) __builtin_amdgcn_s_setprio(0); else __builtin_amdgcn_s_setprio(1); }
;         const int dl = mt < 2 ? dlt0 : dlt1;
;         f32x16 sacc = zero16();
; #pragma unroll
;         for (int ks = 0; ks < 4; ++ks) { const bf16x8_t ka = *(const LAS bf16x8_t*)(Kb + (32 * mt + r) * A_KSTR + 32 * ks + 16 * h); sacc = MFMA32(ka, qf[ks], sacc); }
; #pragma unroll
;         for (int i = 0; i < 16; ++i) {
;             float p;
;             if (MODE == 2) p = ex2(sacc[i]);
;             else if (MODE == 3) p = ex2(sacc[i] + __int_as_float(dl));
;             else { const int ci = 32 * mt + (i & 3) + 8 * (i >> 2); p = ((unsigned)(dl - ci) < ulim) ? ex2(sacc[i]) : 0.f; }
;             sacc[i] = p; ls += p;
;         }
; #pragma unroll
;         for (int s = 0; s < 2; ++s) {
;             const bf16x8_t pf = pack8(sacc, 8 * s);
; #pragma unroll
;             for (int dt = 0; dt < 2; ++dt) {
;                 const LAS unsigned char* vp = Vb + (32 * dt + r) * A_CVSTR + (32 * mt + 16 * s + 4 * h) * 2;
;                 const s16x4_t lo = *(const LAS s16x4_t*)vp, hi = *(const LAS s16x4_t*)(vp + 16);
;                 oacc[dt] = MFMA32(__builtin_shufflevector(lo, hi, 0, 1, 2, 3, 4, 5, 6, 7), pf, oacc[dt]);
;             }
;         }
;     }
	v_mfma_f32_32x32x16_bf16 v[32:47], v[204:207], v[84:87], v[32:47]
	ds_read_b128 v[204:207], v72 offset:13856
	v_exp_f32_e32 v50, v50
	v_exp_f32_e32 v51, v51
	v_add_f32_e32 v232, v232, v48
	v_add_f32_e32 v233, v233, v49
	v_cvt_pk_bf16_f32 v64, v48, v49
	v_mfma_f32_32x32x16_bf16 v[0:15], v[224:227], v[68:71], v[0:15]
	ds_read2_b64 v[224:227], v73 offset0:12 offset1:14
	v_exp_f32_e32 v52, v52
	v_exp_f32_e32 v53, v53
	v_add_f32_e32 v232, v232, v50
	v_add_f32_e32 v233, v233, v51
	v_cvt_pk_bf16_f32 v65, v50, v51
	v_mfma_f32_32x32x16_bf16 v[16:31], v[228:231], v[68:71], v[16:31]
	ds_read2_b64 v[228:231], v74 offset0:44 offset1:46
	v_exp_f32_e32 v54, v54
	v_exp_f32_e32 v55, v55
	v_add_f32_e32 v232, v232, v52
	v_add_f32_e32 v233, v233, v53
	v_cvt_pk_bf16_f32 v66, v52, v53
	v_add_f32_e32 v232, v232, v54
	v_add_f32_e32 v233, v233, v55
	v_cvt_pk_bf16_f32 v67, v54, v55
	s_waitcnt lgkmcnt(7)
	v_mfma_f32_32x32x16_bf16 v[32:47], v[208:211], v[88:91], v[32:47]
	ds_read_b128 v[208:211], v72 offset:13888
	v_exp_f32_e32 v56, v56
	v_exp_f32_e32 v57, v57
	s_waitcnt lgkmcnt(7)
	v_mfma_f32_32x32x16_bf16 v[32:47], v[212:215], v[92:95], v[32:47]
	ds_read_b128 v[212:215], v72 offset:13920
	v_exp_f32_e32 v58, v58
	v_exp_f32_e32 v59, v59
	v_add_f32_e32 v232, v232, v56
	v_add_f32_e32 v233, v233, v57
	v_cvt_pk_bf16_f32 v68, v56, v57
	s_waitcnt lgkmcnt(7)
	v_mfma_f32_32x32x16_bf16 v[0:15], v[216:219], v[64:67], v[0:15]
	ds_read2_b64 v[216:219], v73 offset0:16 offset1:18
	v_exp_f32_e32 v60, v60
	v_exp_f32_e32 v61, v61
	v_add_f32_e32 v232, v232, v58
	v_add_f32_e32 v233, v233, v59
	v_cvt_pk_bf16_f32 v69, v58, v59
	s_waitcnt lgkmcnt(7)
	v_mfma_f32_32x32x16_bf16 v[16:31], v[220:223], v[64:67], v[16:31]
	ds_read2_b64 v[220:223], v74 offset0:48 offset1:50
	v_exp_f32_e32 v62, v62
	v_exp_f32_e32 v63, v63
	v_add_f32_e32 v232, v232, v60
	v_add_f32_e32 v233, v233, v61
	v_cvt_pk_bf16_f32 v70, v60, v61
	v_add_f32_e32 v232, v232, v62
	v_add_f32_e32 v233, v233, v63
	v_cvt_pk_bf16_f32 v71, v62, v63
	s_waitcnt lgkmcnt(7)
	v_mfma_f32_32x32x16_bf16 v[48:63], v[200:203], v[80:83], 0
	v_exp_f32_e32 v32, v32
	v_exp_f32_e32 v33, v33
	s_waitcnt lgkmcnt(6)
	v_mfma_f32_32x32x16_bf16 v[48:63], v[204:207], v[84:87], v[48:63]
	v_exp_f32_e32 v34, v34
	v_exp_f32_e32 v35, v35
	v_add_f32_e32 v232, v232, v32
	v_add_f32_e32 v233, v233, v33
	v_cvt_pk_bf16_f32 v64, v32, v33
	s_waitcnt lgkmcnt(5)
	v_mfma_f32_32x32x16_bf16 v[0:15], v[224:227], v[68:71], v[0:15]
	ds_read2_b64 v[224:227], v73 offset0:20 offset1:22
	v_exp_f32_e32 v36, v36
	v_exp_f32_e32 v37, v37
	v_add_f32_e32 v232, v232, v34
	v_add_f32_e32 v233, v233, v35
	v_cvt_pk_bf16_f32 v65, v34, v35
	s_waitcnt lgkmcnt(5)
	v_mfma_f32_32x32x16_bf16 v[16:31], v[228:231], v[68:71], v[16:31]
	ds_read2_b64 v[228:231], v74 offset0:52 offset1:54
	v_exp_f32_e32 v38, v38
	v_exp_f32_e32 v39, v39
	v_add_f32_e32 v232, v232, v36
	v_add_f32_e32 v233, v233, v37
	v_cvt_pk_bf16_f32 v66, v36, v37
	v_add_f32_e32 v232, v232, v38
	v_add_f32_e32 v233, v233, v39
	v_cvt_pk_bf16_f32 v67, v38, v39
	s_cmp_eq_u32 s45, 0
	s_cbranch_scc1 .Lt2_e0_nostage
	s_waitcnt vmcnt(3)
	ds_write_b128 v251, v[96:99]
	s_waitcnt vmcnt(2)
	ds_write_b128 v251, v[100:103] offset:9216
	s_waitcnt vmcnt(1)
	ds_write2_b64 v252, v[104:105], v[106:107] offset1:1
	s_waitcnt vmcnt(0)
	ds_write2_b64 v252, v[108:109], v[110:111] offset0:16 offset1:17
	s_mov_b32 s47, 1
	s_add_i32 s6, s44, 2
	s_add_i32 s7, s91, s44
	s_add_i32 s7, s7, 1
	s_add_i32 s0, s44, 1
	s_cmp_lt_i32 s0, s90
	s_cbranch_scc0 .Lt2_e0_nostage
	s_cmp_lt_u32 s0, s89
	s_cselect_b32 s0, s71, s75
	s_cselect_b32 s1, s72, s76
	s_cselect_b32 s4, s73, s77
	s_cselect_b32 s5, s74, s78
	s_cselect_b32 s6, s6, s7
	s_ashr_i32 s7, s6, 31
	s_lshl_b64 s[6:7], s[6:7], 14
	s_add_u32 s6, s6, s60
	s_addc_u32 s7, s7, s61
	s_add_u32 s0, s0, s6
	s_addc_u32 s1, s1, s7
	s_add_u32 s4, s4, s6
	s_addc_u32 s5, s5, s7
	global_load_dwordx4 v[96:99], v248, s[0:1]
	global_load_dwordx4 v[100:103], v249, s[0:1]
	global_load_dwordx4 v[104:107], v248, s[4:5]
	global_load_dwordx4 v[108:111], v249, s[4:5]

; #define LAS __attribute__((address_space(3)))
; #define MFMA32(a, b, c) __builtin_amdgcn_mfma_f32_32x32x16_bf16((a), (b), (c), 0, 0, 0)
; __device__ __forceinline__ float ex2(float x) { return __builtin_amdgcn_exp2f(x); }
; template <int MODE>
; __device__ __forceinline__ void attn_tile(const LAS unsigned char* Kb, const LAS unsigned char* Vb, const bf16x8_t (&qf)[4], f32x16 (&oacc)[2], float& l_run,
;                                           int r, int h, int dlt0, int dlt1, bool hiw) {
;     ...
; #pragma unroll
;     for (int mt = 0; mt < 4; ++mt) {
;         if (mt == 0) { if (hiw) __builtin_amdgcn_s_setprio(1); else __builtin_amdgcn_s_setprio(0); }
;         if (mt == 2) { if (hiw) __builtin_amdgcn_s_setprio(0); else __builtin_amdgcn_s_setprio(1); }
;         const int dl = mt < 2 ? dlt0 : dlt1;
;         f32x16 sacc = zero16();
; #pragma unroll
;         for (int ks = 0; ks < 4; ++ks) { const bf16x8_t ka = *(const LAS bf16x8_t*)(Kb + (32 * mt + r) * A_KSTR + 32 * ks + 16 * h); sacc = MFMA32(ka, qf[ks], sacc); }
; #pragma unroll
;         for (int i = 0; i < 16; ++i) {
;             float p;
;             if (MODE == 2) p = ex2(sacc[i]);
;             else if (MODE == 3) p = ex2(sacc[i] + __int_as_float(dl));
;             else { const int ci = 32 * mt + (i & 3) + 8 * (i >> 2); p = ((unsigned)(dl - ci) < ulim) ? ex2(sacc[i]) : 0.f; }
;             sacc[i] = p; ls += p;
;         }
; #pragma unroll
;         for (int s = 0; s < 2; ++s) {
;             const bf16x8_t pf = pack8(sacc, 8 * s);
; #pragma unroll
;             for (int dt = 0; dt < 2; ++dt) {
;                 const LAS unsigned char* vp = Vb + (32 * dt + r) * A_CVSTR + (32 * mt + 16 * s + 4 * h) * 2;
;                 const s16x4_t lo = *(const LAS s16x4_t*)vp, hi = *(const LAS s16x4_t*)(vp + 16);
;                 oacc[dt] = MFMA32(__builtin_shufflevector(lo, hi, 0, 1, 2, 3, 4, 5, 6, 7), pf, oacc[dt]);
;             }
;         }
;     }
.Lt2_e1:
	ds_read_b128 v[200:203], v72 offset:4608
	ds_read_b128 v[204:207], v72 offset:4640
	ds_read_b128 v[208:211], v72 offset:4672
	ds_read_b128 v[212:215], v72 offset:4704
	ds_read2_b64 v[216:219], v73 offset0:8 offset1:10
	ds_read2_b64 v[220:223], v74 offset0:40 offset1:42
	ds_read2_b64 v[224:227], v73 offset0:12 offset1:14
	ds_read2_b64 v[228:231], v74 offset0:44 offset1:46
	s_waitcnt lgkmcnt(7)
	v_mfma_f32_32x32x16_bf16 v[32:47], v[200:203], v[80:83], 0
	ds_read_b128 v[200:203], v72 offset:9216
	s_waitcnt lgkmcnt(7)
	v_mfma_f32_32x32x16_bf16 v[32:47], v[204:207], v[84:87], v[32:47]
	ds_read_b128 v[204:207], v72 offset:9248
	s_waitcnt lgkmcnt(7)
	v_mfma_f32_32x32x16_bf16 v[32:47], v[208:211], v[88:91], v[32:47]
	ds_read_b128 v[208:211], v72 offset:9280
	s_waitcnt lgkmcnt(7)
	v_mfma_f32_32x32x16_bf16 v[32:47], v[212:215], v[92:95], v[32:47]
	ds_read_b128 v[212:215], v72 offset:9312
	s_nop 7
	s_nop 3
	s_waitcnt lgkmcnt(3)
	v_mfma_f32_32x32x16_bf16 v[48:63], v[200:203], v[80:83], 0
	ds_read_b128 v[200:203], v72 offset:13824
	v_cmp_le_i32_e64 s[0:1], 0, v250
	v_cmp_le_i32_e64 s[4:5], 1, v250
	v_exp_f32_e32 v32, v32
	v_exp_f32_e32 v33, v33
	s_waitcnt lgkmcnt(3)
	v_mfma_f32_32x32x16_bf16 v[48:63], v[204:207], v[84:87], v[48:63]
	ds_read_b128 v[204:207], v72 offset:13856
	v_cmp_le_i32_e64 s[6:7], 2, v250
	v_cmp_le_i32_e64 s[48:49], 3, v250
	v_exp_f32_e32 v34, v34
	v_exp_f32_e32 v35, v35
	v_cndmask_b32_e64 v32, v32, 0, s[0:1]
	v_cndmask_b32_e64 v33, v33, 0, s[4:5]
	v_mov_b32_e32 v232, v32
	v_mov_b32_e32 v233, v33
	v_cvt_pk_bf16_f32 v64, v32, v33
	v_cmp_le_i32_e64 s[0:1], 8, v250
	v_cmp_le_i32_e64 s[4:5], 9, v250
	v_exp_f32_e32 v36, v36
	v_exp_f32_e32 v37, v37
	v_cndmask_b32_e64 v34, v34, 0, s[6:7]
	v_cndmask_b32_e64 v35, v35, 0, s[48:49]
	v_add_f32_e32 v232, v232, v34
	v_add_f32_e32 v233, v233, v35
	v_cvt_pk_bf16_f32 v65, v34, v35
	v_cmp_le_i32_e64 s[6:7], 10, v250
	v_cmp_le_i32_e64 s[48:49], 11, v250
	v_exp_f32_e32 v38, v38
	v_exp_f32_e32 v39, v39
	v_cndmask_b32_e64 v36, v36, 0, s[0:1]
	v_cndmask_b32_e64 v37, v37, 0, s[4:5]
	v_add_f32_e32 v232, v232, v36
	v_add_f32_e32 v233, v233, v37
	v_cvt_pk_bf16_f32 v66, v36, v37
	v_cndmask_b32_e64 v38, v38, 0, s[6:7]
	v_cndmask_b32_e64 v39, v39, 0, s[48:49]
	v_add_f32_e32 v232, v232, v38
	v_add_f32_e32 v233, v233, v39
	v_cvt_pk_bf16_f32 v67, v38, v39
	s_waitcnt lgkmcnt(3)
	v_mfma_f32_32x32x16_bf16 v[48:63], v[208:211], v[88:91], v[48:63]
	ds_read_b128 v[208:211], v72 offset:13888
	v_cmp_le_i32_e64 s[0:1], 16, v250
	v_cmp_le_i32_e64 s[4:5], 17, v250
	v_exp_f32_e32 v40, v40
	v_exp_f32_e32 v41, v41
	s_waitcnt lgkmcnt(3)
	v_mfma_f32_32x32x16_bf16 v[48:63], v[212:215], v[92:95], v[48:63]
	ds_read_b128 v[212:215], v72 offset:13920
	v_cmp_le_i32_e64 s[6:7], 18, v250
	v_cmp_le_i32_e64 s[48:49], 19, v250
	v_exp_f32_e32 v42, v42
	v_exp_f32_e32 v43, v43
	v_cndmask_b32_e64 v40, v40, 0, s[0:1]
	v_cndmask_b32_e64 v41, v41, 0, s[4:5]
	v_add_f32_e32 v232, v232, v40
	v_add_f32_e32 v233, v233, v41
	v_cvt_pk_bf16_f32 v68, v40, v41
	v_mfma_f32_32x32x16_bf16 v[0:15], v[216:219], v[64:67], v[0:15]
	ds_read2_b64 v[216:219], v73 offset0:16 offset1:18
	v_cmp_le_i32_e64 s[0:1], 24, v250
	v_cmp_le_i32_e64 s[4:5], 25, v250
	v_exp_f32_e32 v44, v44
	v_exp_f32_e32 v45, v45
	v_cndmask_b32_e64 v42, v42, 0, s[6:7]
	v_cndmask_b32_e64 v43, v43, 0, s[48:49]
	v_add_f32_e32 v232, v232, v42
	v_add_f32_e32 v233, v233, v43
	v_cvt_pk_bf16_f32 v69, v42, v43
	v_mfma_f32_32x32x16_bf16 v[16:31], v[220:223], v[64:67], v[16:31]
	ds_read2_b64 v[220:223], v74 offset0:48 offset1:50
	v_cmp_le_i32_e64 s[6:7], 26, v250
	v_cmp_le_i32_e64 s[48:49], 27, v250
	v_exp_f32_e32 v46, v46
	v_exp_f32_e32 v47, v47
	v_cndmask_b32_e64 v44, v44, 0, s[0:1]
	v_cndmask_b32_e64 v45, v45, 0, s[4:5]
	v_add_f32_e32 v232, v232, v44
	v_add_f32_e32 v233, v233, v45
	v_cvt_pk_bf16_f32 v70, v44, v45
	v_cndmask_b32_e64 v46, v46, 0, s[6:7]
	v_cndmask_b32_e64 v47, v47, 0, s[48:49]
	v_add_f32_e32 v232, v232, v46
	v_add_f32_e32 v233, v233, v47
	v_cvt_pk_bf16_f32 v71, v46, v47
	s_waitcnt lgkmcnt(5)
	v_mfma_f32_32x32x16_bf16 v[32:47], v[200:203], v[80:83], 0
	v_exp_f32_e32 v48, v48
	v_exp_f32_e32 v49, v49
	s_waitcnt lgkmcnt(4)
	v_mfma_f32_32x32x16_bf16 v[32:47], v[204:207], v[84:87], v[32:47]
	v_exp_f32_e32 v50, v50
	v_exp_f32_e32 v51, v51
	v_add_f32_e32 v232, v232, v48
	v_add_f32_e32 v233, v233, v49
	v_cvt_pk_bf16_f32 v64, v48, v49
	v_mfma_f32_32x32x16_bf16 v[0:15], v[224:227], v[68:71], v[0:15]
	ds_read2_b64 v[224:227], v73 offset0:20 offset1:22
	v_exp_f32_e32 v52, v52
	v_exp_f32_e32 v53, v53
	v_add_f32_e32 v232, v232, v50
	v_add_f32_e32 v233, v233, v51
	v_cvt_pk_bf16_f32 v65, v50, v51
	v_mfma_f32_32x32x16_bf16 v[16:31], v[228:231], v[68:71], v[16:31]
	ds_read2_b64 v[228:231], v74 offset0:52 offset1:54
	v_exp_f32_e32 v54, v54
	v_exp_f32_e32 v55, v55
	v_add_f32_e32 v232, v232, v52
	v_add_f32_e32 v233, v233, v53
	v_cvt_pk_bf16_f32 v66, v52, v53
	v_add_f32_e32 v232, v232, v54
	v_add_f32_e32 v233, v233, v55
	v_cvt_pk_bf16_f32 v67, v54, v55
	s_cmp_eq_u32 s45, 0
	s_cbranch_scc1 .Lt2_e1_nostage
	s_waitcnt vmcnt(3)
	ds_write_b128 v251, v[96:99]
	s_waitcnt vmcnt(2)
	ds_write_b128 v251, v[100:103] offset:9216
	s_waitcnt vmcnt(1)
	ds_write2_b64 v252, v[104:105], v[106:107] offset1:1
	s_waitcnt vmcnt(0)
	ds_write2_b64 v252, v[108:109], v[110:111] offset0:16 offset1:17
	s_mov_b32 s47, 1
	s_add_i32 s6, s44, 2
	s_add_i32 s7, s91, s44
	s_add_i32 s7, s7, 1
	s_add_i32 s0, s44, 1
	s_cmp_lt_i32 s0, s90
	s_cbranch_scc0 .Lt2_e1_nostage
	s_cmp_lt_u32 s0, s89
	s_cselect_b32 s0, s71, s75
	s_cselect_b32 s1, s72, s76
	s_cselect_b32 s4, s73, s77
	s_cselect_b32 s5, s74, s78
	s_cselect_b32 s6, s6, s7
	s_ashr_i32 s7, s6, 31
	s_lshl_b64 s[6:7], s[6:7], 14
	s_add_u32 s6, s6, s60
	s_addc_u32 s7, s7, s61
	s_add_u32 s0, s0, s6
	s_addc_u32 s1, s1, s7
	s_add_u32 s4, s4, s6
	s_addc_u32 s5, s5, s7
	global_load_dwordx4 v[96:99], v248, s[0:1]
	global_load_dwordx4 v[100:103], v249, s[0:1]
	global_load_dwordx4 v[104:107], v248, s[4:5]
	global_load_dwordx4 v[108:111], v249, s[4:5]

; #define LAS __attribute__((address_space(3)))
; #define MFMA32(a, b, c) __builtin_amdgcn_mfma_f32_32x32x16_bf16((a), (b), (c), 0, 0, 0)
; __device__ __forceinline__ float ex2(float x) { return __builtin_amdgcn_exp2f(x); }
; template <int MODE>
; __device__ __forceinline__ void attn_tile(const LAS unsigned char* Kb, const LAS unsigned char* Vb, const bf16x8_t (&qf)[4], f32x16 (&oacc)[2], float& l_run,
;                                           int r, int h, int dlt0, int dlt1, bool hiw) {
;     ...
; #pragma unroll
;     for (int mt = 0; mt < 4; ++mt) {
;         if (mt == 0) { if (hiw) __builtin_amdgcn_s_setprio(1); else __builtin_amdgcn_s_setprio(0); }
;         if (mt == 2) { if (hiw) __builtin_amdgcn_s_setprio(0); else __builtin_amdgcn_s_setprio(1); }
;         const int dl = mt < 2 ? dlt0 : dlt1;
;         f32x16 sacc = zero16();
; #pragma unroll
;         for (int ks = 0; ks < 4; ++ks) { const bf16x8_t ka = *(const LAS bf16x8_t*)(Kb + (32 * mt + r) * A_KSTR + 32 * ks + 16 * h); sacc = MFMA32(ka, qf[ks], sacc); }
; #pragma unroll
;         for (int i = 0; i < 16; ++i) {
;             float p;
;             if (MODE == 2) p = ex2(sacc[i]);
;             else if (MODE == 3) p = ex2(sacc[i] + __int_as_float(dl));
;             else { const int ci = 32 * mt + (i & 3) + 8 * (i >> 2); p = ((unsigned)(dl - ci) < ulim) ? ex2(sacc[i]) : 0.f; }
;             sacc[i] = p; ls += p;
;         }
; #pragma unroll
;         for (int s = 0; s < 2; ++s) {
;             const bf16x8_t pf = pack8(sacc, 8 * s);
; #pragma unroll
;             for (int dt = 0; dt < 2; ++dt) {
;                 const LAS unsigned char* vp = Vb + (32 * dt + r) * A_CVSTR + (32 * mt + 16 * s + 4 * h) * 2;
;                 const s16x4_t lo = *(const LAS s16x4_t*)vp, hi = *(const LAS s16x4_t*)(vp + 16);
;                 oacc[dt] = MFMA32(__builtin_shufflevector(lo, hi, 0, 1, 2, 3, 4, 5, 6, 7), pf, oacc[dt]);
;             }
;         }
;     }
.Lt2_e2:
	ds_read_b128 v[200:203], v72 offset:9216
	ds_read_b128 v[204:207], v72 offset:9248
	ds_read_b128 v[208:211], v72 offset:9280
	ds_read_b128 v[212:215], v72 offset:9312
	ds_read2_b64 v[216:219], v73 offset0:16 offset1:18
	ds_read2_b64 v[220:223], v74 offset0:48 offset1:50
	ds_read2_b64 v[224:227], v73 offset0:20 offset1:22
	ds_read2_b64 v[228:231], v74 offset0:52 offset1:54
	s_waitcnt lgkmcnt(7)
	v_mfma_f32_32x32x16_bf16 v[32:47], v[200:203], v[80:83], 0
	ds_read_b128 v[200:203], v72 offset:13824
	s_waitcnt lgkmcnt(7)
	v_mfma_f32_32x32x16_bf16 v[32:47], v[204:207], v[84:87], v[32:47]
	ds_read_b128 v[204:207], v72 offset:13856
	s_waitcnt lgkmcnt(7)
	v_mfma_f32_32x32x16_bf16 v[32:47], v[208:211], v[88:91], v[32:47]
	ds_read_b128 v[208:211], v72 offset:13888
	s_waitcnt lgkmcnt(7)
	v_mfma_f32_32x32x16_bf16 v[32:47], v[212:215], v[92:95], v[32:47]
	ds_read_b128 v[212:215], v72 offset:13920
	s_nop 7
	s_nop 3
	s_waitcnt lgkmcnt(3)
	v_mfma_f32_32x32x16_bf16 v[48:63], v[200:203], v[80:83], 0
	v_cmp_le_i32_e64 s[0:1], 0, v250
	v_cmp_le_i32_e64 s[4:5], 1, v250
	v_exp_f32_e32 v32, v32
	v_exp_f32_e32 v33, v33
	s_waitcnt lgkmcnt(2)
	v_mfma_f32_32x32x16_bf16 v[48:63], v[204:207], v[84:87], v[48:63]
	v_cmp_le_i32_e64 s[6:7], 2, v250
	v_cmp_le_i32_e64 s[48:49], 3, v250
	v_exp_f32_e32 v34, v34
	v_exp_f32_e32 v35, v35
	v_cndmask_b32_e64 v32, v32, 0, s[0:1]
	v_cndmask_b32_e64 v33, v33, 0, s[4:5]
	v_mov_b32_e32 v232, v32
	v_mov_b32_e32 v233, v33
	v_cvt_pk_bf16_f32 v64, v32, v33
	v_cmp_le_i32_e64 s[0:1], 8, v250
	v_cmp_le_i32_e64 s[4:5], 9, v250
	v_exp_f32_e32 v36, v36
	v_exp_f32_e32 v37, v37
	v_cndmask_b32_e64 v34, v34, 0, s[6:7]
	v_cndmask_b32_e64 v35, v35, 0, s[48:49]
	v_add_f32_e32 v232, v232, v34
	v_add_f32_e32 v233, v233, v35
	v_cvt_pk_bf16_f32 v65, v34, v35
	v_cmp_le_i32_e64 s[6:7], 10, v250
	v_cmp_le_i32_e64 s[48:49], 11, v250
	v_exp_f32_e32 v38, v38
	v_exp_f32_e32 v39, v39
	v_cndmask_b32_e64 v36, v36, 0, s[0:1]
	v_cndmask_b32_e64 v37, v37, 0, s[4:5]
	v_add_f32_e32 v232, v232, v36
	v_add_f32_e32 v233, v233, v37
	v_cvt_pk_bf16_f32 v66, v36, v37
	v_cndmask_b32_e64 v38, v38, 0, s[6:7]
	v_cndmask_b32_e64 v39, v39, 0, s[48:49]
	v_add_f32_e32 v232, v232, v38
	v_add_f32_e32 v233, v233, v39
	v_cvt_pk_bf16_f32 v67, v38, v39
	s_cmp_eq_u32 s45, 0
	s_cbranch_scc1 .Lt2_e2_nostage
	s_waitcnt vmcnt(3)
	ds_write_b128 v251, v[96:99]
	s_waitcnt vmcnt(2)
	ds_write_b128 v251, v[100:103] offset:9216
	s_waitcnt vmcnt(1)
	ds_write2_b64 v252, v[104:105], v[106:107] offset1:1
	s_waitcnt vmcnt(0)
	ds_write2_b64 v252, v[108:109], v[110:111] offset0:16 offset1:17
	s_mov_b32 s47, 1
	s_add_i32 s6, s44, 2
	s_add_i32 s7, s91, s44
	s_add_i32 s7, s7, 1
	s_add_i32 s0, s44, 1
	s_cmp_lt_i32 s0, s90
	s_cbranch_scc0 .Lt2_e2_nostage
	s_cmp_lt_u32 s0, s89
	s_cselect_b32 s0, s71, s75
	s_cselect_b32 s1, s72, s76
	s_cselect_b32 s4, s73, s77
	s_cselect_b32 s5, s74, s78
	s_cselect_b32 s6, s6, s7
	s_ashr_i32 s7, s6, 31
	s_lshl_b64 s[6:7], s[6:7], 14
	s_add_u32 s6, s6, s60
	s_addc_u32 s7, s7, s61
	s_add_u32 s0, s0, s6
	s_addc_u32 s1, s1, s7
	s_add_u32 s4, s4, s6
	s_addc_u32 s5, s5, s7
	global_load_dwordx4 v[96:99], v248, s[0:1]
	global_load_dwordx4 v[100:103], v249, s[0:1]
	global_load_dwordx4 v[104:107], v248, s[4:5]
	global_load_dwordx4 v[108:111], v249, s[4:5]

.Lt2_stage:
	s_cmp_eq_u32 s45, 0
	s_cbranch_scc1 .Lt2_latch
	s_cmp_eq_u32 s47, 1
	s_cbranch_scc1 .Lt2_latch
	s_waitcnt vmcnt(3)
	ds_write_b128 v251, v[96:99]
	s_waitcnt vmcnt(2)
	ds_write_b128 v251, v[100:103] offset:9216
	s_waitcnt vmcnt(1)
	ds_write2_b64 v252, v[104:105], v[106:107] offset1:1
	s_waitcnt vmcnt(0)
	ds_write2_b64 v252, v[108:109], v[110:111] offset0:16 offset1:17
	s_add_i32 s6, s44, 2
	s_add_i32 s7, s91, s44
	s_add_i32 s7, s7, 1
	s_add_i32 s0, s44, 1
	s_cmp_lt_i32 s0, s90
	s_cbranch_scc0 .Lt2_latch
	s_cmp_lt_u32 s0, s89
	s_cselect_b32 s0, s71, s75
	s_cselect_b32 s1, s72, s76
	s_cselect_b32 s4, s73, s77
	s_cselect_b32 s5, s74, s78
	s_cselect_b32 s6, s6, s7
	s_ashr_i32 s7, s6, 31
	s_lshl_b64 s[6:7], s[6:7], 14
	s_add_u32 s6, s6, s60
	s_addc_u32 s7, s7, s61
	s_add_u32 s0, s0, s6
	s_addc_u32 s1, s1, s7
	s_add_u32 s4, s4, s6
	s_addc_u32 s5, s5, s7
	global_load_dwordx4 v[96:99], v248, s[0:1]
	global_load_dwordx4 v[100:103], v249, s[0:1]
	global_load_dwordx4 v[104:107], v248, s[4:5]
	global_load_dwordx4 v[108:111], v249, s[4:5]
